# residual GEMM epilogues (4 instances): 16 HB tile loads hoisted to epilogue start with one wait, per-row waits removed; loop-head vmcnt(0) removed
# speedup vs baseline: 1.0080x; 1.0080x over previous
; #define PG8_STAGE(bufoff, gbase, voff) do { _Pragma("unroll") for (int _i = 0; _i < 2; ++_i) \
;         __builtin_amdgcn_global_load_lds((const unsigned*)((const char*)(gbase) + (voff)[_i]), (PG8_LAS unsigned*)(lds + (bufoff) + ldsw + _i * 8192), 16, 0, 0); } while (0)
; #define PG8_LDA(dst, b, h) do { _Pragma("unroll") for (int m = 0; m < 4; ++m) _Pragma("unroll") for (int k = 0; k < 2; ++k) dst[m][k] = *(const PG8_LAS bf16x8*)(lds + PG8_SA(b, h) + aoff + m * 2048 + k * 1024); } while (0)
; #define PG8_LDB(dst, b, h) do { _Pragma("unroll") for (int n = 0; n < 2; ++n) _Pragma("unroll") for (int k = 0; k < 2; ++k) dst[n][k] = *(const PG8_LAS bf16x8*)(lds + PG8_SB(b, h) + boff + n * 2048 + k * 1024); } while (0)
; #define PG8_SCHED __builtin_amdgcn_sched_barrier(0)
;     __device__ bool next(int i, Unit& u) const { if (!StaticOrder::next(i, u)) return false; u.aoff = (u.pn >> 1) * 512; return true; }
; template <class Epi, class Sched, bool ALIGN_EPI = false, bool SP2 = false>
; __device__ __forceinline__ void gemm_phase(PG8_LAS unsigned char* lds, const Gemm g, const Sched& S, const Epi& E) {
;     ...
;         const bool has_next = S.next(ui + 1, nxt);
;         const char* nA = has_next ? (const char*)g.A + (size_t)nxt.pm * tstepA + nxt.aoff : cA; const char* nB = has_next ? (const char*)g.Bt + (size_t)nxt.pn * tstepB : cB;
;         for (int t = 0; t < nt; t += 2) {
;             const bool last = (t == nt - 2);
;             const char* a1 = cA + (size_t)(t + 1) * kstep;
;             const char* a2 = last ? nA : cA + (size_t)(t + 2) * kstep; const char* b2 = last ? nB : cB + (size_t)(t + 2) * kstep;
;             const char* a3 = a2 + kstep; const char* b3 = b2 + kstep;
;             if (last && has_next) S.a_ready(nxt);
;             if constexpr (SP2) {
;             PG8_LDB(B0, 0, 0); PG8_LDB(B1, 0, 1); PG8_SCHED; PG8_LDA(At, 0, 0); PG8_STAGE(PG8_SA(1, 1), a1 + hstepA, voffA);
;     ...
; #pragma unroll
;         for (int a = 0; a < 2; ++a)
; #pragma unroll
;             for (int b = 0; b < 2; ++b)
; #pragma unroll
;                 for (int m = 0; m < 4; ++m)
; #pragma unroll
;                     for (int n = 0; n < 2; ++n) acc[a][b][m][n] = (f32x4){0.f, 0.f, 0.f, 0.f};
;         cur = nxt; cA = nA; cB = nB; ++ui;
.LBB0_659:
	s_ashr_i32 s21, s20, 31
	s_lshl_b64 s[22:23], s[20:21], 20
	s_add_u32 s22, s0, s22
	s_addc_u32 s23, s1, s23
	s_and_b64 s[26:27], s[8:9], exec
	s_cselect_b32 s21, s23, s31
	s_cselect_b32 s29, s22, s30
	s_ashr_i32 s19, s18, 31
	s_lshl_b64 s[26:27], s[18:19], 20
	s_add_u32 s26, s3, s26
	s_addc_u32 s27, s24, s27
	s_and_b64 s[36:37], s[8:9], exec
	s_cselect_b32 s19, s27, s35
	s_cselect_b32 s53, s26, s34
	s_add_u32 s30, s30, 0x80080
	s_addc_u32 s31, s31, 0
	s_add_u32 s54, s34, 0x100
	v_mov_b32_e32 v0, 0
	s_addc_u32 s55, s35, 0
	s_mov_b32 s56, -2
	s_waitcnt lgkmcnt(0)
	v_mov_b32_e32 v1, v0
	v_mov_b32_e32 v2, v0
	v_mov_b32_e32 v3, v0
	v_mov_b32_e32 v4, v0
	v_mov_b32_e32 v5, v0
	v_mov_b32_e32 v6, v0
	v_mov_b32_e32 v7, v0
	v_mov_b32_e32 v16, v0
	v_mov_b32_e32 v17, v0
	v_mov_b32_e32 v18, v0
	v_mov_b32_e32 v19, v0
	v_mov_b32_e32 v20, v0
	v_mov_b32_e32 v21, v0
	v_mov_b32_e32 v22, v0
	v_mov_b32_e32 v23, v0
	v_mov_b32_e32 v32, v0
	v_mov_b32_e32 v33, v0
	v_mov_b32_e32 v34, v0
	v_mov_b32_e32 v35, v0
	v_mov_b32_e32 v36, v0
	v_mov_b32_e32 v37, v0
	v_mov_b32_e32 v38, v0
	v_mov_b32_e32 v39, v0
	v_mov_b32_e32 v48, v0
	v_mov_b32_e32 v49, v0
	v_mov_b32_e32 v50, v0
	v_mov_b32_e32 v51, v0
	v_mov_b32_e32 v52, v0
	v_mov_b32_e32 v53, v0
	v_mov_b32_e32 v54, v0
	v_mov_b32_e32 v55, v0
	v_mov_b32_e32 v8, v0
	v_mov_b32_e32 v9, v0
	v_mov_b32_e32 v10, v0
	v_mov_b32_e32 v11, v0
	v_mov_b32_e32 v12, v0
	v_mov_b32_e32 v13, v0
	v_mov_b32_e32 v14, v0
	v_mov_b32_e32 v15, v0
	v_mov_b32_e32 v24, v0
	v_mov_b32_e32 v25, v0
	v_mov_b32_e32 v26, v0
	v_mov_b32_e32 v27, v0
	v_mov_b32_e32 v28, v0
	v_mov_b32_e32 v29, v0
	v_mov_b32_e32 v30, v0
	v_mov_b32_e32 v31, v0
	v_mov_b32_e32 v40, v0
	v_mov_b32_e32 v41, v0
	v_mov_b32_e32 v42, v0
	v_mov_b32_e32 v43, v0
	v_mov_b32_e32 v44, v0
	v_mov_b32_e32 v45, v0
	v_mov_b32_e32 v46, v0
	v_mov_b32_e32 v47, v0
	v_mov_b32_e32 v56, v0
	v_mov_b32_e32 v57, v0
	v_mov_b32_e32 v58, v0
	v_mov_b32_e32 v59, v0
	v_mov_b32_e32 v60, v0
	v_mov_b32_e32 v61, v0
	v_mov_b32_e32 v62, v0
	v_mov_b32_e32 v63, v0
	v_mov_b32_e32 v64, v0
	v_mov_b32_e32 v65, v0
	v_mov_b32_e32 v66, v0
	v_mov_b32_e32 v67, v0
	v_mov_b32_e32 v68, v0
	v_mov_b32_e32 v69, v0
	v_mov_b32_e32 v70, v0
	v_mov_b32_e32 v71, v0
	v_mov_b32_e32 v80, v0
	v_mov_b32_e32 v81, v0
	v_mov_b32_e32 v82, v0
	v_mov_b32_e32 v83, v0
	v_mov_b32_e32 v84, v0
	v_mov_b32_e32 v85, v0
	v_mov_b32_e32 v86, v0
	v_mov_b32_e32 v87, v0
	v_mov_b32_e32 v96, v0
	v_mov_b32_e32 v97, v0
	v_mov_b32_e32 v98, v0
	v_mov_b32_e32 v99, v0
	v_mov_b32_e32 v100, v0
	v_mov_b32_e32 v101, v0
	v_mov_b32_e32 v102, v0
	v_mov_b32_e32 v103, v0
	v_mov_b32_e32 v112, v0
	v_mov_b32_e32 v113, v0
	v_mov_b32_e32 v114, v0
	v_mov_b32_e32 v115, v0
	v_mov_b32_e32 v116, v0
	v_mov_b32_e32 v117, v0
	v_mov_b32_e32 v118, v0
	v_mov_b32_e32 v119, v0
	v_mov_b32_e32 v72, v0
	v_mov_b32_e32 v73, v0
	v_mov_b32_e32 v74, v0
	v_mov_b32_e32 v75, v0
	v_mov_b32_e32 v76, v0
	v_mov_b32_e32 v77, v0
	v_mov_b32_e32 v78, v0
	v_mov_b32_e32 v79, v0
	v_mov_b32_e32 v88, v0
	v_mov_b32_e32 v89, v0
	v_mov_b32_e32 v90, v0
	v_mov_b32_e32 v91, v0
	v_mov_b32_e32 v92, v0
	v_mov_b32_e32 v93, v0
	v_mov_b32_e32 v94, v0
	v_mov_b32_e32 v95, v0
	v_mov_b32_e32 v104, v0
	v_mov_b32_e32 v105, v0
	v_mov_b32_e32 v106, v0
	v_mov_b32_e32 v107, v0
	v_mov_b32_e32 v108, v0
	v_mov_b32_e32 v109, v0
	v_mov_b32_e32 v110, v0
	v_mov_b32_e32 v111, v0
	v_mov_b32_e32 v120, v0
	v_mov_b32_e32 v121, v0
	v_mov_b32_e32 v122, v0
	v_mov_b32_e32 v123, v0
	v_mov_b32_e32 v124, v0
	v_mov_b32_e32 v125, v0
	v_mov_b32_e32 v126, v0
	v_mov_b32_e32 v127, v0
.LBB0_660:
	ds_read_b128 v[144:147], v149
	ds_read_b128 v[152:155], v149 offset:1024
	ds_read_b128 v[156:159], v149 offset:2048
	ds_read_b128 v[160:163], v149 offset:3072
	ds_read_b128 v[168:171], v150
	ds_read_b128 v[172:175], v150 offset:1024
	ds_read_b128 v[176:179], v150 offset:2048
	ds_read_b128 v[180:183], v150 offset:3072
	s_add_u32 s4, s30, 0xfff80080
	s_addc_u32 s5, s31, -1
	s_cmp_eq_u32 s56, 28
	s_cselect_b32 s37, s21, s5
	s_cselect_b32 s36, s29, s4
	s_cselect_b32 s35, s19, s55
	s_cselect_b32 s34, s53, s54
	v_lshl_add_u64 v[164:165], s[30:31], 0, v[136:137]
	s_add_i32 m0, s25, 0xc000
	ds_read_b128 v[184:187], v151
	ds_read_b128 v[188:191], v151 offset:1024
	ds_read_b128 v[192:195], v151 offset:2048
	ds_read_b128 v[196:199], v151 offset:3072
	ds_read_b128 v[200:203], v151 offset:4096
	ds_read_b128 v[204:207], v151 offset:5120
	ds_read_b128 v[208:211], v151 offset:6144
	ds_read_b128 v[212:215], v151 offset:7168
	global_load_lds_dwordx4 v[164:165], off
	v_lshl_add_u64 v[164:165], s[30:31], 0, v[138:139]
	s_add_i32 m0, s25, 0xe000
	s_nop 0
	global_load_lds_dwordx4 v[164:165], off
	s_waitcnt vmcnt(8)
	s_waitcnt lgkmcnt(0)
	s_barrier
; #define PG8_STAGE(bufoff, gbase, voff) do { _Pragma("unroll") for (int _i = 0; _i < 2; ++_i) \
;         __builtin_amdgcn_global_load_lds((const unsigned*)((const char*)(gbase) + (voff)[_i]), (PG8_LAS unsigned*)(lds + (bufoff) + ldsw + _i * 8192), 16, 0, 0); } while (0)
; #define PG8_LDA(dst, b, h) do { _Pragma("unroll") for (int m = 0; m < 4; ++m) _Pragma("unroll") for (int k = 0; k < 2; ++k) dst[m][k] = *(const PG8_LAS bf16x8*)(lds + PG8_SA(b, h) + aoff + m * 2048 + k * 1024); } while (0)
; #define PG8_LDB(dst, b, h) do { _Pragma("unroll") for (int n = 0; n < 2; ++n) _Pragma("unroll") for (int k = 0; k < 2; ++k) dst[n][k] = *(const PG8_LAS bf16x8*)(lds + PG8_SB(b, h) + boff + n * 2048 + k * 1024); } while (0)
; #define PG8_MMA(ai, bj, At, Bt) do { __builtin_amdgcn_s_setprio(1); _Pragma("unroll") for (int m = 0; m < 4; ++m) _Pragma("unroll") for (int n = 0; n < 2; ++n) _Pragma("unroll") for (int k = 0; k < 2; ++k) \
;         acc[ai][bj][m][n] = __builtin_amdgcn_mfma_f32_16x16x32_bf16(Bt[n][k], At[m][k], acc[ai][bj][m][n], 0, 0, 0); __builtin_amdgcn_s_setprio(0); } while (0)
; #define PG8_WAIT_V(n) asm volatile("s_waitcnt vmcnt(" #n ")" ::: "memory")
; #define PG8_WAIT_L(n) asm volatile("s_waitcnt lgkmcnt(" #n ")" ::: "memory")
; #define PG8_BAR __builtin_amdgcn_s_barrier()
; #define PG8_SCHED __builtin_amdgcn_sched_barrier(0)
; template <class Epi, class Sched, bool ALIGN_EPI = false, bool SP2 = false>
; __device__ __forceinline__ void gemm_phase(PG8_LAS unsigned char* lds, const Gemm g, const Sched& S, const Epi& E) {
;     ...
;             PG8_LDB(B0, 0, 0); PG8_LDB(B1, 0, 1); PG8_SCHED; PG8_LDA(At, 0, 0); PG8_STAGE(PG8_SA(1, 1), a1 + hstepA, voffA);
;             PG8_WAIT_V(8); PG8_WAIT_L(0); PG8_BAR; PG8_MMA(0, 0, At, B0); PG8_MMA(0, 1, At, B1); PG8_BAR; PG8_SCHED;
;             PG8_LDA(At, 0, 1); PG8_STAGE(PG8_SB(0, 0), b2, voffB); PG8_STAGE(PG8_SB(0, 1), b2 + hstepB, voffB); PG8_STAGE(PG8_SA(0, 0), a2, voffA);
;             PG8_WAIT_V(8); PG8_WAIT_L(0); PG8_BAR; PG8_MMA(1, 0, At, B0); PG8_MMA(1, 1, At, B1); PG8_BAR; PG8_SCHED;
	s_setprio 1
	s_waitcnt lgkmcnt(0)
	v_mfma_f32_16x16x32_bf16 v[124:127], v[144:147], v[184:187], v[124:127]
	v_mfma_f32_16x16x32_bf16 v[120:123], v[156:159], v[184:187], v[120:123]
	v_mfma_f32_16x16x32_bf16 v[108:111], v[144:147], v[192:195], v[108:111]
	v_mfma_f32_16x16x32_bf16 v[104:107], v[156:159], v[192:195], v[104:107]
	v_mfma_f32_16x16x32_bf16 v[92:95], v[144:147], v[200:203], v[92:95]
	v_mfma_f32_16x16x32_bf16 v[88:91], v[156:159], v[200:203], v[88:91]
	v_mfma_f32_16x16x32_bf16 v[76:79], v[144:147], v[208:211], v[76:79]
	v_mfma_f32_16x16x32_bf16 v[72:75], v[156:159], v[208:211], v[72:75]
	v_mfma_f32_16x16x32_bf16 v[124:127], v[152:155], v[188:191], v[124:127]
	v_mfma_f32_16x16x32_bf16 v[120:123], v[160:163], v[188:191], v[120:123]
	v_mfma_f32_16x16x32_bf16 v[108:111], v[152:155], v[196:199], v[108:111]
	v_mfma_f32_16x16x32_bf16 v[104:107], v[160:163], v[196:199], v[104:107]
	v_mfma_f32_16x16x32_bf16 v[92:95], v[152:155], v[204:207], v[92:95]
	v_mfma_f32_16x16x32_bf16 v[88:91], v[160:163], v[204:207], v[88:91]
	v_mfma_f32_16x16x32_bf16 v[76:79], v[152:155], v[212:215], v[76:79]
	v_mfma_f32_16x16x32_bf16 v[72:75], v[160:163], v[212:215], v[72:75]
	s_setprio 0
	s_setprio 1
	v_mfma_f32_16x16x32_bf16 v[116:119], v[168:171], v[184:187], v[116:119]
	v_mfma_f32_16x16x32_bf16 v[112:115], v[176:179], v[184:187], v[112:115]
	v_mfma_f32_16x16x32_bf16 v[100:103], v[168:171], v[192:195], v[100:103]
	v_mfma_f32_16x16x32_bf16 v[96:99], v[176:179], v[192:195], v[96:99]
	v_mfma_f32_16x16x32_bf16 v[84:87], v[168:171], v[200:203], v[84:87]
	v_mfma_f32_16x16x32_bf16 v[80:83], v[176:179], v[200:203], v[80:83]
	v_mfma_f32_16x16x32_bf16 v[68:71], v[168:171], v[208:211], v[68:71]
	v_mfma_f32_16x16x32_bf16 v[64:67], v[176:179], v[208:211], v[64:67]
	v_mfma_f32_16x16x32_bf16 v[116:119], v[172:175], v[188:191], v[116:119]
	v_mfma_f32_16x16x32_bf16 v[112:115], v[180:183], v[188:191], v[112:115]
	v_mfma_f32_16x16x32_bf16 v[100:103], v[172:175], v[196:199], v[100:103]
	v_mfma_f32_16x16x32_bf16 v[96:99], v[180:183], v[196:199], v[96:99]
	v_mfma_f32_16x16x32_bf16 v[84:87], v[172:175], v[204:207], v[84:87]
	v_mfma_f32_16x16x32_bf16 v[80:83], v[180:183], v[204:207], v[80:83]
	v_mfma_f32_16x16x32_bf16 v[68:71], v[172:175], v[212:215], v[68:71]
	v_mfma_f32_16x16x32_bf16 v[64:67], v[180:183], v[212:215], v[64:67]
	s_setprio 0
	s_barrier
	s_add_i32 s4, s44, s47
	v_lshl_add_u64 v[164:165], s[34:35], 0, v[130:131]
	s_mov_b32 m0, s4
	ds_read_b128 v[184:187], v151 offset:16384
	ds_read_b128 v[188:191], v151 offset:17408
	ds_read_b128 v[192:195], v151 offset:18432
	ds_read_b128 v[196:199], v151 offset:19456
	ds_read_b128 v[200:203], v151 offset:20480
	ds_read_b128 v[204:207], v151 offset:21504
	ds_read_b128 v[208:211], v151 offset:22528
	ds_read_b128 v[212:215], v151 offset:23552
	global_load_lds_dwordx4 v[164:165], off
	s_add_i32 m0, s4, 0x2000
	s_add_u32 s58, s34, 0x80000
	v_lshl_add_u64 v[216:217], s[34:35], 0, v[134:135]
	s_addc_u32 s59, s35, 0
	s_add_i32 s4, s45, s47
	global_load_lds_dwordx4 v[216:217], off
	v_lshl_add_u64 v[218:219], s[58:59], 0, v[130:131]
	s_mov_b32 m0, s4
	v_lshl_add_u64 v[220:221], s[36:37], 0, v[132:133]
	global_load_lds_dwordx4 v[218:219], off
	v_lshl_add_u64 v[218:219], s[58:59], 0, v[134:135]
	s_add_i32 m0, s4, 0x2000
	s_nop 0
	global_load_lds_dwordx4 v[218:219], off
	v_lshl_add_u64 v[218:219], s[36:37], 0, v[128:129]
	s_mov_b32 m0, s25
	s_nop 0
	global_load_lds_dwordx4 v[218:219], off
	s_mov_b32 m0, s33
	s_nop 0
	global_load_lds_dwordx4 v[220:221], off
	s_waitcnt vmcnt(8)
	s_waitcnt lgkmcnt(0)
	s_barrier
	s_setprio 1
	s_waitcnt lgkmcnt(0)
	v_mfma_f32_16x16x32_bf16 v[60:63], v[144:147], v[184:187], v[60:63]
	v_mfma_f32_16x16x32_bf16 v[56:59], v[156:159], v[184:187], v[56:59]
	v_mfma_f32_16x16x32_bf16 v[44:47], v[144:147], v[192:195], v[44:47]
	v_mfma_f32_16x16x32_bf16 v[40:43], v[156:159], v[192:195], v[40:43]
	v_mfma_f32_16x16x32_bf16 v[28:31], v[144:147], v[200:203], v[28:31]
	v_mfma_f32_16x16x32_bf16 v[24:27], v[156:159], v[200:203], v[24:27]
	v_mfma_f32_16x16x32_bf16 v[12:15], v[144:147], v[208:211], v[12:15]
	v_mfma_f32_16x16x32_bf16 v[8:11], v[156:159], v[208:211], v[8:11]
	v_mfma_f32_16x16x32_bf16 v[60:63], v[152:155], v[188:191], v[60:63]
	v_mfma_f32_16x16x32_bf16 v[56:59], v[160:163], v[188:191], v[56:59]
	v_mfma_f32_16x16x32_bf16 v[44:47], v[152:155], v[196:199], v[44:47]
	v_mfma_f32_16x16x32_bf16 v[40:43], v[160:163], v[196:199], v[40:43]
	v_mfma_f32_16x16x32_bf16 v[28:31], v[152:155], v[204:207], v[28:31]
	v_mfma_f32_16x16x32_bf16 v[24:27], v[160:163], v[204:207], v[24:27]
	v_mfma_f32_16x16x32_bf16 v[12:15], v[152:155], v[212:215], v[12:15]
	v_mfma_f32_16x16x32_bf16 v[8:11], v[160:163], v[212:215], v[8:11]
	s_setprio 0
	s_setprio 1
	v_mfma_f32_16x16x32_bf16 v[52:55], v[168:171], v[184:187], v[52:55]
	v_mfma_f32_16x16x32_bf16 v[48:51], v[176:179], v[184:187], v[48:51]
	v_mfma_f32_16x16x32_bf16 v[36:39], v[168:171], v[192:195], v[36:39]
	v_mfma_f32_16x16x32_bf16 v[32:35], v[176:179], v[192:195], v[32:35]
	v_mfma_f32_16x16x32_bf16 v[20:23], v[168:171], v[200:203], v[20:23]
	v_mfma_f32_16x16x32_bf16 v[16:19], v[176:179], v[200:203], v[16:19]
	v_mfma_f32_16x16x32_bf16 v[4:7], v[168:171], v[208:211], v[4:7]
	v_mfma_f32_16x16x32_bf16 v[0:3], v[176:179], v[208:211], v[0:3]
	v_mfma_f32_16x16x32_bf16 v[52:55], v[172:175], v[188:191], v[52:55]
	v_mfma_f32_16x16x32_bf16 v[48:51], v[180:183], v[188:191], v[48:51]
	v_mfma_f32_16x16x32_bf16 v[36:39], v[172:175], v[196:199], v[36:39]
	v_mfma_f32_16x16x32_bf16 v[32:35], v[180:183], v[196:199], v[32:35]
	v_mfma_f32_16x16x32_bf16 v[20:23], v[172:175], v[204:207], v[20:23]
	v_mfma_f32_16x16x32_bf16 v[16:19], v[180:183], v[204:207], v[16:19]
	v_mfma_f32_16x16x32_bf16 v[4:7], v[172:175], v[212:215], v[4:7]
	v_mfma_f32_16x16x32_bf16 v[0:3], v[180:183], v[212:215], v[0:3]
	s_setprio 0
	s_barrier
; #define PG8_STAGE(bufoff, gbase, voff) do { _Pragma("unroll") for (int _i = 0; _i < 2; ++_i) \
;         __builtin_amdgcn_global_load_lds((const unsigned*)((const char*)(gbase) + (voff)[_i]), (PG8_LAS unsigned*)(lds + (bufoff) + ldsw + _i * 8192), 16, 0, 0); } while (0)
; #define PG8_LDA(dst, b, h) do { _Pragma("unroll") for (int m = 0; m < 4; ++m) _Pragma("unroll") for (int k = 0; k < 2; ++k) dst[m][k] = *(const PG8_LAS bf16x8*)(lds + PG8_SA(b, h) + aoff + m * 2048 + k * 1024); } while (0)
; #define PG8_LDB(dst, b, h) do { _Pragma("unroll") for (int n = 0; n < 2; ++n) _Pragma("unroll") for (int k = 0; k < 2; ++k) dst[n][k] = *(const PG8_LAS bf16x8*)(lds + PG8_SB(b, h) + boff + n * 2048 + k * 1024); } while (0)
; #define PG8_MMA(ai, bj, At, Bt) do { __builtin_amdgcn_s_setprio(1); _Pragma("unroll") for (int m = 0; m < 4; ++m) _Pragma("unroll") for (int n = 0; n < 2; ++n) _Pragma("unroll") for (int k = 0; k < 2; ++k) \
;         acc[ai][bj][m][n] = __builtin_amdgcn_mfma_f32_16x16x32_bf16(Bt[n][k], At[m][k], acc[ai][bj][m][n], 0, 0, 0); __builtin_amdgcn_s_setprio(0); } while (0)
; #define PG8_WAIT_V(n) asm volatile("s_waitcnt vmcnt(" #n ")" ::: "memory")
; #define PG8_WAIT_L(n) asm volatile("s_waitcnt lgkmcnt(" #n ")" ::: "memory")
; #define PG8_BAR __builtin_amdgcn_s_barrier()
; #define PG8_SCHED __builtin_amdgcn_sched_barrier(0)
; template <class Epi, class Sched, bool ALIGN_EPI = false, bool SP2 = false>
; __device__ __forceinline__ void gemm_phase(PG8_LAS unsigned char* lds, const Gemm g, const Sched& S, const Epi& E) {
;     ...
;             PG8_LDB(B0, 1, 0); PG8_LDB(B1, 1, 1); PG8_SCHED; PG8_LDA(At, 1, 0); PG8_STAGE(PG8_SA(0, 1), a2 + hstepA, voffA);
;             PG8_WAIT_V(8); PG8_WAIT_L(0); PG8_BAR; PG8_MMA(0, 0, At, B0); PG8_MMA(0, 1, At, B1); PG8_BAR; PG8_SCHED;
;             PG8_LDA(At, 1, 1); PG8_STAGE(PG8_SB(1, 0), b3, voffB); PG8_STAGE(PG8_SB(1, 1), b3 + hstepB, voffB); PG8_STAGE(PG8_SA(1, 0), a3, voffA);
;             PG8_WAIT_V(8); PG8_WAIT_L(0); PG8_BAR; PG8_MMA(1, 0, At, B0); PG8_MMA(1, 1, At, B1); PG8_BAR; PG8_SCHED;
	s_add_i32 s4, 0, 0x18000
	s_add_i32 s5, 0, 0x1c000
	v_add_u32_e32 v160, s4, v148
	v_add_u32_e32 v166, s5, v148
	ds_read_b128 v[144:147], v160
	ds_read_b128 v[152:155], v160 offset:1024
	ds_read_b128 v[156:159], v160 offset:2048
	ds_read_b128 v[160:163], v160 offset:3072
	ds_read_b128 v[168:171], v166
	ds_read_b128 v[172:175], v166 offset:1024
	ds_read_b128 v[176:179], v166 offset:2048
	ds_read_b128 v[180:183], v166 offset:3072
	s_add_u32 s36, s36, 0x80000
	s_addc_u32 s37, s37, 0
	s_mov_b32 m0, s38
	v_lshl_add_u64 v[222:223], s[36:37], 0, v[128:129]
	ds_read_b128 v[184:187], v151 offset:32768
	ds_read_b128 v[188:191], v151 offset:33792
	ds_read_b128 v[192:195], v151 offset:34816
	ds_read_b128 v[196:199], v151 offset:35840
	ds_read_b128 v[200:203], v151 offset:36864
	ds_read_b128 v[204:207], v151 offset:37888
	ds_read_b128 v[208:211], v151 offset:38912
	ds_read_b128 v[212:215], v151 offset:39936
	global_load_lds_dwordx4 v[222:223], off
	v_lshl_add_u64 v[222:223], s[36:37], 0, v[132:133]
	s_mov_b32 m0, s39
	s_nop 0
	global_load_lds_dwordx4 v[222:223], off
	s_waitcnt vmcnt(8)
	s_waitcnt lgkmcnt(0)
	s_barrier
	s_setprio 1
	s_waitcnt lgkmcnt(0)
	v_mfma_f32_16x16x32_bf16 v[124:127], v[144:147], v[184:187], v[124:127]
	v_mfma_f32_16x16x32_bf16 v[120:123], v[156:159], v[184:187], v[120:123]
	v_mfma_f32_16x16x32_bf16 v[108:111], v[144:147], v[192:195], v[108:111]
	v_mfma_f32_16x16x32_bf16 v[104:107], v[156:159], v[192:195], v[104:107]
	v_mfma_f32_16x16x32_bf16 v[92:95], v[144:147], v[200:203], v[92:95]
	v_mfma_f32_16x16x32_bf16 v[88:91], v[156:159], v[200:203], v[88:91]
	v_mfma_f32_16x16x32_bf16 v[76:79], v[144:147], v[208:211], v[76:79]
	v_mfma_f32_16x16x32_bf16 v[72:75], v[156:159], v[208:211], v[72:75]
	v_mfma_f32_16x16x32_bf16 v[124:127], v[152:155], v[188:191], v[124:127]
	v_mfma_f32_16x16x32_bf16 v[120:123], v[160:163], v[188:191], v[120:123]
	v_mfma_f32_16x16x32_bf16 v[108:111], v[152:155], v[196:199], v[108:111]
	v_mfma_f32_16x16x32_bf16 v[104:107], v[160:163], v[196:199], v[104:107]
	v_mfma_f32_16x16x32_bf16 v[92:95], v[152:155], v[204:207], v[92:95]
	v_mfma_f32_16x16x32_bf16 v[88:91], v[160:163], v[204:207], v[88:91]
	v_mfma_f32_16x16x32_bf16 v[76:79], v[152:155], v[212:215], v[76:79]
	v_mfma_f32_16x16x32_bf16 v[72:75], v[160:163], v[212:215], v[72:75]
	s_setprio 0
	s_setprio 1
	v_mfma_f32_16x16x32_bf16 v[116:119], v[168:171], v[184:187], v[116:119]
	v_mfma_f32_16x16x32_bf16 v[112:115], v[176:179], v[184:187], v[112:115]
	v_mfma_f32_16x16x32_bf16 v[100:103], v[168:171], v[192:195], v[100:103]
	v_mfma_f32_16x16x32_bf16 v[96:99], v[176:179], v[192:195], v[96:99]
	v_mfma_f32_16x16x32_bf16 v[84:87], v[168:171], v[200:203], v[84:87]
	v_mfma_f32_16x16x32_bf16 v[80:83], v[176:179], v[200:203], v[80:83]
	v_mfma_f32_16x16x32_bf16 v[68:71], v[168:171], v[208:211], v[68:71]
	v_mfma_f32_16x16x32_bf16 v[64:67], v[176:179], v[208:211], v[64:67]
	v_mfma_f32_16x16x32_bf16 v[116:119], v[172:175], v[188:191], v[116:119]
	v_mfma_f32_16x16x32_bf16 v[112:115], v[180:183], v[188:191], v[112:115]
	v_mfma_f32_16x16x32_bf16 v[100:103], v[172:175], v[196:199], v[100:103]
	v_mfma_f32_16x16x32_bf16 v[96:99], v[180:183], v[196:199], v[96:99]
	v_mfma_f32_16x16x32_bf16 v[84:87], v[172:175], v[204:207], v[84:87]
	v_mfma_f32_16x16x32_bf16 v[80:83], v[180:183], v[204:207], v[80:83]
	v_mfma_f32_16x16x32_bf16 v[68:71], v[172:175], v[212:215], v[68:71]
	v_mfma_f32_16x16x32_bf16 v[64:67], v[180:183], v[212:215], v[64:67]
	s_setprio 0
	s_barrier
	s_add_i32 s4, s4, s47
	v_lshl_add_u64 v[164:165], v[164:165], 0, s[16:17]
	s_mov_b32 m0, s4
	ds_read_b128 v[184:187], v151 offset:49152
	ds_read_b128 v[188:191], v151 offset:50176
	ds_read_b128 v[192:195], v151 offset:51200
	ds_read_b128 v[196:199], v151 offset:52224
	ds_read_b128 v[200:203], v151 offset:53248
	ds_read_b128 v[204:207], v151 offset:54272
	ds_read_b128 v[208:211], v151 offset:55296
	ds_read_b128 v[212:215], v151 offset:56320
	global_load_lds_dwordx4 v[164:165], off
	s_add_i32 m0, s4, 0x2000
	s_add_u32 s34, s34, 0x80080
	v_lshl_add_u64 v[164:165], v[216:217], 0, s[16:17]
	s_addc_u32 s35, s35, 0
	s_add_i32 s4, s5, s47
	global_load_lds_dwordx4 v[164:165], off
	v_lshl_add_u64 v[164:165], s[34:35], 0, v[130:131]
	s_mov_b32 m0, s4
	s_nop 0
	global_load_lds_dwordx4 v[164:165], off
	v_lshl_add_u64 v[164:165], s[34:35], 0, v[134:135]
	s_add_i32 m0, s4, 0x2000
	s_nop 0
	global_load_lds_dwordx4 v[164:165], off
	v_lshl_add_u64 v[164:165], v[218:219], 0, s[16:17]
	s_mov_b32 m0, s40
	s_nop 0
	global_load_lds_dwordx4 v[164:165], off
	v_lshl_add_u64 v[164:165], v[220:221], 0, s[16:17]
	s_mov_b32 m0, s41
	s_nop 0
	global_load_lds_dwordx4 v[164:165], off
	s_waitcnt vmcnt(8)
	s_waitcnt lgkmcnt(0)
	s_barrier
; __device__ __forceinline__ unsigned cvt_pk_bf16(float lo, float hi) { unsigned r; asm volatile("v_cvt_pk_bf16_f32 %0, %1, %2" : "=v"(r) : "v"(lo), "v"(hi)); return r; }
; __device__ __forceinline__ float shx(float v, int mask, int lane) { return __int_as_float(__builtin_amdgcn_ds_bpermute((lane ^ mask) << 2, __float_as_int(v))); }
; __device__ __forceinline__ float bf_lo(unsigned w) { return __uint_as_float(w << 16); }
; __device__ __forceinline__ float bf_hi(unsigned w) { return __uint_as_float(w & 0xffff0000u); }
;     __device__ __forceinline__ void operator()(const f32x4 (&acc)[2][2][4][2], const Unit& u, int wr, int wc, int fr, int fq) const {
;     ...
;             for (int m = 0; m < 4; ++m) { const int row = row0 + ai * HALF + m * 16; bf16_t* bp = HB + (size_t)row * 2048 + col0; float s = 0.f;
;                 u32x4 hv[2];
; #pragma unroll
;                 for (int bj = 0; bj < 2; ++bj) hv[bj] = *(const u32x4*)(bp + bj * HALF);
; #pragma unroll
;                 for (int bj = 0; bj < 2; ++bj) { const f32x4 a0 = acc[ai][bj][m][0], a1 = acc[ai][bj][m][1]; const u32x4 x = hv[bj];
;                     const float h0 = bf_lo(x.x) + a0[0], h1 = bf_hi(x.x) + a0[1], h2 = bf_lo(x.y) + a0[2], h3 = bf_hi(x.y) + a0[3], h4 = bf_lo(x.z) + a1[0], h5 = bf_hi(x.z) + a1[1], h6 = bf_lo(x.w) + a1[2], h7 = bf_hi(x.w) + a1[3];
;                     s += (h0 * h0 + h1 * h1) + (h2 * h2 + h3 * h3) + (h4 * h4 + h5 * h5) + (h6 * h6 + h7 * h7);
;                     u32x4 w; w.x = cvt_pk_bf16(h0, h1); w.y = cvt_pk_bf16(h2, h3); w.z = cvt_pk_bf16(h4, h5); w.w = cvt_pk_bf16(h6, h7); *(u32x4*)(bp + bj * HALF) = w; }
;                 { const int ln = fr + 16 * fq; s += shx(s, 16, ln); s += shx(s, 32, ln); }
;                 if (fq == 0) ssq_out[(size_t)row * 32 + u.pn * 4 + wc] = s;
	s_setprio 1
	s_waitcnt lgkmcnt(0)
	v_mfma_f32_16x16x32_bf16 v[60:63], v[144:147], v[184:187], v[60:63]
	v_mfma_f32_16x16x32_bf16 v[56:59], v[156:159], v[184:187], v[56:59]
	v_mfma_f32_16x16x32_bf16 v[44:47], v[144:147], v[192:195], v[44:47]
	v_mfma_f32_16x16x32_bf16 v[40:43], v[156:159], v[192:195], v[40:43]
	v_mfma_f32_16x16x32_bf16 v[28:31], v[144:147], v[200:203], v[28:31]
	v_mfma_f32_16x16x32_bf16 v[24:27], v[156:159], v[200:203], v[24:27]
	v_mfma_f32_16x16x32_bf16 v[12:15], v[144:147], v[208:211], v[12:15]
	v_mfma_f32_16x16x32_bf16 v[8:11], v[156:159], v[208:211], v[8:11]
	v_mfma_f32_16x16x32_bf16 v[60:63], v[152:155], v[188:191], v[60:63]
	v_mfma_f32_16x16x32_bf16 v[56:59], v[160:163], v[188:191], v[56:59]
	v_mfma_f32_16x16x32_bf16 v[44:47], v[152:155], v[196:199], v[44:47]
	v_mfma_f32_16x16x32_bf16 v[40:43], v[160:163], v[196:199], v[40:43]
	v_mfma_f32_16x16x32_bf16 v[28:31], v[152:155], v[204:207], v[28:31]
	v_mfma_f32_16x16x32_bf16 v[24:27], v[160:163], v[204:207], v[24:27]
	v_mfma_f32_16x16x32_bf16 v[12:15], v[152:155], v[212:215], v[12:15]
	v_mfma_f32_16x16x32_bf16 v[8:11], v[160:163], v[212:215], v[8:11]
	s_setprio 0
	s_setprio 1
	v_mfma_f32_16x16x32_bf16 v[52:55], v[168:171], v[184:187], v[52:55]
	v_mfma_f32_16x16x32_bf16 v[48:51], v[176:179], v[184:187], v[48:51]
	v_mfma_f32_16x16x32_bf16 v[36:39], v[168:171], v[192:195], v[36:39]
	v_mfma_f32_16x16x32_bf16 v[32:35], v[176:179], v[192:195], v[32:35]
	v_mfma_f32_16x16x32_bf16 v[20:23], v[168:171], v[200:203], v[20:23]
	v_mfma_f32_16x16x32_bf16 v[16:19], v[176:179], v[200:203], v[16:19]
	v_mfma_f32_16x16x32_bf16 v[4:7], v[168:171], v[208:211], v[4:7]
	v_mfma_f32_16x16x32_bf16 v[0:3], v[176:179], v[208:211], v[0:3]
	v_mfma_f32_16x16x32_bf16 v[52:55], v[172:175], v[188:191], v[52:55]
	v_mfma_f32_16x16x32_bf16 v[48:51], v[180:183], v[188:191], v[48:51]
	v_mfma_f32_16x16x32_bf16 v[36:39], v[172:175], v[196:199], v[36:39]
	v_mfma_f32_16x16x32_bf16 v[32:35], v[180:183], v[196:199], v[32:35]
	v_mfma_f32_16x16x32_bf16 v[20:23], v[172:175], v[204:207], v[20:23]
	v_mfma_f32_16x16x32_bf16 v[16:19], v[180:183], v[204:207], v[16:19]
	v_mfma_f32_16x16x32_bf16 v[4:7], v[172:175], v[212:215], v[4:7]
	v_mfma_f32_16x16x32_bf16 v[0:3], v[180:183], v[212:215], v[0:3]
	s_setprio 0
	s_barrier
	s_add_i32 s56, s56, 2
	s_add_u32 s30, s30, 0x100
	s_addc_u32 s31, s31, 0
	s_add_u32 s54, s54, 0x100
	s_addc_u32 s55, s55, 0
	s_cmp_gt_u32 s56, 29
	s_cbranch_scc0 .LBB0_660
	s_and_b64 vcc, exec, s[48:49]
	s_cbranch_vccz .LBB0_663
	s_barrier
.LBB0_663:
	v_and_b32_e32 v232, 15, v167
	v_lshrrev_b32_e32 v233, 4, v167
	s_lshl_b32 s4, s28, 8
	s_add_i32 s4, s4, s78
	v_or_b32_e32 v234, s4, v232
	s_lshl_b32 s4, s10, 8
	s_or_b32 s4, s4, s73
	v_lshl_add_u32 v235, v233, 3, s4
	v_lshlrev_b32_e32 v235, 1, v235
	v_lshl_add_u32 v235, v234, 12, v235
	v_add_u32_e32 v236, 0x10000, v235
	v_add_u32_e32 v237, 0x20000, v235
	v_add_u32_e32 v238, 0x30000, v235
	v_add_u32_e32 v239, 0x80000, v235
	v_add_u32_e32 v240, 0x90000, v235
	v_add_u32_e32 v241, 0xa0000, v235
	v_add_u32_e32 v242, 0xb0000, v235
	global_load_dwordx4 v[168:171], v235, s[12:13]
	global_load_dwordx4 v[172:175], v235, s[12:13] offset:256
	global_load_dwordx4 v[176:179], v236, s[12:13]
	global_load_dwordx4 v[180:183], v236, s[12:13] offset:256
	global_load_dwordx4 v[184:187], v237, s[12:13]
	global_load_dwordx4 v[188:191], v237, s[12:13] offset:256
	global_load_dwordx4 v[192:195], v238, s[12:13]
	global_load_dwordx4 v[196:199], v238, s[12:13] offset:256
	global_load_dwordx4 v[200:203], v239, s[12:13]
	global_load_dwordx4 v[204:207], v239, s[12:13] offset:256
	global_load_dwordx4 v[208:211], v240, s[12:13]
	global_load_dwordx4 v[212:215], v240, s[12:13] offset:256
	global_load_dwordx4 v[216:219], v241, s[12:13]
	global_load_dwordx4 v[220:223], v241, s[12:13] offset:256
	global_load_dwordx4 v[224:227], v242, s[12:13]
	global_load_dwordx4 v[228:231], v242, s[12:13] offset:256
	s_waitcnt vmcnt(0)
	v_mov_b32_e32 v164, v167
	s_lshl_b32 s4, s28, 8
	s_add_i32 s4, s4, s78
	v_and_b32_e32 v165, 15, v164
	v_or_b32_e32 v146, s4, v165
	s_lshl_b32 s4, s10, 8
	v_ashrrev_i32_e32 v166, 4, v164
	s_or_b32 s4, s4, s73
	v_ashrrev_i32_e32 v147, 31, v146
	v_lshl_add_u32 v144, v166, 3, s4
	v_lshlrev_b64 v[152:153], 12, v[146:147]
	v_ashrrev_i32_e32 v145, 31, v144
	v_lshl_add_u64 v[152:153], s[12:13], 0, v[152:153]
	v_lshl_add_u64 v[162:163], v[144:145], 1, v[152:153]
	s_nop 1
	v_mov_b32_e32 v154, v168
	v_mov_b32_e32 v155, v169
	v_mov_b32_e32 v156, v170
	v_mov_b32_e32 v157, v171
	v_mov_b32_e32 v158, v172
	v_mov_b32_e32 v159, v173
	v_mov_b32_e32 v160, v174
	v_mov_b32_e32 v161, v175
	v_cmp_gt_u32_e32 vcc, 16, v164
	v_lshlrev_b32_e32 v152, 6, v166
	v_lshlrev_b32_e32 v164, 2, v165
	v_bitop3_b32 v153, v152, 64, v164 bitop3:0x36
	v_bitop3_b32 v152, v152, s46, v164 bitop3:0x36
	s_lshl_b32 s28, s10, 2
	s_ashr_i32 s29, s28, 31
	v_lshlrev_b32_e32 v164, 16, v154
	v_and_b32_e32 v154, 0xffff0000, v154
	v_lshlrev_b32_e32 v165, 16, v155
	v_and_b32_e32 v155, 0xffff0000, v155
	v_lshlrev_b32_e32 v169, 16, v158
	v_and_b32_e32 v158, 0xffff0000, v158
	v_lshlrev_b32_e32 v170, 16, v159
	v_and_b32_e32 v159, 0xffff0000, v159
	v_lshlrev_b32_e32 v166, 16, v156
	v_and_b32_e32 v156, 0xffff0000, v156
	v_lshlrev_b32_e32 v168, 16, v157
	v_and_b32_e32 v157, 0xffff0000, v157
	v_lshlrev_b32_e32 v171, 16, v160
	v_and_b32_e32 v160, 0xffff0000, v160
	v_lshlrev_b32_e32 v172, 16, v161
	v_and_b32_e32 v161, 0xffff0000, v161
	v_add_f32_e32 v125, v125, v154
	v_add_f32_e32 v127, v127, v155
	v_add_f32_e32 v117, v117, v158
	v_add_f32_e32 v119, v119, v159
	v_add_f32_e32 v124, v124, v164
	v_add_f32_e32 v126, v126, v165
	v_add_f32_e32 v121, v121, v156
	v_add_f32_e32 v123, v123, v157
	v_add_f32_e32 v116, v116, v169
	v_add_f32_e32 v118, v118, v170
	v_add_f32_e32 v154, v112, v171
	v_add_f32_e32 v155, v113, v160
	v_add_f32_e32 v156, v114, v172
	v_add_f32_e32 v157, v115, v161
	v_mul_f32_e32 v114, v125, v125
	v_mul_f32_e32 v115, v127, v127
	v_cvt_pk_bf16_f32 v112, v124, v125
	v_cvt_pk_bf16_f32 v113, v126, v127
	v_mul_f32_e32 v125, v117, v117
	v_mul_f32_e32 v127, v119, v119
	v_add_f32_e32 v120, v120, v166
	v_mul_f32_e32 v158, v121, v121
	v_mul_f32_e32 v160, v155, v155
	v_fmac_f32_e32 v114, v124, v124
	v_fmac_f32_e32 v115, v126, v126
	v_fmac_f32_e32 v125, v116, v116
	v_fmac_f32_e32 v127, v118, v118
	v_add_f32_e32 v122, v122, v168
	v_mul_f32_e32 v159, v123, v123
	v_mul_f32_e32 v161, v157, v157
	v_fmac_f32_e32 v158, v120, v120
	v_fmac_f32_e32 v160, v154, v154
	v_add_f32_e32 v114, v114, v115
	v_add_f32_e32 v115, v125, v127
	v_fmac_f32_e32 v159, v122, v122
	v_fmac_f32_e32 v161, v156, v156
	v_add_f32_e32 v114, v158, v114
	v_add_f32_e32 v115, v160, v115
	v_add_f32_e32 v114, v159, v114
	v_add_f32_e32 v115, v161, v115
	v_add_f32_e32 v124, v114, v115
	ds_bpermute_b32 v125, v153, v124
	v_cvt_pk_bf16_f32 v114, v120, v121
	v_cvt_pk_bf16_f32 v115, v122, v123
	global_store_dwordx4 v[162:163], v[112:115], off
	s_waitcnt lgkmcnt(0)
; __device__ __forceinline__ unsigned cvt_pk_bf16(float lo, float hi) { unsigned r; asm volatile("v_cvt_pk_bf16_f32 %0, %1, %2" : "=v"(r) : "v"(lo), "v"(hi)); return r; }
; __device__ __forceinline__ float shx(float v, int mask, int lane) { return __int_as_float(__builtin_amdgcn_ds_bpermute((lane ^ mask) << 2, __float_as_int(v))); }
; __device__ __forceinline__ float bf_lo(unsigned w) { return __uint_as_float(w << 16); }
; __device__ __forceinline__ float bf_hi(unsigned w) { return __uint_as_float(w & 0xffff0000u); }
;     __device__ __forceinline__ void operator()(const f32x4 (&acc)[2][2][4][2], const Unit& u, int wr, int wc, int fr, int fq) const {
;     ...
;             for (int m = 0; m < 4; ++m) { const int row = row0 + ai * HALF + m * 16; bf16_t* bp = HB + (size_t)row * 2048 + col0; float s = 0.f;
;                 u32x4 hv[2];
; #pragma unroll
;                 for (int bj = 0; bj < 2; ++bj) hv[bj] = *(const u32x4*)(bp + bj * HALF);
; #pragma unroll
;                 for (int bj = 0; bj < 2; ++bj) { const f32x4 a0 = acc[ai][bj][m][0], a1 = acc[ai][bj][m][1]; const u32x4 x = hv[bj];
;                     const float h0 = bf_lo(x.x) + a0[0], h1 = bf_hi(x.x) + a0[1], h2 = bf_lo(x.y) + a0[2], h3 = bf_hi(x.y) + a0[3], h4 = bf_lo(x.z) + a1[0], h5 = bf_hi(x.z) + a1[1], h6 = bf_lo(x.w) + a1[2], h7 = bf_hi(x.w) + a1[3];
;                     s += (h0 * h0 + h1 * h1) + (h2 * h2 + h3 * h3) + (h4 * h4 + h5 * h5) + (h6 * h6 + h7 * h7);
;                     u32x4 w; w.x = cvt_pk_bf16(h0, h1); w.y = cvt_pk_bf16(h2, h3); w.z = cvt_pk_bf16(h4, h5); w.w = cvt_pk_bf16(h6, h7); *(u32x4*)(bp + bj * HALF) = w; }
;                 { const int ln = fr + 16 * fq; s += shx(s, 16, ln); s += shx(s, 32, ln); }
;                 if (fq == 0) ssq_out[(size_t)row * 32 + u.pn * 4 + wc] = s;
	s_nop 0
	v_add_f32_e32 v112, v124, v125
	ds_bpermute_b32 v113, v152, v112
	v_cvt_pk_bf16_f32 v114, v116, v117
	v_cvt_pk_bf16_f32 v115, v118, v119
	v_cvt_pk_bf16_f32 v116, v154, v155
	v_cvt_pk_bf16_f32 v117, v156, v157
	global_store_dwordx4 v[162:163], v[114:117], off offset:256
	s_and_saveexec_b64 s[30:31], vcc
	s_cbranch_execz .LBB0_665
	s_waitcnt lgkmcnt(0)
	v_add_f32_e32 v114, v112, v113
	v_lshlrev_b64 v[112:113], 7, v[146:147]
	v_lshl_add_u64 v[112:113], s[14:15], 0, v[112:113]
	v_lshl_add_u64 v[112:113], s[28:29], 2, v[112:113]
	s_lshl_b32 s10, s72, 2
	v_lshl_add_u64 v[112:113], v[112:113], 0, s[10:11]
	global_store_dword v[112:113], v114, off
.LBB0_665:
	s_or_b64 exec, exec, s[30:31]
	v_or_b32_e32 v112, 16, v146
	s_waitcnt lgkmcnt(0)
	v_ashrrev_i32_e32 v113, 31, v112
	v_lshlrev_b64 v[114:115], 12, v[112:113]
	v_lshl_add_u64 v[114:115], s[12:13], 0, v[114:115]
	v_lshl_add_u64 v[122:123], v[144:145], 1, v[114:115]
	s_nop 1
	v_mov_b32_e32 v114, v176
	v_mov_b32_e32 v115, v177
	v_mov_b32_e32 v116, v178
	v_mov_b32_e32 v117, v179
	v_mov_b32_e32 v118, v180
	v_mov_b32_e32 v119, v181
	v_mov_b32_e32 v120, v182
	v_mov_b32_e32 v121, v183
	v_lshlrev_b32_e32 v124, 16, v114
	v_and_b32_e32 v114, 0xffff0000, v114
	v_lshlrev_b32_e32 v125, 16, v115
	v_and_b32_e32 v115, 0xffff0000, v115
	v_lshlrev_b32_e32 v147, 16, v118
	v_and_b32_e32 v118, 0xffff0000, v118
	v_lshlrev_b32_e32 v154, 16, v119
	v_and_b32_e32 v119, 0xffff0000, v119
	v_lshlrev_b32_e32 v126, 16, v116
	v_and_b32_e32 v116, 0xffff0000, v116
	v_lshlrev_b32_e32 v127, 16, v117
	v_and_b32_e32 v117, 0xffff0000, v117
	v_lshlrev_b32_e32 v155, 16, v120
	v_and_b32_e32 v120, 0xffff0000, v120
	v_lshlrev_b32_e32 v156, 16, v121
	v_and_b32_e32 v121, 0xffff0000, v121
	v_add_f32_e32 v109, v109, v114
	v_add_f32_e32 v111, v111, v115
	v_add_f32_e32 v101, v101, v118
	v_add_f32_e32 v103, v103, v119
	v_add_f32_e32 v108, v108, v124
	v_add_f32_e32 v110, v110, v125
	v_add_f32_e32 v105, v105, v116
	v_add_f32_e32 v107, v107, v117
	v_add_f32_e32 v100, v100, v147
	v_add_f32_e32 v102, v102, v154
	v_add_f32_e32 v114, v96, v155
	v_add_f32_e32 v115, v97, v120
	v_add_f32_e32 v116, v98, v156
	v_add_f32_e32 v117, v99, v121
	v_mul_f32_e32 v98, v109, v109
	v_mul_f32_e32 v99, v111, v111
	v_cvt_pk_bf16_f32 v96, v108, v109
	v_cvt_pk_bf16_f32 v97, v110, v111
	v_mul_f32_e32 v109, v101, v101
	v_mul_f32_e32 v111, v103, v103
	v_add_f32_e32 v104, v104, v126
	v_mul_f32_e32 v118, v105, v105
	v_mul_f32_e32 v120, v115, v115
	v_fmac_f32_e32 v98, v108, v108
	v_fmac_f32_e32 v99, v110, v110
	v_fmac_f32_e32 v109, v100, v100
	v_fmac_f32_e32 v111, v102, v102
	v_add_f32_e32 v106, v106, v127
	v_mul_f32_e32 v119, v107, v107
	v_mul_f32_e32 v121, v117, v117
	v_fmac_f32_e32 v118, v104, v104
	v_fmac_f32_e32 v120, v114, v114
	v_add_f32_e32 v98, v98, v99
	v_add_f32_e32 v99, v109, v111
	v_fmac_f32_e32 v119, v106, v106
	v_fmac_f32_e32 v121, v116, v116
	v_add_f32_e32 v98, v118, v98
	v_add_f32_e32 v99, v120, v99
	v_add_f32_e32 v98, v119, v98
	v_add_f32_e32 v99, v121, v99
	v_add_f32_e32 v108, v98, v99
	ds_bpermute_b32 v109, v153, v108
	v_cvt_pk_bf16_f32 v98, v104, v105
	v_cvt_pk_bf16_f32 v99, v106, v107
	global_store_dwordx4 v[122:123], v[96:99], off
	s_waitcnt lgkmcnt(0)
	s_nop 0
	v_add_f32_e32 v96, v108, v109
	ds_bpermute_b32 v97, v152, v96
	v_cvt_pk_bf16_f32 v98, v100, v101
	v_cvt_pk_bf16_f32 v99, v102, v103
	v_cvt_pk_bf16_f32 v100, v114, v115
	v_cvt_pk_bf16_f32 v101, v116, v117
	global_store_dwordx4 v[122:123], v[98:101], off offset:256
	s_and_saveexec_b64 s[30:31], vcc
	s_cbranch_execz .LBB0_667
	s_waitcnt lgkmcnt(0)
	v_add_f32_e32 v98, v96, v97
	v_lshlrev_b64 v[96:97], 7, v[112:113]
	v_lshl_add_u64 v[96:97], s[14:15], 0, v[96:97]
	v_lshl_add_u64 v[96:97], s[28:29], 2, v[96:97]
	s_lshl_b32 s10, s72, 2
	v_lshl_add_u64 v[96:97], v[96:97], 0, s[10:11]
	global_store_dword v[96:97], v98, off
.LBB0_667:
	s_or_b64 exec, exec, s[30:31]
	v_or_b32_e32 v96, 32, v146
	s_waitcnt lgkmcnt(0)
	v_ashrrev_i32_e32 v97, 31, v96
	v_lshlrev_b64 v[98:99], 12, v[96:97]
	v_lshl_add_u64 v[98:99], s[12:13], 0, v[98:99]
	v_lshl_add_u64 v[106:107], v[144:145], 1, v[98:99]
	s_nop 1
	v_mov_b32_e32 v98, v184
	v_mov_b32_e32 v99, v185
	v_mov_b32_e32 v100, v186
	v_mov_b32_e32 v101, v187
	v_mov_b32_e32 v102, v188
	v_mov_b32_e32 v103, v189
	v_mov_b32_e32 v104, v190
	v_mov_b32_e32 v105, v191
	v_lshlrev_b32_e32 v108, 16, v98
	v_and_b32_e32 v98, 0xffff0000, v98
	v_lshlrev_b32_e32 v109, 16, v99
	v_and_b32_e32 v99, 0xffff0000, v99
	v_lshlrev_b32_e32 v112, 16, v102
	v_and_b32_e32 v102, 0xffff0000, v102
	v_lshlrev_b32_e32 v113, 16, v103
	v_and_b32_e32 v103, 0xffff0000, v103
	v_lshlrev_b32_e32 v110, 16, v100
	v_and_b32_e32 v100, 0xffff0000, v100
	v_lshlrev_b32_e32 v111, 16, v101
	v_and_b32_e32 v101, 0xffff0000, v101
	v_lshlrev_b32_e32 v114, 16, v104
	v_and_b32_e32 v104, 0xffff0000, v104
	v_lshlrev_b32_e32 v115, 16, v105
	v_and_b32_e32 v105, 0xffff0000, v105
	v_add_f32_e32 v93, v93, v98
	v_add_f32_e32 v95, v95, v99
	v_add_f32_e32 v85, v85, v102
	v_add_f32_e32 v87, v87, v103
	v_add_f32_e32 v92, v92, v108
	v_add_f32_e32 v94, v94, v109
	v_add_f32_e32 v89, v89, v100
	v_add_f32_e32 v91, v91, v101
	v_add_f32_e32 v84, v84, v112
	v_add_f32_e32 v86, v86, v113
	v_add_f32_e32 v98, v80, v114
	v_add_f32_e32 v99, v81, v104
	v_add_f32_e32 v100, v82, v115
	v_add_f32_e32 v101, v83, v105
	v_mul_f32_e32 v82, v93, v93
	v_mul_f32_e32 v83, v95, v95
	v_cvt_pk_bf16_f32 v80, v92, v93
	v_cvt_pk_bf16_f32 v81, v94, v95
	v_mul_f32_e32 v93, v85, v85
	v_mul_f32_e32 v95, v87, v87
	v_add_f32_e32 v88, v88, v110
	v_mul_f32_e32 v102, v89, v89
	v_mul_f32_e32 v104, v99, v99
	v_fmac_f32_e32 v82, v92, v92
	v_fmac_f32_e32 v83, v94, v94
	v_fmac_f32_e32 v93, v84, v84
	v_fmac_f32_e32 v95, v86, v86
	v_add_f32_e32 v90, v90, v111
	v_mul_f32_e32 v103, v91, v91
	v_mul_f32_e32 v105, v101, v101
	v_fmac_f32_e32 v102, v88, v88
	v_fmac_f32_e32 v104, v98, v98
	v_add_f32_e32 v82, v82, v83
	v_add_f32_e32 v83, v93, v95
	v_fmac_f32_e32 v103, v90, v90
	v_fmac_f32_e32 v105, v100, v100
	v_add_f32_e32 v82, v102, v82
	v_add_f32_e32 v83, v104, v83
	v_add_f32_e32 v82, v103, v82
	v_add_f32_e32 v83, v105, v83
	v_add_f32_e32 v92, v82, v83
	ds_bpermute_b32 v93, v153, v92
	v_cvt_pk_bf16_f32 v82, v88, v89
	v_cvt_pk_bf16_f32 v83, v90, v91
	global_store_dwordx4 v[106:107], v[80:83], off
	s_waitcnt lgkmcnt(0)
	s_nop 0
	v_add_f32_e32 v80, v92, v93
	ds_bpermute_b32 v81, v152, v80
	v_cvt_pk_bf16_f32 v82, v84, v85
	v_cvt_pk_bf16_f32 v83, v86, v87
	v_cvt_pk_bf16_f32 v84, v98, v99
	v_cvt_pk_bf16_f32 v85, v100, v101
	global_store_dwordx4 v[106:107], v[82:85], off offset:256
	s_and_saveexec_b64 s[30:31], vcc
	s_cbranch_execz .LBB0_669
	s_waitcnt lgkmcnt(0)
	v_add_f32_e32 v82, v80, v81
	v_lshlrev_b64 v[80:81], 7, v[96:97]
	v_lshl_add_u64 v[80:81], s[14:15], 0, v[80:81]
	v_lshl_add_u64 v[80:81], s[28:29], 2, v[80:81]
	s_lshl_b32 s10, s72, 2
	v_lshl_add_u64 v[80:81], v[80:81], 0, s[10:11]
	global_store_dword v[80:81], v82, off
; __device__ __forceinline__ unsigned cvt_pk_bf16(float lo, float hi) { unsigned r; asm volatile("v_cvt_pk_bf16_f32 %0, %1, %2" : "=v"(r) : "v"(lo), "v"(hi)); return r; }
; __device__ __forceinline__ float shx(float v, int mask, int lane) { return __int_as_float(__builtin_amdgcn_ds_bpermute((lane ^ mask) << 2, __float_as_int(v))); }
; __device__ __forceinline__ float bf_lo(unsigned w) { return __uint_as_float(w << 16); }
; __device__ __forceinline__ float bf_hi(unsigned w) { return __uint_as_float(w & 0xffff0000u); }
;     __device__ __forceinline__ void operator()(const f32x4 (&acc)[2][2][4][2], const Unit& u, int wr, int wc, int fr, int fq) const {
;     ...
;             for (int m = 0; m < 4; ++m) { const int row = row0 + ai * HALF + m * 16; bf16_t* bp = HB + (size_t)row * 2048 + col0; float s = 0.f;
;                 u32x4 hv[2];
; #pragma unroll
;                 for (int bj = 0; bj < 2; ++bj) hv[bj] = *(const u32x4*)(bp + bj * HALF);
; #pragma unroll
;                 for (int bj = 0; bj < 2; ++bj) { const f32x4 a0 = acc[ai][bj][m][0], a1 = acc[ai][bj][m][1]; const u32x4 x = hv[bj];
;                     const float h0 = bf_lo(x.x) + a0[0], h1 = bf_hi(x.x) + a0[1], h2 = bf_lo(x.y) + a0[2], h3 = bf_hi(x.y) + a0[3], h4 = bf_lo(x.z) + a1[0], h5 = bf_hi(x.z) + a1[1], h6 = bf_lo(x.w) + a1[2], h7 = bf_hi(x.w) + a1[3];
;                     s += (h0 * h0 + h1 * h1) + (h2 * h2 + h3 * h3) + (h4 * h4 + h5 * h5) + (h6 * h6 + h7 * h7);
;                     u32x4 w; w.x = cvt_pk_bf16(h0, h1); w.y = cvt_pk_bf16(h2, h3); w.z = cvt_pk_bf16(h4, h5); w.w = cvt_pk_bf16(h6, h7); *(u32x4*)(bp + bj * HALF) = w; }
;                 { const int ln = fr + 16 * fq; s += shx(s, 16, ln); s += shx(s, 32, ln); }
;                 if (fq == 0) ssq_out[(size_t)row * 32 + u.pn * 4 + wc] = s;
.LBB0_669:
	s_or_b64 exec, exec, s[30:31]
	v_or_b32_e32 v80, 48, v146
	s_waitcnt lgkmcnt(0)
	v_ashrrev_i32_e32 v81, 31, v80
	v_lshlrev_b64 v[82:83], 12, v[80:81]
	v_lshl_add_u64 v[82:83], s[12:13], 0, v[82:83]
	v_lshl_add_u64 v[90:91], v[144:145], 1, v[82:83]
	s_nop 1
	v_mov_b32_e32 v82, v192
	v_mov_b32_e32 v83, v193
	v_mov_b32_e32 v84, v194
	v_mov_b32_e32 v85, v195
	v_mov_b32_e32 v86, v196
	v_mov_b32_e32 v87, v197
	v_mov_b32_e32 v88, v198
	v_mov_b32_e32 v89, v199
	v_lshlrev_b32_e32 v92, 16, v82
	v_and_b32_e32 v82, 0xffff0000, v82
	v_lshlrev_b32_e32 v93, 16, v83
	v_and_b32_e32 v83, 0xffff0000, v83
	v_lshlrev_b32_e32 v96, 16, v86
	v_and_b32_e32 v86, 0xffff0000, v86
	v_lshlrev_b32_e32 v97, 16, v87
	v_and_b32_e32 v87, 0xffff0000, v87
	v_lshlrev_b32_e32 v94, 16, v84
	v_and_b32_e32 v84, 0xffff0000, v84
	v_lshlrev_b32_e32 v95, 16, v85
	v_and_b32_e32 v85, 0xffff0000, v85
	v_lshlrev_b32_e32 v98, 16, v88
	v_and_b32_e32 v88, 0xffff0000, v88
	v_lshlrev_b32_e32 v99, 16, v89
	v_and_b32_e32 v89, 0xffff0000, v89
	v_add_f32_e32 v77, v77, v82
	v_add_f32_e32 v79, v79, v83
	v_add_f32_e32 v69, v69, v86
	v_add_f32_e32 v71, v71, v87
	v_add_f32_e32 v76, v76, v92
	v_add_f32_e32 v78, v78, v93
	v_add_f32_e32 v73, v73, v84
	v_add_f32_e32 v75, v75, v85
	v_add_f32_e32 v68, v68, v96
	v_add_f32_e32 v70, v70, v97
	v_add_f32_e32 v82, v64, v98
	v_add_f32_e32 v83, v65, v88
	v_add_f32_e32 v84, v66, v99
	v_add_f32_e32 v85, v67, v89
	v_mul_f32_e32 v66, v77, v77
	v_mul_f32_e32 v67, v79, v79
	v_cvt_pk_bf16_f32 v64, v76, v77
	v_cvt_pk_bf16_f32 v65, v78, v79
	v_mul_f32_e32 v77, v69, v69
	v_mul_f32_e32 v79, v71, v71
	v_add_f32_e32 v72, v72, v94
	v_mul_f32_e32 v86, v73, v73
	v_mul_f32_e32 v88, v83, v83
	v_fmac_f32_e32 v66, v76, v76
	v_fmac_f32_e32 v67, v78, v78
	v_fmac_f32_e32 v77, v68, v68
	v_fmac_f32_e32 v79, v70, v70
	v_add_f32_e32 v74, v74, v95
	v_mul_f32_e32 v87, v75, v75
	v_mul_f32_e32 v89, v85, v85
	v_fmac_f32_e32 v86, v72, v72
	v_fmac_f32_e32 v88, v82, v82
	v_add_f32_e32 v66, v66, v67
	v_add_f32_e32 v67, v77, v79
	v_fmac_f32_e32 v87, v74, v74
	v_fmac_f32_e32 v89, v84, v84
	v_add_f32_e32 v66, v86, v66
	v_add_f32_e32 v67, v88, v67
	v_add_f32_e32 v66, v87, v66
	v_add_f32_e32 v67, v89, v67
	v_add_f32_e32 v76, v66, v67
	ds_bpermute_b32 v77, v153, v76
	v_cvt_pk_bf16_f32 v66, v72, v73
	v_cvt_pk_bf16_f32 v67, v74, v75
	global_store_dwordx4 v[90:91], v[64:67], off
	s_waitcnt lgkmcnt(0)
	s_nop 0
	v_add_f32_e32 v64, v76, v77
	ds_bpermute_b32 v65, v152, v64
	v_cvt_pk_bf16_f32 v66, v68, v69
	v_cvt_pk_bf16_f32 v67, v70, v71
	v_cvt_pk_bf16_f32 v68, v82, v83
	v_cvt_pk_bf16_f32 v69, v84, v85
	global_store_dwordx4 v[90:91], v[66:69], off offset:256
	s_and_saveexec_b64 s[30:31], vcc
	s_cbranch_execz .LBB0_671
	s_waitcnt lgkmcnt(0)
	v_add_f32_e32 v66, v64, v65
	v_lshlrev_b64 v[64:65], 7, v[80:81]
	v_lshl_add_u64 v[64:65], s[14:15], 0, v[64:65]
	v_lshl_add_u64 v[64:65], s[28:29], 2, v[64:65]
	s_lshl_b32 s10, s72, 2
	v_lshl_add_u64 v[64:65], v[64:65], 0, s[10:11]
	global_store_dword v[64:65], v66, off
.LBB0_671:
	s_or_b64 exec, exec, s[30:31]
	v_add_u32_e32 v64, 0x80, v146
	s_waitcnt lgkmcnt(0)
	v_ashrrev_i32_e32 v65, 31, v64
	v_lshlrev_b64 v[66:67], 12, v[64:65]
	v_lshl_add_u64 v[66:67], s[12:13], 0, v[66:67]
	v_lshl_add_u64 v[74:75], v[144:145], 1, v[66:67]
	s_nop 1
	v_mov_b32_e32 v66, v200
	v_mov_b32_e32 v67, v201
	v_mov_b32_e32 v68, v202
	v_mov_b32_e32 v69, v203
	v_mov_b32_e32 v70, v204
	v_mov_b32_e32 v71, v205
	v_mov_b32_e32 v72, v206
	v_mov_b32_e32 v73, v207
	v_lshlrev_b32_e32 v76, 16, v66
	v_and_b32_e32 v66, 0xffff0000, v66
	v_lshlrev_b32_e32 v77, 16, v67
	v_and_b32_e32 v67, 0xffff0000, v67
	v_lshlrev_b32_e32 v80, 16, v70
	v_and_b32_e32 v70, 0xffff0000, v70
	v_lshlrev_b32_e32 v81, 16, v71
	v_and_b32_e32 v71, 0xffff0000, v71
	v_lshlrev_b32_e32 v78, 16, v68
	v_and_b32_e32 v68, 0xffff0000, v68
	v_lshlrev_b32_e32 v79, 16, v69
	v_and_b32_e32 v69, 0xffff0000, v69
	v_lshlrev_b32_e32 v82, 16, v72
	v_and_b32_e32 v72, 0xffff0000, v72
	v_lshlrev_b32_e32 v83, 16, v73
	v_and_b32_e32 v73, 0xffff0000, v73
	v_add_f32_e32 v61, v61, v66
	v_add_f32_e32 v63, v63, v67
	v_add_f32_e32 v53, v53, v70
	v_add_f32_e32 v55, v55, v71
	v_add_f32_e32 v60, v60, v76
	v_add_f32_e32 v62, v62, v77
	v_add_f32_e32 v57, v57, v68
	v_add_f32_e32 v59, v59, v69
	v_add_f32_e32 v52, v52, v80
	v_add_f32_e32 v54, v54, v81
	v_add_f32_e32 v66, v48, v82
	v_add_f32_e32 v67, v49, v72
	v_add_f32_e32 v68, v50, v83
	v_add_f32_e32 v69, v51, v73
	v_mul_f32_e32 v50, v61, v61
	v_mul_f32_e32 v51, v63, v63
	v_cvt_pk_bf16_f32 v48, v60, v61
	v_cvt_pk_bf16_f32 v49, v62, v63
	v_mul_f32_e32 v61, v53, v53
	v_mul_f32_e32 v63, v55, v55
	v_add_f32_e32 v56, v56, v78
	v_mul_f32_e32 v70, v57, v57
	v_mul_f32_e32 v72, v67, v67
	v_fmac_f32_e32 v50, v60, v60
	v_fmac_f32_e32 v51, v62, v62
	v_fmac_f32_e32 v61, v52, v52
	v_fmac_f32_e32 v63, v54, v54
	v_add_f32_e32 v58, v58, v79
	v_mul_f32_e32 v71, v59, v59
	v_mul_f32_e32 v73, v69, v69
	v_fmac_f32_e32 v70, v56, v56
	v_fmac_f32_e32 v72, v66, v66
	v_add_f32_e32 v50, v50, v51
	v_add_f32_e32 v51, v61, v63
	v_fmac_f32_e32 v71, v58, v58
	v_fmac_f32_e32 v73, v68, v68
	v_add_f32_e32 v50, v70, v50
	v_add_f32_e32 v51, v72, v51
	v_add_f32_e32 v50, v71, v50
	v_add_f32_e32 v51, v73, v51
	v_add_f32_e32 v60, v50, v51
	ds_bpermute_b32 v61, v153, v60
	v_cvt_pk_bf16_f32 v50, v56, v57
	v_cvt_pk_bf16_f32 v51, v58, v59
	global_store_dwordx4 v[74:75], v[48:51], off
	s_waitcnt lgkmcnt(0)
	s_nop 0
	v_add_f32_e32 v48, v60, v61
	ds_bpermute_b32 v49, v152, v48
	v_cvt_pk_bf16_f32 v50, v52, v53
	v_cvt_pk_bf16_f32 v51, v54, v55
	v_cvt_pk_bf16_f32 v52, v66, v67
	v_cvt_pk_bf16_f32 v53, v68, v69
	global_store_dwordx4 v[74:75], v[50:53], off offset:256
	s_and_saveexec_b64 s[30:31], vcc
	s_cbranch_execz .LBB0_673
	s_waitcnt lgkmcnt(0)
	v_add_f32_e32 v50, v48, v49
	v_lshlrev_b64 v[48:49], 7, v[64:65]
	v_lshl_add_u64 v[48:49], s[14:15], 0, v[48:49]
	v_lshl_add_u64 v[48:49], s[28:29], 2, v[48:49]
	s_lshl_b32 s10, s72, 2
	v_lshl_add_u64 v[48:49], v[48:49], 0, s[10:11]
	global_store_dword v[48:49], v50, off
; __device__ __forceinline__ unsigned cvt_pk_bf16(float lo, float hi) { unsigned r; asm volatile("v_cvt_pk_bf16_f32 %0, %1, %2" : "=v"(r) : "v"(lo), "v"(hi)); return r; }
; __device__ __forceinline__ float shx(float v, int mask, int lane) { return __int_as_float(__builtin_amdgcn_ds_bpermute((lane ^ mask) << 2, __float_as_int(v))); }
; __device__ __forceinline__ float bf_lo(unsigned w) { return __uint_as_float(w << 16); }
; __device__ __forceinline__ float bf_hi(unsigned w) { return __uint_as_float(w & 0xffff0000u); }
;     __device__ __forceinline__ void operator()(const f32x4 (&acc)[2][2][4][2], const Unit& u, int wr, int wc, int fr, int fq) const {
;     ...
;             for (int m = 0; m < 4; ++m) { const int row = row0 + ai * HALF + m * 16; bf16_t* bp = HB + (size_t)row * 2048 + col0; float s = 0.f;
;                 u32x4 hv[2];
; #pragma unroll
;                 for (int bj = 0; bj < 2; ++bj) hv[bj] = *(const u32x4*)(bp + bj * HALF);
; #pragma unroll
;                 for (int bj = 0; bj < 2; ++bj) { const f32x4 a0 = acc[ai][bj][m][0], a1 = acc[ai][bj][m][1]; const u32x4 x = hv[bj];
;                     const float h0 = bf_lo(x.x) + a0[0], h1 = bf_hi(x.x) + a0[1], h2 = bf_lo(x.y) + a0[2], h3 = bf_hi(x.y) + a0[3], h4 = bf_lo(x.z) + a1[0], h5 = bf_hi(x.z) + a1[1], h6 = bf_lo(x.w) + a1[2], h7 = bf_hi(x.w) + a1[3];
;                     s += (h0 * h0 + h1 * h1) + (h2 * h2 + h3 * h3) + (h4 * h4 + h5 * h5) + (h6 * h6 + h7 * h7);
;                     u32x4 w; w.x = cvt_pk_bf16(h0, h1); w.y = cvt_pk_bf16(h2, h3); w.z = cvt_pk_bf16(h4, h5); w.w = cvt_pk_bf16(h6, h7); *(u32x4*)(bp + bj * HALF) = w; }
;                 { const int ln = fr + 16 * fq; s += shx(s, 16, ln); s += shx(s, 32, ln); }
;                 if (fq == 0) ssq_out[(size_t)row * 32 + u.pn * 4 + wc] = s;
.LBB0_673:
	s_or_b64 exec, exec, s[30:31]
	v_add_u32_e32 v48, 0x90, v146
	s_waitcnt lgkmcnt(0)
	v_ashrrev_i32_e32 v49, 31, v48
	v_lshlrev_b64 v[50:51], 12, v[48:49]
	v_lshl_add_u64 v[50:51], s[12:13], 0, v[50:51]
	v_lshl_add_u64 v[58:59], v[144:145], 1, v[50:51]
	s_nop 1
	v_mov_b32_e32 v50, v208
	v_mov_b32_e32 v51, v209
	v_mov_b32_e32 v52, v210
	v_mov_b32_e32 v53, v211
	v_mov_b32_e32 v54, v212
	v_mov_b32_e32 v55, v213
	v_mov_b32_e32 v56, v214
	v_mov_b32_e32 v57, v215
	v_lshlrev_b32_e32 v60, 16, v50
	v_and_b32_e32 v50, 0xffff0000, v50
	v_lshlrev_b32_e32 v61, 16, v51
	v_and_b32_e32 v51, 0xffff0000, v51
	v_lshlrev_b32_e32 v64, 16, v54
	v_and_b32_e32 v54, 0xffff0000, v54
	v_lshlrev_b32_e32 v65, 16, v55
	v_and_b32_e32 v55, 0xffff0000, v55
	v_lshlrev_b32_e32 v62, 16, v52
	v_and_b32_e32 v52, 0xffff0000, v52
	v_lshlrev_b32_e32 v63, 16, v53
	v_and_b32_e32 v53, 0xffff0000, v53
	v_lshlrev_b32_e32 v66, 16, v56
	v_and_b32_e32 v56, 0xffff0000, v56
	v_lshlrev_b32_e32 v67, 16, v57
	v_and_b32_e32 v57, 0xffff0000, v57
	v_add_f32_e32 v45, v45, v50
	v_add_f32_e32 v47, v47, v51
	v_add_f32_e32 v37, v37, v54
	v_add_f32_e32 v39, v39, v55
	v_add_f32_e32 v44, v44, v60
	v_add_f32_e32 v46, v46, v61
	v_add_f32_e32 v41, v41, v52
	v_add_f32_e32 v43, v43, v53
	v_add_f32_e32 v36, v36, v64
	v_add_f32_e32 v38, v38, v65
	v_add_f32_e32 v50, v32, v66
	v_add_f32_e32 v51, v33, v56
	v_add_f32_e32 v52, v34, v67
	v_add_f32_e32 v53, v35, v57
	v_mul_f32_e32 v34, v45, v45
	v_mul_f32_e32 v35, v47, v47
	v_cvt_pk_bf16_f32 v32, v44, v45
	v_cvt_pk_bf16_f32 v33, v46, v47
	v_mul_f32_e32 v45, v37, v37
	v_mul_f32_e32 v47, v39, v39
	v_add_f32_e32 v40, v40, v62
	v_mul_f32_e32 v54, v41, v41
	v_mul_f32_e32 v56, v51, v51
	v_fmac_f32_e32 v34, v44, v44
	v_fmac_f32_e32 v35, v46, v46
	v_fmac_f32_e32 v45, v36, v36
	v_fmac_f32_e32 v47, v38, v38
	v_add_f32_e32 v42, v42, v63
	v_mul_f32_e32 v55, v43, v43
	v_mul_f32_e32 v57, v53, v53
	v_fmac_f32_e32 v54, v40, v40
	v_fmac_f32_e32 v56, v50, v50
	v_add_f32_e32 v34, v34, v35
	v_add_f32_e32 v35, v45, v47
	v_fmac_f32_e32 v55, v42, v42
	v_fmac_f32_e32 v57, v52, v52
	v_add_f32_e32 v34, v54, v34
	v_add_f32_e32 v35, v56, v35
	v_add_f32_e32 v34, v55, v34
	v_add_f32_e32 v35, v57, v35
	v_add_f32_e32 v44, v34, v35
	ds_bpermute_b32 v45, v153, v44
	v_cvt_pk_bf16_f32 v34, v40, v41
	v_cvt_pk_bf16_f32 v35, v42, v43
	global_store_dwordx4 v[58:59], v[32:35], off
	s_waitcnt lgkmcnt(0)
	s_nop 0
	v_add_f32_e32 v32, v44, v45
	ds_bpermute_b32 v33, v152, v32
	v_cvt_pk_bf16_f32 v34, v36, v37
	v_cvt_pk_bf16_f32 v35, v38, v39
	v_cvt_pk_bf16_f32 v36, v50, v51
	v_cvt_pk_bf16_f32 v37, v52, v53
	global_store_dwordx4 v[58:59], v[34:37], off offset:256
	s_and_saveexec_b64 s[30:31], vcc
	s_cbranch_execz .LBB0_675
	s_waitcnt lgkmcnt(0)
	v_add_f32_e32 v34, v32, v33
	v_lshlrev_b64 v[32:33], 7, v[48:49]
	v_lshl_add_u64 v[32:33], s[14:15], 0, v[32:33]
	v_lshl_add_u64 v[32:33], s[28:29], 2, v[32:33]
	s_lshl_b32 s10, s72, 2
	v_lshl_add_u64 v[32:33], v[32:33], 0, s[10:11]
	global_store_dword v[32:33], v34, off
; __device__ __forceinline__ unsigned cvt_pk_bf16(float lo, float hi) { unsigned r; asm volatile("v_cvt_pk_bf16_f32 %0, %1, %2" : "=v"(r) : "v"(lo), "v"(hi)); return r; }
; __device__ __forceinline__ float shx(float v, int mask, int lane) { return __int_as_float(__builtin_amdgcn_ds_bpermute((lane ^ mask) << 2, __float_as_int(v))); }
; __device__ __forceinline__ float bf_lo(unsigned w) { return __uint_as_float(w << 16); }
; __device__ __forceinline__ float bf_hi(unsigned w) { return __uint_as_float(w & 0xffff0000u); }
;     __device__ __forceinline__ void operator()(const f32x4 (&acc)[2][2][4][2], const Unit& u, int wr, int wc, int fr, int fq) const {
;     ...
;             for (int m = 0; m < 4; ++m) { const int row = row0 + ai * HALF + m * 16; bf16_t* bp = HB + (size_t)row * 2048 + col0; float s = 0.f;
;                 u32x4 hv[2];
; #pragma unroll
;                 for (int bj = 0; bj < 2; ++bj) hv[bj] = *(const u32x4*)(bp + bj * HALF);
; #pragma unroll
;                 for (int bj = 0; bj < 2; ++bj) { const f32x4 a0 = acc[ai][bj][m][0], a1 = acc[ai][bj][m][1]; const u32x4 x = hv[bj];
;                     const float h0 = bf_lo(x.x) + a0[0], h1 = bf_hi(x.x) + a0[1], h2 = bf_lo(x.y) + a0[2], h3 = bf_hi(x.y) + a0[3], h4 = bf_lo(x.z) + a1[0], h5 = bf_hi(x.z) + a1[1], h6 = bf_lo(x.w) + a1[2], h7 = bf_hi(x.w) + a1[3];
;                     s += (h0 * h0 + h1 * h1) + (h2 * h2 + h3 * h3) + (h4 * h4 + h5 * h5) + (h6 * h6 + h7 * h7);
;                     u32x4 w; w.x = cvt_pk_bf16(h0, h1); w.y = cvt_pk_bf16(h2, h3); w.z = cvt_pk_bf16(h4, h5); w.w = cvt_pk_bf16(h6, h7); *(u32x4*)(bp + bj * HALF) = w; }
;                 { const int ln = fr + 16 * fq; s += shx(s, 16, ln); s += shx(s, 32, ln); }
;                 if (fq == 0) ssq_out[(size_t)row * 32 + u.pn * 4 + wc] = s;
.LBB0_675:
	s_or_b64 exec, exec, s[30:31]
	v_add_u32_e32 v32, 0xa0, v146
	s_waitcnt lgkmcnt(0)
	v_ashrrev_i32_e32 v33, 31, v32
	v_lshlrev_b64 v[34:35], 12, v[32:33]
	v_lshl_add_u64 v[34:35], s[12:13], 0, v[34:35]
	v_lshl_add_u64 v[42:43], v[144:145], 1, v[34:35]
	s_nop 1
	v_mov_b32_e32 v34, v216
	v_mov_b32_e32 v35, v217
	v_mov_b32_e32 v36, v218
	v_mov_b32_e32 v37, v219
	v_mov_b32_e32 v38, v220
	v_mov_b32_e32 v39, v221
	v_mov_b32_e32 v40, v222
	v_mov_b32_e32 v41, v223
	v_lshlrev_b32_e32 v44, 16, v34
	v_and_b32_e32 v34, 0xffff0000, v34
	v_lshlrev_b32_e32 v45, 16, v35
	v_and_b32_e32 v35, 0xffff0000, v35
	v_lshlrev_b32_e32 v48, 16, v38
	v_and_b32_e32 v38, 0xffff0000, v38
	v_lshlrev_b32_e32 v49, 16, v39
	v_and_b32_e32 v39, 0xffff0000, v39
	v_lshlrev_b32_e32 v46, 16, v36
	v_and_b32_e32 v36, 0xffff0000, v36
	v_lshlrev_b32_e32 v47, 16, v37
	v_and_b32_e32 v37, 0xffff0000, v37
	v_lshlrev_b32_e32 v50, 16, v40
	v_and_b32_e32 v40, 0xffff0000, v40
	v_lshlrev_b32_e32 v51, 16, v41
	v_and_b32_e32 v41, 0xffff0000, v41
	v_add_f32_e32 v29, v29, v34
	v_add_f32_e32 v31, v31, v35
	v_add_f32_e32 v21, v21, v38
	v_add_f32_e32 v23, v23, v39
	v_add_f32_e32 v28, v28, v44
	v_add_f32_e32 v30, v30, v45
	v_add_f32_e32 v25, v25, v36
	v_add_f32_e32 v27, v27, v37
	v_add_f32_e32 v20, v20, v48
	v_add_f32_e32 v22, v22, v49
	v_add_f32_e32 v34, v16, v50
	v_add_f32_e32 v35, v17, v40
	v_add_f32_e32 v36, v18, v51
	v_add_f32_e32 v37, v19, v41
	v_mul_f32_e32 v18, v29, v29
	v_mul_f32_e32 v19, v31, v31
	v_cvt_pk_bf16_f32 v16, v28, v29
	v_cvt_pk_bf16_f32 v17, v30, v31
	v_mul_f32_e32 v29, v21, v21
	v_mul_f32_e32 v31, v23, v23
	v_add_f32_e32 v24, v24, v46
	v_mul_f32_e32 v38, v25, v25
	v_mul_f32_e32 v40, v35, v35
	v_fmac_f32_e32 v18, v28, v28
	v_fmac_f32_e32 v19, v30, v30
	v_fmac_f32_e32 v29, v20, v20
	v_fmac_f32_e32 v31, v22, v22
	v_add_f32_e32 v26, v26, v47
	v_mul_f32_e32 v39, v27, v27
	v_mul_f32_e32 v41, v37, v37
	v_fmac_f32_e32 v38, v24, v24
	v_fmac_f32_e32 v40, v34, v34
	v_add_f32_e32 v18, v18, v19
	v_add_f32_e32 v19, v29, v31
	v_fmac_f32_e32 v39, v26, v26
	v_fmac_f32_e32 v41, v36, v36
	v_add_f32_e32 v18, v38, v18
	v_add_f32_e32 v19, v40, v19
	v_add_f32_e32 v18, v39, v18
	v_add_f32_e32 v19, v41, v19
	v_add_f32_e32 v28, v18, v19
	ds_bpermute_b32 v29, v153, v28
	v_cvt_pk_bf16_f32 v18, v24, v25
	v_cvt_pk_bf16_f32 v19, v26, v27
	global_store_dwordx4 v[42:43], v[16:19], off
	s_waitcnt lgkmcnt(0)
	s_nop 0
	v_add_f32_e32 v16, v28, v29
	ds_bpermute_b32 v17, v152, v16
	v_cvt_pk_bf16_f32 v18, v20, v21
	v_cvt_pk_bf16_f32 v19, v22, v23
	v_cvt_pk_bf16_f32 v20, v34, v35
	v_cvt_pk_bf16_f32 v21, v36, v37
	global_store_dwordx4 v[42:43], v[18:21], off offset:256
	s_and_saveexec_b64 s[30:31], vcc
	s_cbranch_execz .LBB0_677
	s_waitcnt lgkmcnt(0)
	v_add_f32_e32 v18, v16, v17
	v_lshlrev_b64 v[16:17], 7, v[32:33]
	v_lshl_add_u64 v[16:17], s[14:15], 0, v[16:17]
	v_lshl_add_u64 v[16:17], s[28:29], 2, v[16:17]
	s_lshl_b32 s10, s72, 2
	v_lshl_add_u64 v[16:17], v[16:17], 0, s[10:11]
	global_store_dword v[16:17], v18, off
.LBB0_677:
	s_or_b64 exec, exec, s[30:31]
	v_add_u32_e32 v16, 0xb0, v146
	s_waitcnt lgkmcnt(0)
	v_ashrrev_i32_e32 v17, 31, v16
	v_lshlrev_b64 v[18:19], 12, v[16:17]
	v_lshl_add_u64 v[18:19], s[12:13], 0, v[18:19]
	v_lshl_add_u64 v[26:27], v[144:145], 1, v[18:19]
	s_nop 1
	v_mov_b32_e32 v18, v224
	v_mov_b32_e32 v19, v225
	v_mov_b32_e32 v20, v226
	v_mov_b32_e32 v21, v227
	v_mov_b32_e32 v22, v228
	v_mov_b32_e32 v23, v229
	v_mov_b32_e32 v24, v230
	v_mov_b32_e32 v25, v231
	v_lshlrev_b32_e32 v28, 16, v18
	v_and_b32_e32 v18, 0xffff0000, v18
	v_lshlrev_b32_e32 v29, 16, v19
	v_and_b32_e32 v19, 0xffff0000, v19
	v_lshlrev_b32_e32 v32, 16, v22
	v_and_b32_e32 v22, 0xffff0000, v22
	v_lshlrev_b32_e32 v33, 16, v23
	v_and_b32_e32 v23, 0xffff0000, v23
	v_lshlrev_b32_e32 v30, 16, v20
	v_and_b32_e32 v20, 0xffff0000, v20
	v_lshlrev_b32_e32 v31, 16, v21
	v_and_b32_e32 v21, 0xffff0000, v21
	v_lshlrev_b32_e32 v34, 16, v24
	v_and_b32_e32 v24, 0xffff0000, v24
	v_lshlrev_b32_e32 v35, 16, v25
	v_and_b32_e32 v25, 0xffff0000, v25
	v_add_f32_e32 v13, v13, v18
	v_add_f32_e32 v15, v15, v19
	v_add_f32_e32 v5, v5, v22
	v_add_f32_e32 v7, v7, v23
	v_add_f32_e32 v12, v12, v28
	v_add_f32_e32 v14, v14, v29
	v_add_f32_e32 v9, v9, v20
	v_add_f32_e32 v11, v11, v21
	v_add_f32_e32 v4, v4, v32
	v_add_f32_e32 v6, v6, v33
	v_add_f32_e32 v18, v0, v34
	v_add_f32_e32 v19, v1, v24
	v_add_f32_e32 v20, v2, v35
	v_add_f32_e32 v21, v3, v25
	v_mul_f32_e32 v2, v13, v13
	v_mul_f32_e32 v3, v15, v15
	v_cvt_pk_bf16_f32 v0, v12, v13
	v_cvt_pk_bf16_f32 v1, v14, v15
	v_mul_f32_e32 v13, v5, v5
	v_mul_f32_e32 v15, v7, v7
	v_add_f32_e32 v8, v8, v30
	v_mul_f32_e32 v22, v9, v9
	v_mul_f32_e32 v24, v19, v19
	v_fmac_f32_e32 v2, v12, v12
	v_fmac_f32_e32 v3, v14, v14
	v_fmac_f32_e32 v13, v4, v4
	v_fmac_f32_e32 v15, v6, v6
	v_add_f32_e32 v10, v10, v31
	v_mul_f32_e32 v23, v11, v11
	v_mul_f32_e32 v25, v21, v21
	v_fmac_f32_e32 v22, v8, v8
	v_fmac_f32_e32 v24, v18, v18
	v_add_f32_e32 v2, v2, v3
	v_add_f32_e32 v3, v13, v15
	v_fmac_f32_e32 v23, v10, v10
	v_fmac_f32_e32 v25, v20, v20
	v_add_f32_e32 v2, v22, v2
	v_add_f32_e32 v3, v24, v3
	v_add_f32_e32 v2, v23, v2
	v_add_f32_e32 v3, v25, v3
	v_add_f32_e32 v12, v2, v3
	ds_bpermute_b32 v13, v153, v12
	v_cvt_pk_bf16_f32 v2, v8, v9
	v_cvt_pk_bf16_f32 v3, v10, v11
	global_store_dwordx4 v[26:27], v[0:3], off
	s_waitcnt lgkmcnt(0)
	s_nop 0
	v_add_f32_e32 v0, v12, v13
	ds_bpermute_b32 v1, v152, v0
	v_cvt_pk_bf16_f32 v2, v4, v5
	v_cvt_pk_bf16_f32 v3, v6, v7
	v_cvt_pk_bf16_f32 v4, v18, v19
	v_cvt_pk_bf16_f32 v5, v20, v21
	global_store_dwordx4 v[26:27], v[2:5], off offset:256
	s_and_saveexec_b64 s[30:31], vcc
	s_cbranch_execz .LBB0_679
	s_waitcnt lgkmcnt(0)
	v_add_f32_e32 v2, v0, v1
	v_lshlrev_b64 v[0:1], 7, v[16:17]
	v_lshl_add_u64 v[0:1], s[14:15], 0, v[0:1]
	v_lshl_add_u64 v[0:1], s[28:29], 2, v[0:1]
	s_lshl_b32 s10, s72, 2
	v_lshl_add_u64 v[0:1], v[0:1], 0, s[10:11]
	global_store_dword v[0:1], v2, off

; #define PG8_STAGE(bufoff, gbase, voff) do { _Pragma("unroll") for (int _i = 0; _i < 2; ++_i) \
;         __builtin_amdgcn_global_load_lds((const unsigned*)((const char*)(gbase) + (voff)[_i]), (PG8_LAS unsigned*)(lds + (bufoff) + ldsw + _i * 8192), 16, 0, 0); } while (0)
; #define PG8_LDA(dst, b, h) do { _Pragma("unroll") for (int m = 0; m < 4; ++m) _Pragma("unroll") for (int k = 0; k < 2; ++k) dst[m][k] = *(const PG8_LAS bf16x8*)(lds + PG8_SA(b, h) + aoff + m * 2048 + k * 1024); } while (0)
; #define PG8_LDB(dst, b, h) do { _Pragma("unroll") for (int n = 0; n < 2; ++n) _Pragma("unroll") for (int k = 0; k < 2; ++k) dst[n][k] = *(const PG8_LAS bf16x8*)(lds + PG8_SB(b, h) + boff + n * 2048 + k * 1024); } while (0)
; #define PG8_MMA(ai, bj, At, Bt) do { __builtin_amdgcn_s_setprio(1); _Pragma("unroll") for (int m = 0; m < 4; ++m) _Pragma("unroll") for (int n = 0; n < 2; ++n) _Pragma("unroll") for (int k = 0; k < 2; ++k) \
;         acc[ai][bj][m][n] = __builtin_amdgcn_mfma_f32_16x16x32_bf16(Bt[n][k], At[m][k], acc[ai][bj][m][n], 0, 0, 0); __builtin_amdgcn_s_setprio(0); } while (0)
; #define PG8_WAIT_V(n) asm volatile("s_waitcnt vmcnt(" #n ")" ::: "memory")
; #define PG8_WAIT_L(n) asm volatile("s_waitcnt lgkmcnt(" #n ")" ::: "memory")
; #define PG8_BAR __builtin_amdgcn_s_barrier()
; #define PG8_SCHED __builtin_amdgcn_sched_barrier(0)
; template <class Epi, class Sched, bool ALIGN_EPI = false, bool SP2 = false>
; __device__ __forceinline__ void gemm_phase(PG8_LAS unsigned char* lds, const Gemm g, const Sched& S, const Epi& E) {
;     ...
;             PG8_LDB(B0, 0, 0); PG8_LDB(B1, 0, 1); PG8_SCHED; PG8_LDA(At, 0, 0); PG8_STAGE(PG8_SA(1, 1), a1 + hstepA, voffA);
;             PG8_WAIT_V(8); PG8_WAIT_L(0); PG8_BAR; PG8_MMA(0, 0, At, B0); PG8_MMA(0, 1, At, B1); PG8_BAR; PG8_SCHED;
;     ...
; #pragma unroll
;         for (int a = 0; a < 2; ++a)
; #pragma unroll
;             for (int b = 0; b < 2; ++b)
; #pragma unroll
;                 for (int m = 0; m < 4; ++m)
; #pragma unroll
;                     for (int n = 0; n < 2; ++n) acc[a][b][m][n] = (f32x4){0.f, 0.f, 0.f, 0.f};
;         cur = nxt; cA = nA; cB = nB; ++ui;
.LBB0_809:
	s_add_u32 s54, s26, 0x100
	v_mov_b32_e32 v0, 0
	s_addc_u32 s55, s27, 0
	s_mov_b32 s56, -2
	s_waitcnt lgkmcnt(0)
	v_mov_b32_e32 v1, v0
	v_mov_b32_e32 v2, v0
	v_mov_b32_e32 v3, v0
	v_mov_b32_e32 v4, v0
	v_mov_b32_e32 v5, v0
	v_mov_b32_e32 v6, v0
	v_mov_b32_e32 v7, v0
	v_mov_b32_e32 v16, v0
	v_mov_b32_e32 v17, v0
	v_mov_b32_e32 v18, v0
	v_mov_b32_e32 v19, v0
	v_mov_b32_e32 v20, v0
	v_mov_b32_e32 v21, v0
	v_mov_b32_e32 v22, v0
	v_mov_b32_e32 v23, v0
	v_mov_b32_e32 v32, v0
	v_mov_b32_e32 v33, v0
	v_mov_b32_e32 v34, v0
	v_mov_b32_e32 v35, v0
	v_mov_b32_e32 v36, v0
	v_mov_b32_e32 v37, v0
	v_mov_b32_e32 v38, v0
	v_mov_b32_e32 v39, v0
	v_mov_b32_e32 v48, v0
	v_mov_b32_e32 v49, v0
	v_mov_b32_e32 v50, v0
	v_mov_b32_e32 v51, v0
	v_mov_b32_e32 v52, v0
	v_mov_b32_e32 v53, v0
	v_mov_b32_e32 v54, v0
	v_mov_b32_e32 v55, v0
	v_mov_b32_e32 v8, v0
	v_mov_b32_e32 v9, v0
	v_mov_b32_e32 v10, v0
	v_mov_b32_e32 v11, v0
	v_mov_b32_e32 v12, v0
	v_mov_b32_e32 v13, v0
	v_mov_b32_e32 v14, v0
	v_mov_b32_e32 v15, v0
	v_mov_b32_e32 v24, v0
	v_mov_b32_e32 v25, v0
	v_mov_b32_e32 v26, v0
	v_mov_b32_e32 v27, v0
	v_mov_b32_e32 v28, v0
	v_mov_b32_e32 v29, v0
	v_mov_b32_e32 v30, v0
	v_mov_b32_e32 v31, v0
	v_mov_b32_e32 v40, v0
	v_mov_b32_e32 v41, v0
	v_mov_b32_e32 v42, v0
	v_mov_b32_e32 v43, v0
	v_mov_b32_e32 v44, v0
	v_mov_b32_e32 v45, v0
	v_mov_b32_e32 v46, v0
	v_mov_b32_e32 v47, v0
	v_mov_b32_e32 v56, v0
	v_mov_b32_e32 v57, v0
	v_mov_b32_e32 v58, v0
	v_mov_b32_e32 v59, v0
	v_mov_b32_e32 v60, v0
	v_mov_b32_e32 v61, v0
	v_mov_b32_e32 v62, v0
	v_mov_b32_e32 v63, v0
	v_mov_b32_e32 v64, v0
	v_mov_b32_e32 v65, v0
	v_mov_b32_e32 v66, v0
	v_mov_b32_e32 v67, v0
	v_mov_b32_e32 v68, v0
	v_mov_b32_e32 v69, v0
	v_mov_b32_e32 v70, v0
	v_mov_b32_e32 v71, v0
	v_mov_b32_e32 v80, v0
	v_mov_b32_e32 v81, v0
	v_mov_b32_e32 v82, v0
	v_mov_b32_e32 v83, v0
	v_mov_b32_e32 v84, v0
	v_mov_b32_e32 v85, v0
	v_mov_b32_e32 v86, v0
	v_mov_b32_e32 v87, v0
	v_mov_b32_e32 v96, v0
	v_mov_b32_e32 v97, v0
	v_mov_b32_e32 v98, v0
	v_mov_b32_e32 v99, v0
	v_mov_b32_e32 v100, v0
	v_mov_b32_e32 v101, v0
	v_mov_b32_e32 v102, v0
	v_mov_b32_e32 v103, v0
	v_mov_b32_e32 v112, v0
	v_mov_b32_e32 v113, v0
	v_mov_b32_e32 v114, v0
	v_mov_b32_e32 v115, v0
	v_mov_b32_e32 v116, v0
	v_mov_b32_e32 v117, v0
	v_mov_b32_e32 v118, v0
	v_mov_b32_e32 v119, v0
	v_mov_b32_e32 v72, v0
	v_mov_b32_e32 v73, v0
	v_mov_b32_e32 v74, v0
	v_mov_b32_e32 v75, v0
	v_mov_b32_e32 v76, v0
	v_mov_b32_e32 v77, v0
	v_mov_b32_e32 v78, v0
	v_mov_b32_e32 v79, v0
	v_mov_b32_e32 v88, v0
	v_mov_b32_e32 v89, v0
	v_mov_b32_e32 v90, v0
	v_mov_b32_e32 v91, v0
	v_mov_b32_e32 v92, v0
	v_mov_b32_e32 v93, v0
	v_mov_b32_e32 v94, v0
	v_mov_b32_e32 v95, v0
	v_mov_b32_e32 v104, v0
	v_mov_b32_e32 v105, v0
	v_mov_b32_e32 v106, v0
	v_mov_b32_e32 v107, v0
	v_mov_b32_e32 v108, v0
	v_mov_b32_e32 v109, v0
	v_mov_b32_e32 v110, v0
	v_mov_b32_e32 v111, v0
	v_mov_b32_e32 v120, v0
	v_mov_b32_e32 v121, v0
	v_mov_b32_e32 v122, v0
	v_mov_b32_e32 v123, v0
	v_mov_b32_e32 v124, v0
	v_mov_b32_e32 v125, v0
	v_mov_b32_e32 v126, v0
	v_mov_b32_e32 v127, v0
.LBB0_810:
	ds_read_b128 v[144:147], v149
	ds_read_b128 v[152:155], v149 offset:1024
	ds_read_b128 v[156:159], v149 offset:2048
	ds_read_b128 v[160:163], v149 offset:3072
	ds_read_b128 v[168:171], v150
	ds_read_b128 v[172:175], v150 offset:1024
	ds_read_b128 v[176:179], v150 offset:2048
	ds_read_b128 v[180:183], v150 offset:3072
	s_add_u32 s26, s22, 0x100
	s_addc_u32 s27, s23, 0
	s_cmpk_eq_i32 s56, 0x54
	s_cselect_b32 s31, s11, s27
	s_cselect_b32 s30, s10, s26
	s_cselect_b32 s29, s21, s55
	s_cselect_b32 s28, s20, s54
	v_lshl_add_u64 v[164:165], s[22:23], 0, v[136:137]
	s_add_i32 m0, s25, 0xc000
	ds_read_b128 v[184:187], v151
	ds_read_b128 v[188:191], v151 offset:1024
	ds_read_b128 v[192:195], v151 offset:2048
	ds_read_b128 v[196:199], v151 offset:3072
	ds_read_b128 v[200:203], v151 offset:4096
	ds_read_b128 v[204:207], v151 offset:5120
	ds_read_b128 v[208:211], v151 offset:6144
	ds_read_b128 v[212:215], v151 offset:7168
	global_load_lds_dwordx4 v[164:165], off
	v_lshl_add_u64 v[164:165], s[22:23], 0, v[138:139]
	s_add_i32 m0, s25, 0xe000
	s_nop 0
	global_load_lds_dwordx4 v[164:165], off
	s_waitcnt vmcnt(8)
	s_waitcnt lgkmcnt(0)
	s_barrier
	s_setprio 1
	s_waitcnt lgkmcnt(0)
	v_mfma_f32_16x16x32_bf16 v[124:127], v[144:147], v[184:187], v[124:127]
	v_mfma_f32_16x16x32_bf16 v[120:123], v[156:159], v[184:187], v[120:123]
	v_mfma_f32_16x16x32_bf16 v[108:111], v[144:147], v[192:195], v[108:111]
	v_mfma_f32_16x16x32_bf16 v[104:107], v[156:159], v[192:195], v[104:107]
	v_mfma_f32_16x16x32_bf16 v[92:95], v[144:147], v[200:203], v[92:95]
	v_mfma_f32_16x16x32_bf16 v[88:91], v[156:159], v[200:203], v[88:91]
	v_mfma_f32_16x16x32_bf16 v[76:79], v[144:147], v[208:211], v[76:79]
	v_mfma_f32_16x16x32_bf16 v[72:75], v[156:159], v[208:211], v[72:75]
	v_mfma_f32_16x16x32_bf16 v[124:127], v[152:155], v[188:191], v[124:127]
	v_mfma_f32_16x16x32_bf16 v[120:123], v[160:163], v[188:191], v[120:123]
	v_mfma_f32_16x16x32_bf16 v[108:111], v[152:155], v[196:199], v[108:111]
	v_mfma_f32_16x16x32_bf16 v[104:107], v[160:163], v[196:199], v[104:107]
	v_mfma_f32_16x16x32_bf16 v[92:95], v[152:155], v[204:207], v[92:95]
	v_mfma_f32_16x16x32_bf16 v[88:91], v[160:163], v[204:207], v[88:91]
	v_mfma_f32_16x16x32_bf16 v[76:79], v[152:155], v[212:215], v[76:79]
	v_mfma_f32_16x16x32_bf16 v[72:75], v[160:163], v[212:215], v[72:75]
	s_setprio 0
	s_setprio 1
	v_mfma_f32_16x16x32_bf16 v[116:119], v[168:171], v[184:187], v[116:119]
	v_mfma_f32_16x16x32_bf16 v[112:115], v[176:179], v[184:187], v[112:115]
	v_mfma_f32_16x16x32_bf16 v[100:103], v[168:171], v[192:195], v[100:103]
	v_mfma_f32_16x16x32_bf16 v[96:99], v[176:179], v[192:195], v[96:99]
	v_mfma_f32_16x16x32_bf16 v[84:87], v[168:171], v[200:203], v[84:87]
	v_mfma_f32_16x16x32_bf16 v[80:83], v[176:179], v[200:203], v[80:83]
	v_mfma_f32_16x16x32_bf16 v[68:71], v[168:171], v[208:211], v[68:71]
	v_mfma_f32_16x16x32_bf16 v[64:67], v[176:179], v[208:211], v[64:67]
	v_mfma_f32_16x16x32_bf16 v[116:119], v[172:175], v[188:191], v[116:119]
	v_mfma_f32_16x16x32_bf16 v[112:115], v[180:183], v[188:191], v[112:115]
	v_mfma_f32_16x16x32_bf16 v[100:103], v[172:175], v[196:199], v[100:103]
	v_mfma_f32_16x16x32_bf16 v[96:99], v[180:183], v[196:199], v[96:99]
	v_mfma_f32_16x16x32_bf16 v[84:87], v[172:175], v[204:207], v[84:87]
	v_mfma_f32_16x16x32_bf16 v[80:83], v[180:183], v[204:207], v[80:83]
	v_mfma_f32_16x16x32_bf16 v[68:71], v[172:175], v[212:215], v[68:71]
	v_mfma_f32_16x16x32_bf16 v[64:67], v[180:183], v[212:215], v[64:67]
	s_setprio 0
	s_barrier
; #define PG8_STAGE(bufoff, gbase, voff) do { _Pragma("unroll") for (int _i = 0; _i < 2; ++_i) \
;         __builtin_amdgcn_global_load_lds((const unsigned*)((const char*)(gbase) + (voff)[_i]), (PG8_LAS unsigned*)(lds + (bufoff) + ldsw + _i * 8192), 16, 0, 0); } while (0)
; #define PG8_LDA(dst, b, h) do { _Pragma("unroll") for (int m = 0; m < 4; ++m) _Pragma("unroll") for (int k = 0; k < 2; ++k) dst[m][k] = *(const PG8_LAS bf16x8*)(lds + PG8_SA(b, h) + aoff + m * 2048 + k * 1024); } while (0)
; #define PG8_LDB(dst, b, h) do { _Pragma("unroll") for (int n = 0; n < 2; ++n) _Pragma("unroll") for (int k = 0; k < 2; ++k) dst[n][k] = *(const PG8_LAS bf16x8*)(lds + PG8_SB(b, h) + boff + n * 2048 + k * 1024); } while (0)
; #define PG8_MMA(ai, bj, At, Bt) do { __builtin_amdgcn_s_setprio(1); _Pragma("unroll") for (int m = 0; m < 4; ++m) _Pragma("unroll") for (int n = 0; n < 2; ++n) _Pragma("unroll") for (int k = 0; k < 2; ++k) \
;         acc[ai][bj][m][n] = __builtin_amdgcn_mfma_f32_16x16x32_bf16(Bt[n][k], At[m][k], acc[ai][bj][m][n], 0, 0, 0); __builtin_amdgcn_s_setprio(0); } while (0)
; #define PG8_WAIT_V(n) asm volatile("s_waitcnt vmcnt(" #n ")" ::: "memory")
; #define PG8_WAIT_L(n) asm volatile("s_waitcnt lgkmcnt(" #n ")" ::: "memory")
; #define PG8_BAR __builtin_amdgcn_s_barrier()
; #define PG8_SCHED __builtin_amdgcn_sched_barrier(0)
; template <class Epi, class Sched, bool ALIGN_EPI = false, bool SP2 = false>
; __device__ __forceinline__ void gemm_phase(PG8_LAS unsigned char* lds, const Gemm g, const Sched& S, const Epi& E) {
;     ...
;             PG8_LDA(At, 0, 1); PG8_STAGE(PG8_SB(0, 0), b2, voffB); PG8_STAGE(PG8_SB(0, 1), b2 + hstepB, voffB); PG8_STAGE(PG8_SA(0, 0), a2, voffA);
;             PG8_WAIT_V(8); PG8_WAIT_L(0); PG8_BAR; PG8_MMA(1, 0, At, B0); PG8_MMA(1, 1, At, B1); PG8_BAR; PG8_SCHED;
;             PG8_LDB(B0, 1, 0); PG8_LDB(B1, 1, 1); PG8_SCHED; PG8_LDA(At, 1, 0); PG8_STAGE(PG8_SA(0, 1), a2 + hstepA, voffA);
;             PG8_WAIT_V(8); PG8_WAIT_L(0); PG8_BAR; PG8_MMA(0, 0, At, B0); PG8_MMA(0, 1, At, B1); PG8_BAR; PG8_SCHED;
	s_add_i32 s4, s38, s47
	v_lshl_add_u64 v[164:165], s[28:29], 0, v[130:131]
	s_mov_b32 m0, s4
	ds_read_b128 v[184:187], v151 offset:16384
	ds_read_b128 v[188:191], v151 offset:17408
	ds_read_b128 v[192:195], v151 offset:18432
	ds_read_b128 v[196:199], v151 offset:19456
	ds_read_b128 v[200:203], v151 offset:20480
	ds_read_b128 v[204:207], v151 offset:21504
	ds_read_b128 v[208:211], v151 offset:22528
	ds_read_b128 v[212:215], v151 offset:23552
	global_load_lds_dwordx4 v[164:165], off
	s_add_i32 m0, s4, 0x2000
	s_add_u32 s4, s28, 0x160000
	v_lshl_add_u64 v[216:217], s[28:29], 0, v[134:135]
	s_addc_u32 s5, s29, 0
	s_add_i32 s22, s39, s47
	global_load_lds_dwordx4 v[216:217], off
	v_lshl_add_u64 v[218:219], s[4:5], 0, v[130:131]
	s_mov_b32 m0, s22
	v_lshl_add_u64 v[220:221], s[30:31], 0, v[132:133]
	global_load_lds_dwordx4 v[218:219], off
	v_lshl_add_u64 v[218:219], s[4:5], 0, v[134:135]
	s_add_i32 m0, s22, 0x2000
	s_nop 0
	global_load_lds_dwordx4 v[218:219], off
	v_lshl_add_u64 v[218:219], s[30:31], 0, v[128:129]
	s_mov_b32 m0, s25
	s_nop 0
	global_load_lds_dwordx4 v[218:219], off
	s_mov_b32 m0, s33
	s_nop 0
	global_load_lds_dwordx4 v[220:221], off
	s_waitcnt vmcnt(8)
	s_waitcnt lgkmcnt(0)
	s_barrier
	s_setprio 1
	s_waitcnt lgkmcnt(0)
	v_mfma_f32_16x16x32_bf16 v[60:63], v[144:147], v[184:187], v[60:63]
	v_mfma_f32_16x16x32_bf16 v[56:59], v[156:159], v[184:187], v[56:59]
	v_mfma_f32_16x16x32_bf16 v[44:47], v[144:147], v[192:195], v[44:47]
	v_mfma_f32_16x16x32_bf16 v[40:43], v[156:159], v[192:195], v[40:43]
	v_mfma_f32_16x16x32_bf16 v[28:31], v[144:147], v[200:203], v[28:31]
	v_mfma_f32_16x16x32_bf16 v[24:27], v[156:159], v[200:203], v[24:27]
	v_mfma_f32_16x16x32_bf16 v[12:15], v[144:147], v[208:211], v[12:15]
	v_mfma_f32_16x16x32_bf16 v[8:11], v[156:159], v[208:211], v[8:11]
	v_mfma_f32_16x16x32_bf16 v[60:63], v[152:155], v[188:191], v[60:63]
	v_mfma_f32_16x16x32_bf16 v[56:59], v[160:163], v[188:191], v[56:59]
	v_mfma_f32_16x16x32_bf16 v[44:47], v[152:155], v[196:199], v[44:47]
	v_mfma_f32_16x16x32_bf16 v[40:43], v[160:163], v[196:199], v[40:43]
	v_mfma_f32_16x16x32_bf16 v[28:31], v[152:155], v[204:207], v[28:31]
	v_mfma_f32_16x16x32_bf16 v[24:27], v[160:163], v[204:207], v[24:27]
	v_mfma_f32_16x16x32_bf16 v[12:15], v[152:155], v[212:215], v[12:15]
	v_mfma_f32_16x16x32_bf16 v[8:11], v[160:163], v[212:215], v[8:11]
	s_setprio 0
	s_setprio 1
	v_mfma_f32_16x16x32_bf16 v[52:55], v[168:171], v[184:187], v[52:55]
	v_mfma_f32_16x16x32_bf16 v[48:51], v[176:179], v[184:187], v[48:51]
	v_mfma_f32_16x16x32_bf16 v[36:39], v[168:171], v[192:195], v[36:39]
	v_mfma_f32_16x16x32_bf16 v[32:35], v[176:179], v[192:195], v[32:35]
	v_mfma_f32_16x16x32_bf16 v[20:23], v[168:171], v[200:203], v[20:23]
	v_mfma_f32_16x16x32_bf16 v[16:19], v[176:179], v[200:203], v[16:19]
	v_mfma_f32_16x16x32_bf16 v[4:7], v[168:171], v[208:211], v[4:7]
	v_mfma_f32_16x16x32_bf16 v[0:3], v[176:179], v[208:211], v[0:3]
	v_mfma_f32_16x16x32_bf16 v[52:55], v[172:175], v[188:191], v[52:55]
	v_mfma_f32_16x16x32_bf16 v[48:51], v[180:183], v[188:191], v[48:51]
	v_mfma_f32_16x16x32_bf16 v[36:39], v[172:175], v[196:199], v[36:39]
	v_mfma_f32_16x16x32_bf16 v[32:35], v[180:183], v[196:199], v[32:35]
	v_mfma_f32_16x16x32_bf16 v[20:23], v[172:175], v[204:207], v[20:23]
	v_mfma_f32_16x16x32_bf16 v[16:19], v[180:183], v[204:207], v[16:19]
	v_mfma_f32_16x16x32_bf16 v[4:7], v[172:175], v[212:215], v[4:7]
	v_mfma_f32_16x16x32_bf16 v[0:3], v[180:183], v[212:215], v[0:3]
	s_setprio 0
	s_barrier
	s_add_i32 s22, 0, 0x18000
	s_add_i32 s23, 0, 0x1c000
	v_add_u32_e32 v160, s22, v148
	v_add_u32_e32 v166, s23, v148
	ds_read_b128 v[144:147], v160
	ds_read_b128 v[152:155], v160 offset:1024
	ds_read_b128 v[156:159], v160 offset:2048
	ds_read_b128 v[160:163], v160 offset:3072
	ds_read_b128 v[168:171], v166
	ds_read_b128 v[172:175], v166 offset:1024
	ds_read_b128 v[176:179], v166 offset:2048
	ds_read_b128 v[180:183], v166 offset:3072
	s_add_u32 s4, s30, 0x160000
	s_addc_u32 s5, s31, 0
	s_mov_b32 m0, s34
	v_lshl_add_u64 v[222:223], s[4:5], 0, v[128:129]
	ds_read_b128 v[184:187], v151 offset:32768
	ds_read_b128 v[188:191], v151 offset:33792
	ds_read_b128 v[192:195], v151 offset:34816
	ds_read_b128 v[196:199], v151 offset:35840
	ds_read_b128 v[200:203], v151 offset:36864
	ds_read_b128 v[204:207], v151 offset:37888
	ds_read_b128 v[208:211], v151 offset:38912
	ds_read_b128 v[212:215], v151 offset:39936
	global_load_lds_dwordx4 v[222:223], off
	v_lshl_add_u64 v[222:223], s[4:5], 0, v[132:133]
	s_mov_b32 m0, s35
	s_nop 0
	global_load_lds_dwordx4 v[222:223], off
	s_waitcnt vmcnt(8)
	s_waitcnt lgkmcnt(0)
	s_barrier
; #define PG8_STAGE(bufoff, gbase, voff) do { _Pragma("unroll") for (int _i = 0; _i < 2; ++_i) \
;         __builtin_amdgcn_global_load_lds((const unsigned*)((const char*)(gbase) + (voff)[_i]), (PG8_LAS unsigned*)(lds + (bufoff) + ldsw + _i * 8192), 16, 0, 0); } while (0)
; #define PG8_LDA(dst, b, h) do { _Pragma("unroll") for (int m = 0; m < 4; ++m) _Pragma("unroll") for (int k = 0; k < 2; ++k) dst[m][k] = *(const PG8_LAS bf16x8*)(lds + PG8_SA(b, h) + aoff + m * 2048 + k * 1024); } while (0)
; #define PG8_MMA(ai, bj, At, Bt) do { __builtin_amdgcn_s_setprio(1); _Pragma("unroll") for (int m = 0; m < 4; ++m) _Pragma("unroll") for (int n = 0; n < 2; ++n) _Pragma("unroll") for (int k = 0; k < 2; ++k) \
;         acc[ai][bj][m][n] = __builtin_amdgcn_mfma_f32_16x16x32_bf16(Bt[n][k], At[m][k], acc[ai][bj][m][n], 0, 0, 0); __builtin_amdgcn_s_setprio(0); } while (0)
; #define PG8_WAIT_V(n) asm volatile("s_waitcnt vmcnt(" #n ")" ::: "memory")
; #define PG8_WAIT_L(n) asm volatile("s_waitcnt lgkmcnt(" #n ")" ::: "memory")
; #define PG8_BAR __builtin_amdgcn_s_barrier()
; #define PG8_SCHED __builtin_amdgcn_sched_barrier(0)
; template <class Epi, class Sched, bool ALIGN_EPI = false, bool SP2 = false>
; __device__ __forceinline__ void gemm_phase(PG8_LAS unsigned char* lds, const Gemm g, const Sched& S, const Epi& E) {
;     ...
;             PG8_WAIT_V(8); PG8_WAIT_L(0); PG8_BAR; PG8_MMA(0, 0, At, B0); PG8_MMA(0, 1, At, B1); PG8_BAR; PG8_SCHED;
;             PG8_LDA(At, 1, 1); PG8_STAGE(PG8_SB(1, 0), b3, voffB); PG8_STAGE(PG8_SB(1, 1), b3 + hstepB, voffB); PG8_STAGE(PG8_SA(1, 0), a3, voffA);
;             PG8_WAIT_V(8); PG8_WAIT_L(0); PG8_BAR; PG8_MMA(1, 0, At, B0); PG8_MMA(1, 1, At, B1); PG8_BAR; PG8_SCHED;
	s_setprio 1
	s_waitcnt lgkmcnt(0)
	v_mfma_f32_16x16x32_bf16 v[124:127], v[144:147], v[184:187], v[124:127]
	v_mfma_f32_16x16x32_bf16 v[120:123], v[156:159], v[184:187], v[120:123]
	v_mfma_f32_16x16x32_bf16 v[108:111], v[144:147], v[192:195], v[108:111]
	v_mfma_f32_16x16x32_bf16 v[104:107], v[156:159], v[192:195], v[104:107]
	v_mfma_f32_16x16x32_bf16 v[92:95], v[144:147], v[200:203], v[92:95]
	v_mfma_f32_16x16x32_bf16 v[88:91], v[156:159], v[200:203], v[88:91]
	v_mfma_f32_16x16x32_bf16 v[76:79], v[144:147], v[208:211], v[76:79]
	v_mfma_f32_16x16x32_bf16 v[72:75], v[156:159], v[208:211], v[72:75]
	v_mfma_f32_16x16x32_bf16 v[124:127], v[152:155], v[188:191], v[124:127]
	v_mfma_f32_16x16x32_bf16 v[120:123], v[160:163], v[188:191], v[120:123]
	v_mfma_f32_16x16x32_bf16 v[108:111], v[152:155], v[196:199], v[108:111]
	v_mfma_f32_16x16x32_bf16 v[104:107], v[160:163], v[196:199], v[104:107]
	v_mfma_f32_16x16x32_bf16 v[92:95], v[152:155], v[204:207], v[92:95]
	v_mfma_f32_16x16x32_bf16 v[88:91], v[160:163], v[204:207], v[88:91]
	v_mfma_f32_16x16x32_bf16 v[76:79], v[152:155], v[212:215], v[76:79]
	v_mfma_f32_16x16x32_bf16 v[72:75], v[160:163], v[212:215], v[72:75]
	s_setprio 0
	s_setprio 1
	v_mfma_f32_16x16x32_bf16 v[116:119], v[168:171], v[184:187], v[116:119]
	v_mfma_f32_16x16x32_bf16 v[112:115], v[176:179], v[184:187], v[112:115]
	v_mfma_f32_16x16x32_bf16 v[100:103], v[168:171], v[192:195], v[100:103]
	v_mfma_f32_16x16x32_bf16 v[96:99], v[176:179], v[192:195], v[96:99]
	v_mfma_f32_16x16x32_bf16 v[84:87], v[168:171], v[200:203], v[84:87]
	v_mfma_f32_16x16x32_bf16 v[80:83], v[176:179], v[200:203], v[80:83]
	v_mfma_f32_16x16x32_bf16 v[68:71], v[168:171], v[208:211], v[68:71]
	v_mfma_f32_16x16x32_bf16 v[64:67], v[176:179], v[208:211], v[64:67]
	v_mfma_f32_16x16x32_bf16 v[116:119], v[172:175], v[188:191], v[116:119]
	v_mfma_f32_16x16x32_bf16 v[112:115], v[180:183], v[188:191], v[112:115]
	v_mfma_f32_16x16x32_bf16 v[100:103], v[172:175], v[196:199], v[100:103]
	v_mfma_f32_16x16x32_bf16 v[96:99], v[180:183], v[196:199], v[96:99]
	v_mfma_f32_16x16x32_bf16 v[84:87], v[172:175], v[204:207], v[84:87]
	v_mfma_f32_16x16x32_bf16 v[80:83], v[180:183], v[204:207], v[80:83]
	v_mfma_f32_16x16x32_bf16 v[68:71], v[172:175], v[212:215], v[68:71]
	v_mfma_f32_16x16x32_bf16 v[64:67], v[180:183], v[212:215], v[64:67]
	s_setprio 0
	s_barrier
	s_add_i32 s4, s22, s47
	v_lshl_add_u64 v[164:165], v[164:165], 0, s[18:19]
	s_mov_b32 m0, s4
	ds_read_b128 v[184:187], v151 offset:49152
	ds_read_b128 v[188:191], v151 offset:50176
	ds_read_b128 v[192:195], v151 offset:51200
	ds_read_b128 v[196:199], v151 offset:52224
	ds_read_b128 v[200:203], v151 offset:53248
	ds_read_b128 v[204:207], v151 offset:54272
	ds_read_b128 v[208:211], v151 offset:55296
	ds_read_b128 v[212:215], v151 offset:56320
	global_load_lds_dwordx4 v[164:165], off
	s_add_i32 m0, s4, 0x2000
	s_add_u32 s4, s28, 0x160080
	v_lshl_add_u64 v[164:165], v[216:217], 0, s[18:19]
	s_addc_u32 s5, s29, 0
	s_add_i32 s22, s23, s47
	global_load_lds_dwordx4 v[164:165], off
	v_lshl_add_u64 v[164:165], s[4:5], 0, v[130:131]
	s_mov_b32 m0, s22
	s_nop 0
	global_load_lds_dwordx4 v[164:165], off
	v_lshl_add_u64 v[164:165], s[4:5], 0, v[134:135]
	s_add_i32 m0, s22, 0x2000
	s_nop 0
	global_load_lds_dwordx4 v[164:165], off
	v_lshl_add_u64 v[164:165], v[218:219], 0, s[18:19]
	s_mov_b32 m0, s36
	s_nop 0
	global_load_lds_dwordx4 v[164:165], off
	v_lshl_add_u64 v[164:165], v[220:221], 0, s[18:19]
	s_mov_b32 m0, s37
	s_nop 0
	global_load_lds_dwordx4 v[164:165], off
	s_waitcnt vmcnt(8)
	s_waitcnt lgkmcnt(0)
	s_barrier
	s_setprio 1
	s_waitcnt lgkmcnt(0)
	v_mfma_f32_16x16x32_bf16 v[60:63], v[144:147], v[184:187], v[60:63]
	v_mfma_f32_16x16x32_bf16 v[56:59], v[156:159], v[184:187], v[56:59]
	v_mfma_f32_16x16x32_bf16 v[44:47], v[144:147], v[192:195], v[44:47]
	v_mfma_f32_16x16x32_bf16 v[40:43], v[156:159], v[192:195], v[40:43]
	v_mfma_f32_16x16x32_bf16 v[28:31], v[144:147], v[200:203], v[28:31]
	v_mfma_f32_16x16x32_bf16 v[24:27], v[156:159], v[200:203], v[24:27]
	v_mfma_f32_16x16x32_bf16 v[12:15], v[144:147], v[208:211], v[12:15]
	v_mfma_f32_16x16x32_bf16 v[8:11], v[156:159], v[208:211], v[8:11]
	v_mfma_f32_16x16x32_bf16 v[60:63], v[152:155], v[188:191], v[60:63]
	v_mfma_f32_16x16x32_bf16 v[56:59], v[160:163], v[188:191], v[56:59]
	v_mfma_f32_16x16x32_bf16 v[44:47], v[152:155], v[196:199], v[44:47]
	v_mfma_f32_16x16x32_bf16 v[40:43], v[160:163], v[196:199], v[40:43]
	v_mfma_f32_16x16x32_bf16 v[28:31], v[152:155], v[204:207], v[28:31]
	v_mfma_f32_16x16x32_bf16 v[24:27], v[160:163], v[204:207], v[24:27]
	v_mfma_f32_16x16x32_bf16 v[12:15], v[152:155], v[212:215], v[12:15]
	v_mfma_f32_16x16x32_bf16 v[8:11], v[160:163], v[212:215], v[8:11]
	s_setprio 0
	s_setprio 1
	v_mfma_f32_16x16x32_bf16 v[52:55], v[168:171], v[184:187], v[52:55]
	v_mfma_f32_16x16x32_bf16 v[48:51], v[176:179], v[184:187], v[48:51]
	v_mfma_f32_16x16x32_bf16 v[36:39], v[168:171], v[192:195], v[36:39]
	v_mfma_f32_16x16x32_bf16 v[32:35], v[176:179], v[192:195], v[32:35]
	v_mfma_f32_16x16x32_bf16 v[20:23], v[168:171], v[200:203], v[20:23]
	v_mfma_f32_16x16x32_bf16 v[16:19], v[176:179], v[200:203], v[16:19]
	v_mfma_f32_16x16x32_bf16 v[4:7], v[168:171], v[208:211], v[4:7]
	v_mfma_f32_16x16x32_bf16 v[0:3], v[176:179], v[208:211], v[0:3]
	v_mfma_f32_16x16x32_bf16 v[52:55], v[172:175], v[188:191], v[52:55]
	v_mfma_f32_16x16x32_bf16 v[48:51], v[180:183], v[188:191], v[48:51]
	v_mfma_f32_16x16x32_bf16 v[36:39], v[172:175], v[196:199], v[36:39]
	v_mfma_f32_16x16x32_bf16 v[32:35], v[180:183], v[196:199], v[32:35]
	v_mfma_f32_16x16x32_bf16 v[20:23], v[172:175], v[204:207], v[20:23]
	v_mfma_f32_16x16x32_bf16 v[16:19], v[180:183], v[204:207], v[16:19]
	v_mfma_f32_16x16x32_bf16 v[4:7], v[172:175], v[212:215], v[4:7]
	v_mfma_f32_16x16x32_bf16 v[0:3], v[180:183], v[212:215], v[0:3]
	s_setprio 0
	s_barrier
	s_add_i32 s56, s56, 2
	s_add_u32 s54, s54, 0x100
	s_addc_u32 s55, s55, 0
	s_cmpk_gt_u32 s56, 0x55
	s_mov_b64 s[22:23], s[26:27]
	s_cbranch_scc0 .LBB0_810
	s_and_b64 vcc, exec, s[48:49]
	s_cbranch_vccz .LBB0_813
	s_barrier
; __device__ __forceinline__ unsigned cvt_pk_bf16(float lo, float hi) { unsigned r; asm volatile("v_cvt_pk_bf16_f32 %0, %1, %2" : "=v"(r) : "v"(lo), "v"(hi)); return r; }
; __device__ __forceinline__ float shx(float v, int mask, int lane) { return __int_as_float(__builtin_amdgcn_ds_bpermute((lane ^ mask) << 2, __float_as_int(v))); }
; __device__ __forceinline__ float bf_lo(unsigned w) { return __uint_as_float(w << 16); }
; __device__ __forceinline__ float bf_hi(unsigned w) { return __uint_as_float(w & 0xffff0000u); }
;     __device__ __forceinline__ void operator()(const f32x4 (&acc)[2][2][4][2], const Unit& u, int wr, int wc, int fr, int fq) const {
;     ...
;             for (int m = 0; m < 4; ++m) { const int row = row0 + ai * HALF + m * 16; bf16_t* bp = HB + (size_t)row * 2048 + col0; float s = 0.f;
;                 u32x4 hv[2];
; #pragma unroll
;                 for (int bj = 0; bj < 2; ++bj) hv[bj] = *(const u32x4*)(bp + bj * HALF);
; #pragma unroll
;                 for (int bj = 0; bj < 2; ++bj) { const f32x4 a0 = acc[ai][bj][m][0], a1 = acc[ai][bj][m][1]; const u32x4 x = hv[bj];
;                     const float h0 = bf_lo(x.x) + a0[0], h1 = bf_hi(x.x) + a0[1], h2 = bf_lo(x.y) + a0[2], h3 = bf_hi(x.y) + a0[3], h4 = bf_lo(x.z) + a1[0], h5 = bf_hi(x.z) + a1[1], h6 = bf_lo(x.w) + a1[2], h7 = bf_hi(x.w) + a1[3];
;                     s += (h0 * h0 + h1 * h1) + (h2 * h2 + h3 * h3) + (h4 * h4 + h5 * h5) + (h6 * h6 + h7 * h7);
;                     u32x4 w; w.x = cvt_pk_bf16(h0, h1); w.y = cvt_pk_bf16(h2, h3); w.z = cvt_pk_bf16(h4, h5); w.w = cvt_pk_bf16(h6, h7); *(u32x4*)(bp + bj * HALF) = w; }
;                 { const int ln = fr + 16 * fq; s += shx(s, 16, ln); s += shx(s, 32, ln); }
;                 if (fq == 0) ssq_out[(size_t)row * 32 + u.pn * 4 + wc] = s;
.LBB0_813:
	v_and_b32_e32 v232, 15, v167
	v_lshrrev_b32_e32 v233, 4, v167
	s_lshl_b32 s4, s46, 8
	s_add_i32 s4, s4, s78
	v_or_b32_e32 v234, s4, v232
	s_lshl_b32 s4, s12, 8
	s_or_b32 s4, s4, s73
	v_lshl_add_u32 v235, v233, 3, s4
	v_lshlrev_b32_e32 v235, 1, v235
	v_lshl_add_u32 v235, v234, 12, v235
	v_add_u32_e32 v236, 0x10000, v235
	v_add_u32_e32 v237, 0x20000, v235
	v_add_u32_e32 v238, 0x30000, v235
	v_add_u32_e32 v239, 0x80000, v235
	v_add_u32_e32 v240, 0x90000, v235
	v_add_u32_e32 v241, 0xa0000, v235
	v_add_u32_e32 v242, 0xb0000, v235
	global_load_dwordx4 v[168:171], v235, s[14:15]
	global_load_dwordx4 v[172:175], v235, s[14:15] offset:256
	global_load_dwordx4 v[176:179], v236, s[14:15]
	global_load_dwordx4 v[180:183], v236, s[14:15] offset:256
	global_load_dwordx4 v[184:187], v237, s[14:15]
	global_load_dwordx4 v[188:191], v237, s[14:15] offset:256
	global_load_dwordx4 v[192:195], v238, s[14:15]
	global_load_dwordx4 v[196:199], v238, s[14:15] offset:256
	global_load_dwordx4 v[200:203], v239, s[14:15]
	global_load_dwordx4 v[204:207], v239, s[14:15] offset:256
	global_load_dwordx4 v[208:211], v240, s[14:15]
	global_load_dwordx4 v[212:215], v240, s[14:15] offset:256
	global_load_dwordx4 v[216:219], v241, s[14:15]
	global_load_dwordx4 v[220:223], v241, s[14:15] offset:256
	global_load_dwordx4 v[224:227], v242, s[14:15]
	global_load_dwordx4 v[228:231], v242, s[14:15] offset:256
	s_waitcnt vmcnt(0)
	v_mov_b32_e32 v164, v167
	s_lshl_b32 s4, s46, 8
	s_add_i32 s4, s4, s78
	v_and_b32_e32 v165, 15, v164
	v_or_b32_e32 v146, s4, v165
	s_lshl_b32 s4, s12, 8
	v_ashrrev_i32_e32 v166, 4, v164
	s_or_b32 s4, s4, s73
	v_ashrrev_i32_e32 v147, 31, v146
	v_lshl_add_u32 v144, v166, 3, s4
	v_lshlrev_b64 v[152:153], 12, v[146:147]
	v_ashrrev_i32_e32 v145, 31, v144
	v_lshl_add_u64 v[152:153], s[14:15], 0, v[152:153]
	v_lshl_add_u64 v[162:163], v[144:145], 1, v[152:153]
	s_nop 1
	v_mov_b32_e32 v154, v168
	v_mov_b32_e32 v155, v169
	v_mov_b32_e32 v156, v170
	v_mov_b32_e32 v157, v171
	v_mov_b32_e32 v158, v172
	v_mov_b32_e32 v159, v173
	v_mov_b32_e32 v160, v174
	v_mov_b32_e32 v161, v175
	v_cmp_gt_u32_e32 vcc, 16, v164
	v_lshlrev_b32_e32 v152, 6, v166
	v_lshlrev_b32_e32 v164, 2, v165
	v_bitop3_b32 v153, v152, 64, v164 bitop3:0x36
	v_bitop3_b32 v152, v152, s40, v164 bitop3:0x36
	s_lshl_b32 s22, s12, 2
	s_ashr_i32 s23, s22, 31
	v_lshlrev_b32_e32 v164, 16, v154
	v_and_b32_e32 v154, 0xffff0000, v154
	v_lshlrev_b32_e32 v165, 16, v155
	v_and_b32_e32 v155, 0xffff0000, v155
	v_lshlrev_b32_e32 v169, 16, v158
	v_and_b32_e32 v158, 0xffff0000, v158
	v_lshlrev_b32_e32 v170, 16, v159
	v_and_b32_e32 v159, 0xffff0000, v159
	v_lshlrev_b32_e32 v166, 16, v156
	v_and_b32_e32 v156, 0xffff0000, v156
	v_lshlrev_b32_e32 v168, 16, v157
	v_and_b32_e32 v157, 0xffff0000, v157
	v_lshlrev_b32_e32 v171, 16, v160
	v_and_b32_e32 v160, 0xffff0000, v160
	v_lshlrev_b32_e32 v172, 16, v161
	v_and_b32_e32 v161, 0xffff0000, v161
	v_add_f32_e32 v125, v125, v154
	v_add_f32_e32 v127, v127, v155
	v_add_f32_e32 v117, v117, v158
	v_add_f32_e32 v119, v119, v159
	v_add_f32_e32 v124, v124, v164
	v_add_f32_e32 v126, v126, v165
	v_add_f32_e32 v121, v121, v156
	v_add_f32_e32 v123, v123, v157
	v_add_f32_e32 v116, v116, v169
	v_add_f32_e32 v118, v118, v170
	v_add_f32_e32 v154, v112, v171
	v_add_f32_e32 v155, v113, v160
	v_add_f32_e32 v156, v114, v172
	v_add_f32_e32 v157, v115, v161
	v_mul_f32_e32 v114, v125, v125
	v_mul_f32_e32 v115, v127, v127
	v_cvt_pk_bf16_f32 v112, v124, v125
	v_cvt_pk_bf16_f32 v113, v126, v127
	v_mul_f32_e32 v125, v117, v117
	v_mul_f32_e32 v127, v119, v119
	v_add_f32_e32 v120, v120, v166
	v_mul_f32_e32 v158, v121, v121
	v_mul_f32_e32 v160, v155, v155
	v_fmac_f32_e32 v114, v124, v124
	v_fmac_f32_e32 v115, v126, v126
	v_fmac_f32_e32 v125, v116, v116
	v_fmac_f32_e32 v127, v118, v118
	v_add_f32_e32 v122, v122, v168
	v_mul_f32_e32 v159, v123, v123
	v_mul_f32_e32 v161, v157, v157
	v_fmac_f32_e32 v158, v120, v120
	v_fmac_f32_e32 v160, v154, v154
	v_add_f32_e32 v114, v114, v115
	v_add_f32_e32 v115, v125, v127
	v_fmac_f32_e32 v159, v122, v122
	v_fmac_f32_e32 v161, v156, v156
	v_add_f32_e32 v114, v158, v114
	v_add_f32_e32 v115, v160, v115
	v_add_f32_e32 v114, v159, v114
	v_add_f32_e32 v115, v161, v115
	v_add_f32_e32 v124, v114, v115
	ds_bpermute_b32 v125, v153, v124
	v_cvt_pk_bf16_f32 v114, v120, v121
	v_cvt_pk_bf16_f32 v115, v122, v123
	global_store_dwordx4 v[162:163], v[112:115], off
	s_waitcnt lgkmcnt(0)
	s_nop 0
	v_add_f32_e32 v112, v124, v125
	ds_bpermute_b32 v113, v152, v112
	v_cvt_pk_bf16_f32 v114, v116, v117
	v_cvt_pk_bf16_f32 v115, v118, v119
	v_cvt_pk_bf16_f32 v116, v154, v155
	v_cvt_pk_bf16_f32 v117, v156, v157
	global_store_dwordx4 v[162:163], v[114:117], off offset:256
	s_and_saveexec_b64 s[26:27], vcc
	s_cbranch_execz .LBB0_815
	s_waitcnt lgkmcnt(0)
	v_add_f32_e32 v114, v112, v113
	v_lshlrev_b64 v[112:113], 7, v[146:147]
	v_lshl_add_u64 v[112:113], s[16:17], 0, v[112:113]
	v_lshl_add_u64 v[112:113], s[22:23], 2, v[112:113]
	s_lshl_b32 s12, s72, 2
	v_lshl_add_u64 v[112:113], v[112:113], 0, s[12:13]
	global_store_dword v[112:113], v114, off
; __device__ __forceinline__ unsigned cvt_pk_bf16(float lo, float hi) { unsigned r; asm volatile("v_cvt_pk_bf16_f32 %0, %1, %2" : "=v"(r) : "v"(lo), "v"(hi)); return r; }
; __device__ __forceinline__ float shx(float v, int mask, int lane) { return __int_as_float(__builtin_amdgcn_ds_bpermute((lane ^ mask) << 2, __float_as_int(v))); }
; __device__ __forceinline__ float bf_lo(unsigned w) { return __uint_as_float(w << 16); }
; __device__ __forceinline__ float bf_hi(unsigned w) { return __uint_as_float(w & 0xffff0000u); }
;     __device__ __forceinline__ void operator()(const f32x4 (&acc)[2][2][4][2], const Unit& u, int wr, int wc, int fr, int fq) const {
;     ...
;             for (int m = 0; m < 4; ++m) { const int row = row0 + ai * HALF + m * 16; bf16_t* bp = HB + (size_t)row * 2048 + col0; float s = 0.f;
;                 u32x4 hv[2];
; #pragma unroll
;                 for (int bj = 0; bj < 2; ++bj) hv[bj] = *(const u32x4*)(bp + bj * HALF);
; #pragma unroll
;                 for (int bj = 0; bj < 2; ++bj) { const f32x4 a0 = acc[ai][bj][m][0], a1 = acc[ai][bj][m][1]; const u32x4 x = hv[bj];
;                     const float h0 = bf_lo(x.x) + a0[0], h1 = bf_hi(x.x) + a0[1], h2 = bf_lo(x.y) + a0[2], h3 = bf_hi(x.y) + a0[3], h4 = bf_lo(x.z) + a1[0], h5 = bf_hi(x.z) + a1[1], h6 = bf_lo(x.w) + a1[2], h7 = bf_hi(x.w) + a1[3];
;                     s += (h0 * h0 + h1 * h1) + (h2 * h2 + h3 * h3) + (h4 * h4 + h5 * h5) + (h6 * h6 + h7 * h7);
;                     u32x4 w; w.x = cvt_pk_bf16(h0, h1); w.y = cvt_pk_bf16(h2, h3); w.z = cvt_pk_bf16(h4, h5); w.w = cvt_pk_bf16(h6, h7); *(u32x4*)(bp + bj * HALF) = w; }
;                 { const int ln = fr + 16 * fq; s += shx(s, 16, ln); s += shx(s, 32, ln); }
;                 if (fq == 0) ssq_out[(size_t)row * 32 + u.pn * 4 + wc] = s;
.LBB0_815:
	s_or_b64 exec, exec, s[26:27]
	v_or_b32_e32 v112, 16, v146
	s_waitcnt lgkmcnt(0)
	v_ashrrev_i32_e32 v113, 31, v112
	v_lshlrev_b64 v[114:115], 12, v[112:113]
	v_lshl_add_u64 v[114:115], s[14:15], 0, v[114:115]
	v_lshl_add_u64 v[122:123], v[144:145], 1, v[114:115]
	s_nop 1
	v_mov_b32_e32 v114, v176
	v_mov_b32_e32 v115, v177
	v_mov_b32_e32 v116, v178
	v_mov_b32_e32 v117, v179
	v_mov_b32_e32 v118, v180
	v_mov_b32_e32 v119, v181
	v_mov_b32_e32 v120, v182
	v_mov_b32_e32 v121, v183
	v_lshlrev_b32_e32 v124, 16, v114
	v_and_b32_e32 v114, 0xffff0000, v114
	v_lshlrev_b32_e32 v125, 16, v115
	v_and_b32_e32 v115, 0xffff0000, v115
	v_lshlrev_b32_e32 v147, 16, v118
	v_and_b32_e32 v118, 0xffff0000, v118
	v_lshlrev_b32_e32 v154, 16, v119
	v_and_b32_e32 v119, 0xffff0000, v119
	v_lshlrev_b32_e32 v126, 16, v116
	v_and_b32_e32 v116, 0xffff0000, v116
	v_lshlrev_b32_e32 v127, 16, v117
	v_and_b32_e32 v117, 0xffff0000, v117
	v_lshlrev_b32_e32 v155, 16, v120
	v_and_b32_e32 v120, 0xffff0000, v120
	v_lshlrev_b32_e32 v156, 16, v121
	v_and_b32_e32 v121, 0xffff0000, v121
	v_add_f32_e32 v109, v109, v114
	v_add_f32_e32 v111, v111, v115
	v_add_f32_e32 v101, v101, v118
	v_add_f32_e32 v103, v103, v119
	v_add_f32_e32 v108, v108, v124
	v_add_f32_e32 v110, v110, v125
	v_add_f32_e32 v105, v105, v116
	v_add_f32_e32 v107, v107, v117
	v_add_f32_e32 v100, v100, v147
	v_add_f32_e32 v102, v102, v154
	v_add_f32_e32 v114, v96, v155
	v_add_f32_e32 v115, v97, v120
	v_add_f32_e32 v116, v98, v156
	v_add_f32_e32 v117, v99, v121
	v_mul_f32_e32 v98, v109, v109
	v_mul_f32_e32 v99, v111, v111
	v_cvt_pk_bf16_f32 v96, v108, v109
	v_cvt_pk_bf16_f32 v97, v110, v111
	v_mul_f32_e32 v109, v101, v101
	v_mul_f32_e32 v111, v103, v103
	v_add_f32_e32 v104, v104, v126
	v_mul_f32_e32 v118, v105, v105
	v_mul_f32_e32 v120, v115, v115
	v_fmac_f32_e32 v98, v108, v108
	v_fmac_f32_e32 v99, v110, v110
	v_fmac_f32_e32 v109, v100, v100
	v_fmac_f32_e32 v111, v102, v102
	v_add_f32_e32 v106, v106, v127
	v_mul_f32_e32 v119, v107, v107
	v_mul_f32_e32 v121, v117, v117
	v_fmac_f32_e32 v118, v104, v104
	v_fmac_f32_e32 v120, v114, v114
	v_add_f32_e32 v98, v98, v99
	v_add_f32_e32 v99, v109, v111
	v_fmac_f32_e32 v119, v106, v106
	v_fmac_f32_e32 v121, v116, v116
	v_add_f32_e32 v98, v118, v98
	v_add_f32_e32 v99, v120, v99
	v_add_f32_e32 v98, v119, v98
	v_add_f32_e32 v99, v121, v99
	v_add_f32_e32 v108, v98, v99
	ds_bpermute_b32 v109, v153, v108
	v_cvt_pk_bf16_f32 v98, v104, v105
	v_cvt_pk_bf16_f32 v99, v106, v107
	global_store_dwordx4 v[122:123], v[96:99], off
	s_waitcnt lgkmcnt(0)
	s_nop 0
	v_add_f32_e32 v96, v108, v109
	ds_bpermute_b32 v97, v152, v96
	v_cvt_pk_bf16_f32 v98, v100, v101
	v_cvt_pk_bf16_f32 v99, v102, v103
	v_cvt_pk_bf16_f32 v100, v114, v115
	v_cvt_pk_bf16_f32 v101, v116, v117
	global_store_dwordx4 v[122:123], v[98:101], off offset:256
	s_and_saveexec_b64 s[26:27], vcc
	s_cbranch_execz .LBB0_817
	s_waitcnt lgkmcnt(0)
	v_add_f32_e32 v98, v96, v97
	v_lshlrev_b64 v[96:97], 7, v[112:113]
	v_lshl_add_u64 v[96:97], s[16:17], 0, v[96:97]
	v_lshl_add_u64 v[96:97], s[22:23], 2, v[96:97]
	s_lshl_b32 s12, s72, 2
	v_lshl_add_u64 v[96:97], v[96:97], 0, s[12:13]
	global_store_dword v[96:97], v98, off
.LBB0_817:
	s_or_b64 exec, exec, s[26:27]
	v_or_b32_e32 v96, 32, v146
	s_waitcnt lgkmcnt(0)
	v_ashrrev_i32_e32 v97, 31, v96
	v_lshlrev_b64 v[98:99], 12, v[96:97]
	v_lshl_add_u64 v[98:99], s[14:15], 0, v[98:99]
	v_lshl_add_u64 v[106:107], v[144:145], 1, v[98:99]
	s_nop 1
	v_mov_b32_e32 v98, v184
	v_mov_b32_e32 v99, v185
	v_mov_b32_e32 v100, v186
	v_mov_b32_e32 v101, v187
	v_mov_b32_e32 v102, v188
	v_mov_b32_e32 v103, v189
	v_mov_b32_e32 v104, v190
	v_mov_b32_e32 v105, v191
	v_lshlrev_b32_e32 v108, 16, v98
	v_and_b32_e32 v98, 0xffff0000, v98
	v_lshlrev_b32_e32 v109, 16, v99
	v_and_b32_e32 v99, 0xffff0000, v99
	v_lshlrev_b32_e32 v112, 16, v102
	v_and_b32_e32 v102, 0xffff0000, v102
	v_lshlrev_b32_e32 v113, 16, v103
	v_and_b32_e32 v103, 0xffff0000, v103
	v_lshlrev_b32_e32 v110, 16, v100
	v_and_b32_e32 v100, 0xffff0000, v100
	v_lshlrev_b32_e32 v111, 16, v101
	v_and_b32_e32 v101, 0xffff0000, v101
	v_lshlrev_b32_e32 v114, 16, v104
	v_and_b32_e32 v104, 0xffff0000, v104
	v_lshlrev_b32_e32 v115, 16, v105
	v_and_b32_e32 v105, 0xffff0000, v105
	v_add_f32_e32 v93, v93, v98
	v_add_f32_e32 v95, v95, v99
	v_add_f32_e32 v85, v85, v102
	v_add_f32_e32 v87, v87, v103
	v_add_f32_e32 v92, v92, v108
	v_add_f32_e32 v94, v94, v109
	v_add_f32_e32 v89, v89, v100
	v_add_f32_e32 v91, v91, v101
	v_add_f32_e32 v84, v84, v112
	v_add_f32_e32 v86, v86, v113
	v_add_f32_e32 v98, v80, v114
	v_add_f32_e32 v99, v81, v104
	v_add_f32_e32 v100, v82, v115
	v_add_f32_e32 v101, v83, v105
	v_mul_f32_e32 v82, v93, v93
	v_mul_f32_e32 v83, v95, v95
	v_cvt_pk_bf16_f32 v80, v92, v93
	v_cvt_pk_bf16_f32 v81, v94, v95
	v_mul_f32_e32 v93, v85, v85
	v_mul_f32_e32 v95, v87, v87
	v_add_f32_e32 v88, v88, v110
	v_mul_f32_e32 v102, v89, v89
	v_mul_f32_e32 v104, v99, v99
	v_fmac_f32_e32 v82, v92, v92
	v_fmac_f32_e32 v83, v94, v94
	v_fmac_f32_e32 v93, v84, v84
	v_fmac_f32_e32 v95, v86, v86
	v_add_f32_e32 v90, v90, v111
	v_mul_f32_e32 v103, v91, v91
	v_mul_f32_e32 v105, v101, v101
	v_fmac_f32_e32 v102, v88, v88
	v_fmac_f32_e32 v104, v98, v98
	v_add_f32_e32 v82, v82, v83
	v_add_f32_e32 v83, v93, v95
	v_fmac_f32_e32 v103, v90, v90
	v_fmac_f32_e32 v105, v100, v100
	v_add_f32_e32 v82, v102, v82
	v_add_f32_e32 v83, v104, v83
	v_add_f32_e32 v82, v103, v82
	v_add_f32_e32 v83, v105, v83
	v_add_f32_e32 v92, v82, v83
	ds_bpermute_b32 v93, v153, v92
	v_cvt_pk_bf16_f32 v82, v88, v89
	v_cvt_pk_bf16_f32 v83, v90, v91
	global_store_dwordx4 v[106:107], v[80:83], off
	s_waitcnt lgkmcnt(0)
	s_nop 0
	v_add_f32_e32 v80, v92, v93
	ds_bpermute_b32 v81, v152, v80
	v_cvt_pk_bf16_f32 v82, v84, v85
	v_cvt_pk_bf16_f32 v83, v86, v87
	v_cvt_pk_bf16_f32 v84, v98, v99
	v_cvt_pk_bf16_f32 v85, v100, v101
	global_store_dwordx4 v[106:107], v[82:85], off offset:256
	s_and_saveexec_b64 s[26:27], vcc
	s_cbranch_execz .LBB0_819
	s_waitcnt lgkmcnt(0)
	v_add_f32_e32 v82, v80, v81
	v_lshlrev_b64 v[80:81], 7, v[96:97]
	v_lshl_add_u64 v[80:81], s[16:17], 0, v[80:81]
	v_lshl_add_u64 v[80:81], s[22:23], 2, v[80:81]
	s_lshl_b32 s12, s72, 2
	v_lshl_add_u64 v[80:81], v[80:81], 0, s[12:13]
	global_store_dword v[80:81], v82, off
; __device__ __forceinline__ unsigned cvt_pk_bf16(float lo, float hi) { unsigned r; asm volatile("v_cvt_pk_bf16_f32 %0, %1, %2" : "=v"(r) : "v"(lo), "v"(hi)); return r; }
; __device__ __forceinline__ float shx(float v, int mask, int lane) { return __int_as_float(__builtin_amdgcn_ds_bpermute((lane ^ mask) << 2, __float_as_int(v))); }
; __device__ __forceinline__ float bf_lo(unsigned w) { return __uint_as_float(w << 16); }
; __device__ __forceinline__ float bf_hi(unsigned w) { return __uint_as_float(w & 0xffff0000u); }
;     __device__ __forceinline__ void operator()(const f32x4 (&acc)[2][2][4][2], const Unit& u, int wr, int wc, int fr, int fq) const {
;     ...
;             for (int m = 0; m < 4; ++m) { const int row = row0 + ai * HALF + m * 16; bf16_t* bp = HB + (size_t)row * 2048 + col0; float s = 0.f;
;                 u32x4 hv[2];
; #pragma unroll
;                 for (int bj = 0; bj < 2; ++bj) hv[bj] = *(const u32x4*)(bp + bj * HALF);
; #pragma unroll
;                 for (int bj = 0; bj < 2; ++bj) { const f32x4 a0 = acc[ai][bj][m][0], a1 = acc[ai][bj][m][1]; const u32x4 x = hv[bj];
;                     const float h0 = bf_lo(x.x) + a0[0], h1 = bf_hi(x.x) + a0[1], h2 = bf_lo(x.y) + a0[2], h3 = bf_hi(x.y) + a0[3], h4 = bf_lo(x.z) + a1[0], h5 = bf_hi(x.z) + a1[1], h6 = bf_lo(x.w) + a1[2], h7 = bf_hi(x.w) + a1[3];
;                     s += (h0 * h0 + h1 * h1) + (h2 * h2 + h3 * h3) + (h4 * h4 + h5 * h5) + (h6 * h6 + h7 * h7);
;                     u32x4 w; w.x = cvt_pk_bf16(h0, h1); w.y = cvt_pk_bf16(h2, h3); w.z = cvt_pk_bf16(h4, h5); w.w = cvt_pk_bf16(h6, h7); *(u32x4*)(bp + bj * HALF) = w; }
;                 { const int ln = fr + 16 * fq; s += shx(s, 16, ln); s += shx(s, 32, ln); }
;                 if (fq == 0) ssq_out[(size_t)row * 32 + u.pn * 4 + wc] = s;
.LBB0_819:
	s_or_b64 exec, exec, s[26:27]
	v_or_b32_e32 v80, 48, v146
	s_waitcnt lgkmcnt(0)
	v_ashrrev_i32_e32 v81, 31, v80
	v_lshlrev_b64 v[82:83], 12, v[80:81]
	v_lshl_add_u64 v[82:83], s[14:15], 0, v[82:83]
	v_lshl_add_u64 v[90:91], v[144:145], 1, v[82:83]
	s_nop 1
	v_mov_b32_e32 v82, v192
	v_mov_b32_e32 v83, v193
	v_mov_b32_e32 v84, v194
	v_mov_b32_e32 v85, v195
	v_mov_b32_e32 v86, v196
	v_mov_b32_e32 v87, v197
	v_mov_b32_e32 v88, v198
	v_mov_b32_e32 v89, v199
	v_lshlrev_b32_e32 v92, 16, v82
	v_and_b32_e32 v82, 0xffff0000, v82
	v_lshlrev_b32_e32 v93, 16, v83
	v_and_b32_e32 v83, 0xffff0000, v83
	v_lshlrev_b32_e32 v96, 16, v86
	v_and_b32_e32 v86, 0xffff0000, v86
	v_lshlrev_b32_e32 v97, 16, v87
	v_and_b32_e32 v87, 0xffff0000, v87
	v_lshlrev_b32_e32 v94, 16, v84
	v_and_b32_e32 v84, 0xffff0000, v84
	v_lshlrev_b32_e32 v95, 16, v85
	v_and_b32_e32 v85, 0xffff0000, v85
	v_lshlrev_b32_e32 v98, 16, v88
	v_and_b32_e32 v88, 0xffff0000, v88
	v_lshlrev_b32_e32 v99, 16, v89
	v_and_b32_e32 v89, 0xffff0000, v89
	v_add_f32_e32 v77, v77, v82
	v_add_f32_e32 v79, v79, v83
	v_add_f32_e32 v69, v69, v86
	v_add_f32_e32 v71, v71, v87
	v_add_f32_e32 v76, v76, v92
	v_add_f32_e32 v78, v78, v93
	v_add_f32_e32 v73, v73, v84
	v_add_f32_e32 v75, v75, v85
	v_add_f32_e32 v68, v68, v96
	v_add_f32_e32 v70, v70, v97
	v_add_f32_e32 v82, v64, v98
	v_add_f32_e32 v83, v65, v88
	v_add_f32_e32 v84, v66, v99
	v_add_f32_e32 v85, v67, v89
	v_mul_f32_e32 v66, v77, v77
	v_mul_f32_e32 v67, v79, v79
	v_cvt_pk_bf16_f32 v64, v76, v77
	v_cvt_pk_bf16_f32 v65, v78, v79
	v_mul_f32_e32 v77, v69, v69
	v_mul_f32_e32 v79, v71, v71
	v_add_f32_e32 v72, v72, v94
	v_mul_f32_e32 v86, v73, v73
	v_mul_f32_e32 v88, v83, v83
	v_fmac_f32_e32 v66, v76, v76
	v_fmac_f32_e32 v67, v78, v78
	v_fmac_f32_e32 v77, v68, v68
	v_fmac_f32_e32 v79, v70, v70
	v_add_f32_e32 v74, v74, v95
	v_mul_f32_e32 v87, v75, v75
	v_mul_f32_e32 v89, v85, v85
	v_fmac_f32_e32 v86, v72, v72
	v_fmac_f32_e32 v88, v82, v82
	v_add_f32_e32 v66, v66, v67
	v_add_f32_e32 v67, v77, v79
	v_fmac_f32_e32 v87, v74, v74
	v_fmac_f32_e32 v89, v84, v84
	v_add_f32_e32 v66, v86, v66
	v_add_f32_e32 v67, v88, v67
	v_add_f32_e32 v66, v87, v66
	v_add_f32_e32 v67, v89, v67
	v_add_f32_e32 v76, v66, v67
	ds_bpermute_b32 v77, v153, v76
	v_cvt_pk_bf16_f32 v66, v72, v73
	v_cvt_pk_bf16_f32 v67, v74, v75
	global_store_dwordx4 v[90:91], v[64:67], off
	s_waitcnt lgkmcnt(0)
	s_nop 0
	v_add_f32_e32 v64, v76, v77
	ds_bpermute_b32 v65, v152, v64
	v_cvt_pk_bf16_f32 v66, v68, v69
	v_cvt_pk_bf16_f32 v67, v70, v71
	v_cvt_pk_bf16_f32 v68, v82, v83
	v_cvt_pk_bf16_f32 v69, v84, v85
	global_store_dwordx4 v[90:91], v[66:69], off offset:256
	s_and_saveexec_b64 s[26:27], vcc
	s_cbranch_execz .LBB0_821
	s_waitcnt lgkmcnt(0)
	v_add_f32_e32 v66, v64, v65
	v_lshlrev_b64 v[64:65], 7, v[80:81]
	v_lshl_add_u64 v[64:65], s[16:17], 0, v[64:65]
	v_lshl_add_u64 v[64:65], s[22:23], 2, v[64:65]
	s_lshl_b32 s12, s72, 2
	v_lshl_add_u64 v[64:65], v[64:65], 0, s[12:13]
	global_store_dword v[64:65], v66, off
.LBB0_821:
	s_or_b64 exec, exec, s[26:27]
	v_add_u32_e32 v64, 0x80, v146
	s_waitcnt lgkmcnt(0)
	v_ashrrev_i32_e32 v65, 31, v64
	v_lshlrev_b64 v[66:67], 12, v[64:65]
	v_lshl_add_u64 v[66:67], s[14:15], 0, v[66:67]
	v_lshl_add_u64 v[74:75], v[144:145], 1, v[66:67]
	s_nop 1
	v_mov_b32_e32 v66, v200
	v_mov_b32_e32 v67, v201
	v_mov_b32_e32 v68, v202
	v_mov_b32_e32 v69, v203
	v_mov_b32_e32 v70, v204
	v_mov_b32_e32 v71, v205
	v_mov_b32_e32 v72, v206
	v_mov_b32_e32 v73, v207
	v_lshlrev_b32_e32 v76, 16, v66
	v_and_b32_e32 v66, 0xffff0000, v66
	v_lshlrev_b32_e32 v77, 16, v67
	v_and_b32_e32 v67, 0xffff0000, v67
	v_lshlrev_b32_e32 v80, 16, v70
	v_and_b32_e32 v70, 0xffff0000, v70
	v_lshlrev_b32_e32 v81, 16, v71
	v_and_b32_e32 v71, 0xffff0000, v71
	v_lshlrev_b32_e32 v78, 16, v68
	v_and_b32_e32 v68, 0xffff0000, v68
	v_lshlrev_b32_e32 v79, 16, v69
	v_and_b32_e32 v69, 0xffff0000, v69
	v_lshlrev_b32_e32 v82, 16, v72
	v_and_b32_e32 v72, 0xffff0000, v72
	v_lshlrev_b32_e32 v83, 16, v73
	v_and_b32_e32 v73, 0xffff0000, v73
	v_add_f32_e32 v61, v61, v66
	v_add_f32_e32 v63, v63, v67
	v_add_f32_e32 v53, v53, v70
	v_add_f32_e32 v55, v55, v71
	v_add_f32_e32 v60, v60, v76
	v_add_f32_e32 v62, v62, v77
	v_add_f32_e32 v57, v57, v68
	v_add_f32_e32 v59, v59, v69
	v_add_f32_e32 v52, v52, v80
	v_add_f32_e32 v54, v54, v81
	v_add_f32_e32 v66, v48, v82
	v_add_f32_e32 v67, v49, v72
	v_add_f32_e32 v68, v50, v83
	v_add_f32_e32 v69, v51, v73
	v_mul_f32_e32 v50, v61, v61
	v_mul_f32_e32 v51, v63, v63
	v_cvt_pk_bf16_f32 v48, v60, v61
	v_cvt_pk_bf16_f32 v49, v62, v63
	v_mul_f32_e32 v61, v53, v53
	v_mul_f32_e32 v63, v55, v55
	v_add_f32_e32 v56, v56, v78
	v_mul_f32_e32 v70, v57, v57
	v_mul_f32_e32 v72, v67, v67
	v_fmac_f32_e32 v50, v60, v60
	v_fmac_f32_e32 v51, v62, v62
	v_fmac_f32_e32 v61, v52, v52
	v_fmac_f32_e32 v63, v54, v54
	v_add_f32_e32 v58, v58, v79
	v_mul_f32_e32 v71, v59, v59
	v_mul_f32_e32 v73, v69, v69
	v_fmac_f32_e32 v70, v56, v56
	v_fmac_f32_e32 v72, v66, v66
	v_add_f32_e32 v50, v50, v51
	v_add_f32_e32 v51, v61, v63
	v_fmac_f32_e32 v71, v58, v58
	v_fmac_f32_e32 v73, v68, v68
	v_add_f32_e32 v50, v70, v50
	v_add_f32_e32 v51, v72, v51
	v_add_f32_e32 v50, v71, v50
	v_add_f32_e32 v51, v73, v51
	v_add_f32_e32 v60, v50, v51
	ds_bpermute_b32 v61, v153, v60
	v_cvt_pk_bf16_f32 v50, v56, v57
	v_cvt_pk_bf16_f32 v51, v58, v59
	global_store_dwordx4 v[74:75], v[48:51], off
	s_waitcnt lgkmcnt(0)
	s_nop 0
	v_add_f32_e32 v48, v60, v61
	ds_bpermute_b32 v49, v152, v48
	v_cvt_pk_bf16_f32 v50, v52, v53
	v_cvt_pk_bf16_f32 v51, v54, v55
	v_cvt_pk_bf16_f32 v52, v66, v67
	v_cvt_pk_bf16_f32 v53, v68, v69
	global_store_dwordx4 v[74:75], v[50:53], off offset:256
	s_and_saveexec_b64 s[26:27], vcc
	s_cbranch_execz .LBB0_823
	s_waitcnt lgkmcnt(0)
	v_add_f32_e32 v50, v48, v49
	v_lshlrev_b64 v[48:49], 7, v[64:65]
	v_lshl_add_u64 v[48:49], s[16:17], 0, v[48:49]
	v_lshl_add_u64 v[48:49], s[22:23], 2, v[48:49]
	s_lshl_b32 s12, s72, 2
	v_lshl_add_u64 v[48:49], v[48:49], 0, s[12:13]
	global_store_dword v[48:49], v50, off
; __device__ __forceinline__ unsigned cvt_pk_bf16(float lo, float hi) { unsigned r; asm volatile("v_cvt_pk_bf16_f32 %0, %1, %2" : "=v"(r) : "v"(lo), "v"(hi)); return r; }
; __device__ __forceinline__ float shx(float v, int mask, int lane) { return __int_as_float(__builtin_amdgcn_ds_bpermute((lane ^ mask) << 2, __float_as_int(v))); }
; __device__ __forceinline__ float bf_lo(unsigned w) { return __uint_as_float(w << 16); }
; __device__ __forceinline__ float bf_hi(unsigned w) { return __uint_as_float(w & 0xffff0000u); }
;     __device__ __forceinline__ void operator()(const f32x4 (&acc)[2][2][4][2], const Unit& u, int wr, int wc, int fr, int fq) const {
;     ...
;             for (int m = 0; m < 4; ++m) { const int row = row0 + ai * HALF + m * 16; bf16_t* bp = HB + (size_t)row * 2048 + col0; float s = 0.f;
;                 u32x4 hv[2];
; #pragma unroll
;                 for (int bj = 0; bj < 2; ++bj) hv[bj] = *(const u32x4*)(bp + bj * HALF);
; #pragma unroll
;                 for (int bj = 0; bj < 2; ++bj) { const f32x4 a0 = acc[ai][bj][m][0], a1 = acc[ai][bj][m][1]; const u32x4 x = hv[bj];
;                     const float h0 = bf_lo(x.x) + a0[0], h1 = bf_hi(x.x) + a0[1], h2 = bf_lo(x.y) + a0[2], h3 = bf_hi(x.y) + a0[3], h4 = bf_lo(x.z) + a1[0], h5 = bf_hi(x.z) + a1[1], h6 = bf_lo(x.w) + a1[2], h7 = bf_hi(x.w) + a1[3];
;                     s += (h0 * h0 + h1 * h1) + (h2 * h2 + h3 * h3) + (h4 * h4 + h5 * h5) + (h6 * h6 + h7 * h7);
;                     u32x4 w; w.x = cvt_pk_bf16(h0, h1); w.y = cvt_pk_bf16(h2, h3); w.z = cvt_pk_bf16(h4, h5); w.w = cvt_pk_bf16(h6, h7); *(u32x4*)(bp + bj * HALF) = w; }
;                 { const int ln = fr + 16 * fq; s += shx(s, 16, ln); s += shx(s, 32, ln); }
;                 if (fq == 0) ssq_out[(size_t)row * 32 + u.pn * 4 + wc] = s;
.LBB0_823:
	s_or_b64 exec, exec, s[26:27]
	v_add_u32_e32 v48, 0x90, v146
	s_waitcnt lgkmcnt(0)
	v_ashrrev_i32_e32 v49, 31, v48
	v_lshlrev_b64 v[50:51], 12, v[48:49]
	v_lshl_add_u64 v[50:51], s[14:15], 0, v[50:51]
	v_lshl_add_u64 v[58:59], v[144:145], 1, v[50:51]
	s_nop 1
	v_mov_b32_e32 v50, v208
	v_mov_b32_e32 v51, v209
	v_mov_b32_e32 v52, v210
	v_mov_b32_e32 v53, v211
	v_mov_b32_e32 v54, v212
	v_mov_b32_e32 v55, v213
	v_mov_b32_e32 v56, v214
	v_mov_b32_e32 v57, v215
	v_lshlrev_b32_e32 v60, 16, v50
	v_and_b32_e32 v50, 0xffff0000, v50
	v_lshlrev_b32_e32 v61, 16, v51
	v_and_b32_e32 v51, 0xffff0000, v51
	v_lshlrev_b32_e32 v64, 16, v54
	v_and_b32_e32 v54, 0xffff0000, v54
	v_lshlrev_b32_e32 v65, 16, v55
	v_and_b32_e32 v55, 0xffff0000, v55
	v_lshlrev_b32_e32 v62, 16, v52
	v_and_b32_e32 v52, 0xffff0000, v52
	v_lshlrev_b32_e32 v63, 16, v53
	v_and_b32_e32 v53, 0xffff0000, v53
	v_lshlrev_b32_e32 v66, 16, v56
	v_and_b32_e32 v56, 0xffff0000, v56
	v_lshlrev_b32_e32 v67, 16, v57
	v_and_b32_e32 v57, 0xffff0000, v57
	v_add_f32_e32 v45, v45, v50
	v_add_f32_e32 v47, v47, v51
	v_add_f32_e32 v37, v37, v54
	v_add_f32_e32 v39, v39, v55
	v_add_f32_e32 v44, v44, v60
	v_add_f32_e32 v46, v46, v61
	v_add_f32_e32 v41, v41, v52
	v_add_f32_e32 v43, v43, v53
	v_add_f32_e32 v36, v36, v64
	v_add_f32_e32 v38, v38, v65
	v_add_f32_e32 v50, v32, v66
	v_add_f32_e32 v51, v33, v56
	v_add_f32_e32 v52, v34, v67
	v_add_f32_e32 v53, v35, v57
	v_mul_f32_e32 v34, v45, v45
	v_mul_f32_e32 v35, v47, v47
	v_cvt_pk_bf16_f32 v32, v44, v45
	v_cvt_pk_bf16_f32 v33, v46, v47
	v_mul_f32_e32 v45, v37, v37
	v_mul_f32_e32 v47, v39, v39
	v_add_f32_e32 v40, v40, v62
	v_mul_f32_e32 v54, v41, v41
	v_mul_f32_e32 v56, v51, v51
	v_fmac_f32_e32 v34, v44, v44
	v_fmac_f32_e32 v35, v46, v46
	v_fmac_f32_e32 v45, v36, v36
	v_fmac_f32_e32 v47, v38, v38
	v_add_f32_e32 v42, v42, v63
	v_mul_f32_e32 v55, v43, v43
	v_mul_f32_e32 v57, v53, v53
	v_fmac_f32_e32 v54, v40, v40
	v_fmac_f32_e32 v56, v50, v50
	v_add_f32_e32 v34, v34, v35
	v_add_f32_e32 v35, v45, v47
	v_fmac_f32_e32 v55, v42, v42
	v_fmac_f32_e32 v57, v52, v52
	v_add_f32_e32 v34, v54, v34
	v_add_f32_e32 v35, v56, v35
	v_add_f32_e32 v34, v55, v34
	v_add_f32_e32 v35, v57, v35
	v_add_f32_e32 v44, v34, v35
	ds_bpermute_b32 v45, v153, v44
	v_cvt_pk_bf16_f32 v34, v40, v41
	v_cvt_pk_bf16_f32 v35, v42, v43
	global_store_dwordx4 v[58:59], v[32:35], off
	s_waitcnt lgkmcnt(0)
	s_nop 0
	v_add_f32_e32 v32, v44, v45
	ds_bpermute_b32 v33, v152, v32
	v_cvt_pk_bf16_f32 v34, v36, v37
	v_cvt_pk_bf16_f32 v35, v38, v39
	v_cvt_pk_bf16_f32 v36, v50, v51
	v_cvt_pk_bf16_f32 v37, v52, v53
	global_store_dwordx4 v[58:59], v[34:37], off offset:256
	s_and_saveexec_b64 s[26:27], vcc
	s_cbranch_execz .LBB0_825
	s_waitcnt lgkmcnt(0)
	v_add_f32_e32 v34, v32, v33
	v_lshlrev_b64 v[32:33], 7, v[48:49]
	v_lshl_add_u64 v[32:33], s[16:17], 0, v[32:33]
	v_lshl_add_u64 v[32:33], s[22:23], 2, v[32:33]
	s_lshl_b32 s12, s72, 2
	v_lshl_add_u64 v[32:33], v[32:33], 0, s[12:13]
	global_store_dword v[32:33], v34, off
; __device__ __forceinline__ unsigned cvt_pk_bf16(float lo, float hi) { unsigned r; asm volatile("v_cvt_pk_bf16_f32 %0, %1, %2" : "=v"(r) : "v"(lo), "v"(hi)); return r; }
; __device__ __forceinline__ float shx(float v, int mask, int lane) { return __int_as_float(__builtin_amdgcn_ds_bpermute((lane ^ mask) << 2, __float_as_int(v))); }
; __device__ __forceinline__ float bf_lo(unsigned w) { return __uint_as_float(w << 16); }
; __device__ __forceinline__ float bf_hi(unsigned w) { return __uint_as_float(w & 0xffff0000u); }
;     __device__ __forceinline__ void operator()(const f32x4 (&acc)[2][2][4][2], const Unit& u, int wr, int wc, int fr, int fq) const {
;     ...
;             for (int m = 0; m < 4; ++m) { const int row = row0 + ai * HALF + m * 16; bf16_t* bp = HB + (size_t)row * 2048 + col0; float s = 0.f;
;                 u32x4 hv[2];
; #pragma unroll
;                 for (int bj = 0; bj < 2; ++bj) hv[bj] = *(const u32x4*)(bp + bj * HALF);
; #pragma unroll
;                 for (int bj = 0; bj < 2; ++bj) { const f32x4 a0 = acc[ai][bj][m][0], a1 = acc[ai][bj][m][1]; const u32x4 x = hv[bj];
;                     const float h0 = bf_lo(x.x) + a0[0], h1 = bf_hi(x.x) + a0[1], h2 = bf_lo(x.y) + a0[2], h3 = bf_hi(x.y) + a0[3], h4 = bf_lo(x.z) + a1[0], h5 = bf_hi(x.z) + a1[1], h6 = bf_lo(x.w) + a1[2], h7 = bf_hi(x.w) + a1[3];
;                     s += (h0 * h0 + h1 * h1) + (h2 * h2 + h3 * h3) + (h4 * h4 + h5 * h5) + (h6 * h6 + h7 * h7);
;                     u32x4 w; w.x = cvt_pk_bf16(h0, h1); w.y = cvt_pk_bf16(h2, h3); w.z = cvt_pk_bf16(h4, h5); w.w = cvt_pk_bf16(h6, h7); *(u32x4*)(bp + bj * HALF) = w; }
;                 { const int ln = fr + 16 * fq; s += shx(s, 16, ln); s += shx(s, 32, ln); }
;                 if (fq == 0) ssq_out[(size_t)row * 32 + u.pn * 4 + wc] = s;
.LBB0_825:
	s_or_b64 exec, exec, s[26:27]
	v_add_u32_e32 v32, 0xa0, v146
	s_waitcnt lgkmcnt(0)
	v_ashrrev_i32_e32 v33, 31, v32
	v_lshlrev_b64 v[34:35], 12, v[32:33]
	v_lshl_add_u64 v[34:35], s[14:15], 0, v[34:35]
	v_lshl_add_u64 v[42:43], v[144:145], 1, v[34:35]
	s_nop 1
	v_mov_b32_e32 v34, v216
	v_mov_b32_e32 v35, v217
	v_mov_b32_e32 v36, v218
	v_mov_b32_e32 v37, v219
	v_mov_b32_e32 v38, v220
	v_mov_b32_e32 v39, v221
	v_mov_b32_e32 v40, v222
	v_mov_b32_e32 v41, v223
	v_lshlrev_b32_e32 v44, 16, v34
	v_and_b32_e32 v34, 0xffff0000, v34
	v_lshlrev_b32_e32 v45, 16, v35
	v_and_b32_e32 v35, 0xffff0000, v35
	v_lshlrev_b32_e32 v48, 16, v38
	v_and_b32_e32 v38, 0xffff0000, v38
	v_lshlrev_b32_e32 v49, 16, v39
	v_and_b32_e32 v39, 0xffff0000, v39
	v_lshlrev_b32_e32 v46, 16, v36
	v_and_b32_e32 v36, 0xffff0000, v36
	v_lshlrev_b32_e32 v47, 16, v37
	v_and_b32_e32 v37, 0xffff0000, v37
	v_lshlrev_b32_e32 v50, 16, v40
	v_and_b32_e32 v40, 0xffff0000, v40
	v_lshlrev_b32_e32 v51, 16, v41
	v_and_b32_e32 v41, 0xffff0000, v41
	v_add_f32_e32 v29, v29, v34
	v_add_f32_e32 v31, v31, v35
	v_add_f32_e32 v21, v21, v38
	v_add_f32_e32 v23, v23, v39
	v_add_f32_e32 v28, v28, v44
	v_add_f32_e32 v30, v30, v45
	v_add_f32_e32 v25, v25, v36
	v_add_f32_e32 v27, v27, v37
	v_add_f32_e32 v20, v20, v48
	v_add_f32_e32 v22, v22, v49
	v_add_f32_e32 v34, v16, v50
	v_add_f32_e32 v35, v17, v40
	v_add_f32_e32 v36, v18, v51
	v_add_f32_e32 v37, v19, v41
	v_mul_f32_e32 v18, v29, v29
	v_mul_f32_e32 v19, v31, v31
	v_cvt_pk_bf16_f32 v16, v28, v29
	v_cvt_pk_bf16_f32 v17, v30, v31
	v_mul_f32_e32 v29, v21, v21
	v_mul_f32_e32 v31, v23, v23
	v_add_f32_e32 v24, v24, v46
	v_mul_f32_e32 v38, v25, v25
	v_mul_f32_e32 v40, v35, v35
	v_fmac_f32_e32 v18, v28, v28
	v_fmac_f32_e32 v19, v30, v30
	v_fmac_f32_e32 v29, v20, v20
	v_fmac_f32_e32 v31, v22, v22
	v_add_f32_e32 v26, v26, v47
	v_mul_f32_e32 v39, v27, v27
	v_mul_f32_e32 v41, v37, v37
	v_fmac_f32_e32 v38, v24, v24
	v_fmac_f32_e32 v40, v34, v34
	v_add_f32_e32 v18, v18, v19
	v_add_f32_e32 v19, v29, v31
	v_fmac_f32_e32 v39, v26, v26
	v_fmac_f32_e32 v41, v36, v36
	v_add_f32_e32 v18, v38, v18
	v_add_f32_e32 v19, v40, v19
	v_add_f32_e32 v18, v39, v18
	v_add_f32_e32 v19, v41, v19
	v_add_f32_e32 v28, v18, v19
	ds_bpermute_b32 v29, v153, v28
	v_cvt_pk_bf16_f32 v18, v24, v25
	v_cvt_pk_bf16_f32 v19, v26, v27
	global_store_dwordx4 v[42:43], v[16:19], off
	s_waitcnt lgkmcnt(0)
	s_nop 0
	v_add_f32_e32 v16, v28, v29
	ds_bpermute_b32 v17, v152, v16
	v_cvt_pk_bf16_f32 v18, v20, v21
	v_cvt_pk_bf16_f32 v19, v22, v23
	v_cvt_pk_bf16_f32 v20, v34, v35
	v_cvt_pk_bf16_f32 v21, v36, v37
	global_store_dwordx4 v[42:43], v[18:21], off offset:256
	s_and_saveexec_b64 s[26:27], vcc
	s_cbranch_execz .LBB0_827
	s_waitcnt lgkmcnt(0)
	v_add_f32_e32 v18, v16, v17
	v_lshlrev_b64 v[16:17], 7, v[32:33]
	v_lshl_add_u64 v[16:17], s[16:17], 0, v[16:17]
	v_lshl_add_u64 v[16:17], s[22:23], 2, v[16:17]
	s_lshl_b32 s12, s72, 2
	v_lshl_add_u64 v[16:17], v[16:17], 0, s[12:13]
	global_store_dword v[16:17], v18, off
.LBB0_827:
	s_or_b64 exec, exec, s[26:27]
	v_add_u32_e32 v16, 0xb0, v146
	s_waitcnt lgkmcnt(0)
	v_ashrrev_i32_e32 v17, 31, v16
	v_lshlrev_b64 v[18:19], 12, v[16:17]
	v_lshl_add_u64 v[18:19], s[14:15], 0, v[18:19]
	v_lshl_add_u64 v[26:27], v[144:145], 1, v[18:19]
	s_nop 1
	v_mov_b32_e32 v18, v224
	v_mov_b32_e32 v19, v225
	v_mov_b32_e32 v20, v226
	v_mov_b32_e32 v21, v227
	v_mov_b32_e32 v22, v228
	v_mov_b32_e32 v23, v229
	v_mov_b32_e32 v24, v230
	v_mov_b32_e32 v25, v231
	v_lshlrev_b32_e32 v28, 16, v18
	v_and_b32_e32 v18, 0xffff0000, v18
	v_lshlrev_b32_e32 v29, 16, v19
	v_and_b32_e32 v19, 0xffff0000, v19
	v_lshlrev_b32_e32 v32, 16, v22
	v_and_b32_e32 v22, 0xffff0000, v22
	v_lshlrev_b32_e32 v33, 16, v23
	v_and_b32_e32 v23, 0xffff0000, v23
	v_lshlrev_b32_e32 v30, 16, v20
	v_and_b32_e32 v20, 0xffff0000, v20
	v_lshlrev_b32_e32 v31, 16, v21
	v_and_b32_e32 v21, 0xffff0000, v21
	v_lshlrev_b32_e32 v34, 16, v24
	v_and_b32_e32 v24, 0xffff0000, v24
	v_lshlrev_b32_e32 v35, 16, v25
	v_and_b32_e32 v25, 0xffff0000, v25
	v_add_f32_e32 v13, v13, v18
	v_add_f32_e32 v15, v15, v19
	v_add_f32_e32 v5, v5, v22
	v_add_f32_e32 v7, v7, v23
	v_add_f32_e32 v12, v12, v28
	v_add_f32_e32 v14, v14, v29
	v_add_f32_e32 v9, v9, v20
	v_add_f32_e32 v11, v11, v21
	v_add_f32_e32 v4, v4, v32
	v_add_f32_e32 v6, v6, v33
	v_add_f32_e32 v18, v0, v34
	v_add_f32_e32 v19, v1, v24
	v_add_f32_e32 v20, v2, v35
	v_add_f32_e32 v21, v3, v25
	v_mul_f32_e32 v2, v13, v13
	v_mul_f32_e32 v3, v15, v15
	v_cvt_pk_bf16_f32 v0, v12, v13
	v_cvt_pk_bf16_f32 v1, v14, v15
	v_mul_f32_e32 v13, v5, v5
	v_mul_f32_e32 v15, v7, v7
	v_add_f32_e32 v8, v8, v30
	v_mul_f32_e32 v22, v9, v9
	v_mul_f32_e32 v24, v19, v19
	v_fmac_f32_e32 v2, v12, v12
	v_fmac_f32_e32 v3, v14, v14
	v_fmac_f32_e32 v13, v4, v4
	v_fmac_f32_e32 v15, v6, v6
	v_add_f32_e32 v10, v10, v31
	v_mul_f32_e32 v23, v11, v11
	v_mul_f32_e32 v25, v21, v21
	v_fmac_f32_e32 v22, v8, v8
	v_fmac_f32_e32 v24, v18, v18
	v_add_f32_e32 v2, v2, v3
	v_add_f32_e32 v3, v13, v15
	v_fmac_f32_e32 v23, v10, v10
	v_fmac_f32_e32 v25, v20, v20
	v_add_f32_e32 v2, v22, v2
	v_add_f32_e32 v3, v24, v3
	v_add_f32_e32 v2, v23, v2
	v_add_f32_e32 v3, v25, v3
	v_add_f32_e32 v12, v2, v3
	ds_bpermute_b32 v13, v153, v12
	v_cvt_pk_bf16_f32 v2, v8, v9
	v_cvt_pk_bf16_f32 v3, v10, v11
	global_store_dwordx4 v[26:27], v[0:3], off
	s_waitcnt lgkmcnt(0)
	s_nop 0
	v_add_f32_e32 v0, v12, v13
	ds_bpermute_b32 v1, v152, v0
	v_cvt_pk_bf16_f32 v2, v4, v5
	v_cvt_pk_bf16_f32 v3, v6, v7
	v_cvt_pk_bf16_f32 v4, v18, v19
	v_cvt_pk_bf16_f32 v5, v20, v21
	global_store_dwordx4 v[26:27], v[2:5], off offset:256
	s_and_saveexec_b64 s[26:27], vcc
	s_cbranch_execz .LBB0_829
	s_waitcnt lgkmcnt(0)
	v_add_f32_e32 v2, v0, v1
	v_lshlrev_b64 v[0:1], 7, v[16:17]
	v_lshl_add_u64 v[0:1], s[16:17], 0, v[0:1]
	v_lshl_add_u64 v[0:1], s[22:23], 2, v[0:1]
	s_lshl_b32 s12, s72, 2
	v_lshl_add_u64 v[0:1], v[0:1], 0, s[12:13]
	global_store_dword v[0:1], v2, off

;     __device__ bool next(int i, Unit& u) const { if (!StaticOrder::next(i, u)) return false; u.aoff = (u.pn >> 1) * 512; return true; }
; template <class Epi, class Sched, bool ALIGN_EPI = false, bool SP2 = false>
; __device__ __forceinline__ void gemm_phase(PG8_LAS unsigned char* lds, const Gemm g, const Sched& S, const Epi& E) {
;     ...
;         const bool has_next = S.next(ui + 1, nxt);
;         const char* nA = has_next ? (const char*)g.A + (size_t)nxt.pm * tstepA + nxt.aoff : cA; const char* nB = has_next ? (const char*)g.Bt + (size_t)nxt.pn * tstepB : cB;
;     ...
; #pragma unroll
;         for (int a = 0; a < 2; ++a)
; #pragma unroll
;             for (int b = 0; b < 2; ++b)
; #pragma unroll
;                 for (int m = 0; m < 4; ++m)
; #pragma unroll
;                     for (int n = 0; n < 2; ++n) acc[a][b][m][n] = (f32x4){0.f, 0.f, 0.f, 0.f};
;         cur = nxt; cA = nA; cB = nB; ++ui;
.LBB0_1210:
	s_ashr_i32 s21, s20, 31
	s_lshl_b64 s[4:5], s[20:21], 20
	s_add_u32 s22, s0, s4
	s_addc_u32 s23, s1, s5
	s_and_b64 s[4:5], s[8:9], exec
	s_cselect_b32 s21, s23, s31
	s_cselect_b32 s29, s22, s30
	s_ashr_i32 s19, s18, 31
	s_lshl_b64 s[4:5], s[18:19], 20
	s_add_u32 s26, s3, s4
	s_addc_u32 s27, s24, s5
	s_and_b64 s[4:5], s[8:9], exec
	s_cselect_b32 s19, s27, s35
	s_cselect_b32 s55, s26, s34
	s_add_u32 s30, s30, 0x80080
	s_addc_u32 s31, s31, 0
	s_add_u32 s56, s34, 0x100
	v_mov_b32_e32 v0, 0
	s_addc_u32 s57, s35, 0
	s_mov_b32 s58, -2
	s_waitcnt lgkmcnt(0)
	v_mov_b32_e32 v1, v0
	v_mov_b32_e32 v2, v0
	v_mov_b32_e32 v3, v0
	v_mov_b32_e32 v4, v0
	v_mov_b32_e32 v5, v0
	v_mov_b32_e32 v6, v0
	v_mov_b32_e32 v7, v0
	v_mov_b32_e32 v16, v0
	v_mov_b32_e32 v17, v0
	v_mov_b32_e32 v18, v0
	v_mov_b32_e32 v19, v0
	v_mov_b32_e32 v20, v0
	v_mov_b32_e32 v21, v0
	v_mov_b32_e32 v22, v0
	v_mov_b32_e32 v23, v0
	v_mov_b32_e32 v32, v0
	v_mov_b32_e32 v33, v0
	v_mov_b32_e32 v34, v0
	v_mov_b32_e32 v35, v0
	v_mov_b32_e32 v36, v0
	v_mov_b32_e32 v37, v0
	v_mov_b32_e32 v38, v0
	v_mov_b32_e32 v39, v0
	v_mov_b32_e32 v48, v0
	v_mov_b32_e32 v49, v0
	v_mov_b32_e32 v50, v0
	v_mov_b32_e32 v51, v0
	v_mov_b32_e32 v52, v0
	v_mov_b32_e32 v53, v0
	v_mov_b32_e32 v54, v0
	v_mov_b32_e32 v55, v0
	v_mov_b32_e32 v8, v0
	v_mov_b32_e32 v9, v0
	v_mov_b32_e32 v10, v0
	v_mov_b32_e32 v11, v0
	v_mov_b32_e32 v12, v0
	v_mov_b32_e32 v13, v0
	v_mov_b32_e32 v14, v0
	v_mov_b32_e32 v15, v0
	v_mov_b32_e32 v24, v0
	v_mov_b32_e32 v25, v0
	v_mov_b32_e32 v26, v0
	v_mov_b32_e32 v27, v0
	v_mov_b32_e32 v28, v0
	v_mov_b32_e32 v29, v0
	v_mov_b32_e32 v30, v0
	v_mov_b32_e32 v31, v0
	v_mov_b32_e32 v40, v0
	v_mov_b32_e32 v41, v0
	v_mov_b32_e32 v42, v0
	v_mov_b32_e32 v43, v0
	v_mov_b32_e32 v44, v0
	v_mov_b32_e32 v45, v0
	v_mov_b32_e32 v46, v0
	v_mov_b32_e32 v47, v0
	v_mov_b32_e32 v56, v0
	v_mov_b32_e32 v57, v0
	v_mov_b32_e32 v58, v0
	v_mov_b32_e32 v59, v0
	v_mov_b32_e32 v60, v0
	v_mov_b32_e32 v61, v0
	v_mov_b32_e32 v62, v0
	v_mov_b32_e32 v63, v0
	v_mov_b32_e32 v64, v0
	v_mov_b32_e32 v65, v0
	v_mov_b32_e32 v66, v0
	v_mov_b32_e32 v67, v0
	v_mov_b32_e32 v68, v0
	v_mov_b32_e32 v69, v0
	v_mov_b32_e32 v70, v0
	v_mov_b32_e32 v71, v0
	v_mov_b32_e32 v80, v0
	v_mov_b32_e32 v81, v0
	v_mov_b32_e32 v82, v0
	v_mov_b32_e32 v83, v0
	v_mov_b32_e32 v84, v0
	v_mov_b32_e32 v85, v0
	v_mov_b32_e32 v86, v0
	v_mov_b32_e32 v87, v0
	v_mov_b32_e32 v96, v0
	v_mov_b32_e32 v97, v0
	v_mov_b32_e32 v98, v0
	v_mov_b32_e32 v99, v0
	v_mov_b32_e32 v100, v0
	v_mov_b32_e32 v101, v0
	v_mov_b32_e32 v102, v0
	v_mov_b32_e32 v103, v0
	v_mov_b32_e32 v112, v0
	v_mov_b32_e32 v113, v0
	v_mov_b32_e32 v114, v0
	v_mov_b32_e32 v115, v0
	v_mov_b32_e32 v116, v0
	v_mov_b32_e32 v117, v0
	v_mov_b32_e32 v118, v0
	v_mov_b32_e32 v119, v0
	v_mov_b32_e32 v72, v0
	v_mov_b32_e32 v73, v0
	v_mov_b32_e32 v74, v0
	v_mov_b32_e32 v75, v0
	v_mov_b32_e32 v76, v0
	v_mov_b32_e32 v77, v0
	v_mov_b32_e32 v78, v0
	v_mov_b32_e32 v79, v0
	v_mov_b32_e32 v88, v0
	v_mov_b32_e32 v89, v0
	v_mov_b32_e32 v90, v0
	v_mov_b32_e32 v91, v0
	v_mov_b32_e32 v92, v0
	v_mov_b32_e32 v93, v0
	v_mov_b32_e32 v94, v0
	v_mov_b32_e32 v95, v0
	v_mov_b32_e32 v104, v0
	v_mov_b32_e32 v105, v0
	v_mov_b32_e32 v106, v0
	v_mov_b32_e32 v107, v0
	v_mov_b32_e32 v108, v0
	v_mov_b32_e32 v109, v0
	v_mov_b32_e32 v110, v0
	v_mov_b32_e32 v111, v0
	v_mov_b32_e32 v120, v0
	v_mov_b32_e32 v121, v0
	v_mov_b32_e32 v122, v0
	v_mov_b32_e32 v123, v0
	v_mov_b32_e32 v124, v0
	v_mov_b32_e32 v125, v0
	v_mov_b32_e32 v126, v0
	v_mov_b32_e32 v127, v0
.LBB0_1211:
	ds_read_b128 v[144:147], v149
	ds_read_b128 v[152:155], v149 offset:1024
	ds_read_b128 v[156:159], v149 offset:2048
	ds_read_b128 v[160:163], v149 offset:3072
	ds_read_b128 v[168:171], v150
	ds_read_b128 v[172:175], v150 offset:1024
	ds_read_b128 v[176:179], v150 offset:2048
	ds_read_b128 v[180:183], v150 offset:3072
	s_add_u32 s4, s30, 0xfff80080
	s_addc_u32 s5, s31, -1
	s_cmp_eq_u32 s58, 28
	s_cselect_b32 s37, s21, s5
	s_cselect_b32 s36, s29, s4
	s_cselect_b32 s35, s19, s57
	s_cselect_b32 s34, s55, s56
	v_lshl_add_u64 v[164:165], s[30:31], 0, v[136:137]
	s_add_i32 m0, s25, 0xc000
	ds_read_b128 v[184:187], v151
	ds_read_b128 v[188:191], v151 offset:1024
	ds_read_b128 v[192:195], v151 offset:2048
	ds_read_b128 v[196:199], v151 offset:3072
	ds_read_b128 v[200:203], v151 offset:4096
	ds_read_b128 v[204:207], v151 offset:5120
	ds_read_b128 v[208:211], v151 offset:6144
	ds_read_b128 v[212:215], v151 offset:7168
	global_load_lds_dwordx4 v[164:165], off
	v_lshl_add_u64 v[164:165], s[30:31], 0, v[138:139]
	s_add_i32 m0, s25, 0xe000
	s_nop 0
	global_load_lds_dwordx4 v[164:165], off
	s_waitcnt vmcnt(8)
	s_waitcnt lgkmcnt(0)
	s_barrier
; #define PG8_STAGE(bufoff, gbase, voff) do { _Pragma("unroll") for (int _i = 0; _i < 2; ++_i) \
;         __builtin_amdgcn_global_load_lds((const unsigned*)((const char*)(gbase) + (voff)[_i]), (PG8_LAS unsigned*)(lds + (bufoff) + ldsw + _i * 8192), 16, 0, 0); } while (0)
; #define PG8_LDA(dst, b, h) do { _Pragma("unroll") for (int m = 0; m < 4; ++m) _Pragma("unroll") for (int k = 0; k < 2; ++k) dst[m][k] = *(const PG8_LAS bf16x8*)(lds + PG8_SA(b, h) + aoff + m * 2048 + k * 1024); } while (0)
; #define PG8_LDB(dst, b, h) do { _Pragma("unroll") for (int n = 0; n < 2; ++n) _Pragma("unroll") for (int k = 0; k < 2; ++k) dst[n][k] = *(const PG8_LAS bf16x8*)(lds + PG8_SB(b, h) + boff + n * 2048 + k * 1024); } while (0)
; #define PG8_MMA(ai, bj, At, Bt) do { __builtin_amdgcn_s_setprio(1); _Pragma("unroll") for (int m = 0; m < 4; ++m) _Pragma("unroll") for (int n = 0; n < 2; ++n) _Pragma("unroll") for (int k = 0; k < 2; ++k) \
;         acc[ai][bj][m][n] = __builtin_amdgcn_mfma_f32_16x16x32_bf16(Bt[n][k], At[m][k], acc[ai][bj][m][n], 0, 0, 0); __builtin_amdgcn_s_setprio(0); } while (0)
; #define PG8_WAIT_V(n) asm volatile("s_waitcnt vmcnt(" #n ")" ::: "memory")
; #define PG8_WAIT_L(n) asm volatile("s_waitcnt lgkmcnt(" #n ")" ::: "memory")
; #define PG8_BAR __builtin_amdgcn_s_barrier()
; #define PG8_SCHED __builtin_amdgcn_sched_barrier(0)
; template <class Epi, class Sched, bool ALIGN_EPI = false, bool SP2 = false>
; __device__ __forceinline__ void gemm_phase(PG8_LAS unsigned char* lds, const Gemm g, const Sched& S, const Epi& E) {
;     ...
;             PG8_WAIT_V(8); PG8_WAIT_L(0); PG8_BAR; PG8_MMA(0, 0, At, B0); PG8_MMA(0, 1, At, B1); PG8_BAR; PG8_SCHED;
;             PG8_LDA(At, 0, 1); PG8_STAGE(PG8_SB(0, 0), b2, voffB); PG8_STAGE(PG8_SB(0, 1), b2 + hstepB, voffB); PG8_STAGE(PG8_SA(0, 0), a2, voffA);
;             PG8_WAIT_V(8); PG8_WAIT_L(0); PG8_BAR; PG8_MMA(1, 0, At, B0); PG8_MMA(1, 1, At, B1); PG8_BAR; PG8_SCHED;
;             PG8_LDB(B0, 1, 0); PG8_LDB(B1, 1, 1); PG8_SCHED; PG8_LDA(At, 1, 0); PG8_STAGE(PG8_SA(0, 1), a2 + hstepA, voffA);
;             PG8_WAIT_V(8); PG8_WAIT_L(0); PG8_BAR; PG8_MMA(0, 0, At, B0); PG8_MMA(0, 1, At, B1); PG8_BAR; PG8_SCHED;
	s_setprio 1
	s_waitcnt lgkmcnt(0)
	v_mfma_f32_16x16x32_bf16 v[124:127], v[144:147], v[184:187], v[124:127]
	v_mfma_f32_16x16x32_bf16 v[120:123], v[156:159], v[184:187], v[120:123]
	v_mfma_f32_16x16x32_bf16 v[108:111], v[144:147], v[192:195], v[108:111]
	v_mfma_f32_16x16x32_bf16 v[104:107], v[156:159], v[192:195], v[104:107]
	v_mfma_f32_16x16x32_bf16 v[92:95], v[144:147], v[200:203], v[92:95]
	v_mfma_f32_16x16x32_bf16 v[88:91], v[156:159], v[200:203], v[88:91]
	v_mfma_f32_16x16x32_bf16 v[76:79], v[144:147], v[208:211], v[76:79]
	v_mfma_f32_16x16x32_bf16 v[72:75], v[156:159], v[208:211], v[72:75]
	v_mfma_f32_16x16x32_bf16 v[124:127], v[152:155], v[188:191], v[124:127]
	v_mfma_f32_16x16x32_bf16 v[120:123], v[160:163], v[188:191], v[120:123]
	v_mfma_f32_16x16x32_bf16 v[108:111], v[152:155], v[196:199], v[108:111]
	v_mfma_f32_16x16x32_bf16 v[104:107], v[160:163], v[196:199], v[104:107]
	v_mfma_f32_16x16x32_bf16 v[92:95], v[152:155], v[204:207], v[92:95]
	v_mfma_f32_16x16x32_bf16 v[88:91], v[160:163], v[204:207], v[88:91]
	v_mfma_f32_16x16x32_bf16 v[76:79], v[152:155], v[212:215], v[76:79]
	v_mfma_f32_16x16x32_bf16 v[72:75], v[160:163], v[212:215], v[72:75]
	s_setprio 0
	s_setprio 1
	v_mfma_f32_16x16x32_bf16 v[116:119], v[168:171], v[184:187], v[116:119]
	v_mfma_f32_16x16x32_bf16 v[112:115], v[176:179], v[184:187], v[112:115]
	v_mfma_f32_16x16x32_bf16 v[100:103], v[168:171], v[192:195], v[100:103]
	v_mfma_f32_16x16x32_bf16 v[96:99], v[176:179], v[192:195], v[96:99]
	v_mfma_f32_16x16x32_bf16 v[84:87], v[168:171], v[200:203], v[84:87]
	v_mfma_f32_16x16x32_bf16 v[80:83], v[176:179], v[200:203], v[80:83]
	v_mfma_f32_16x16x32_bf16 v[68:71], v[168:171], v[208:211], v[68:71]
	v_mfma_f32_16x16x32_bf16 v[64:67], v[176:179], v[208:211], v[64:67]
	v_mfma_f32_16x16x32_bf16 v[116:119], v[172:175], v[188:191], v[116:119]
	v_mfma_f32_16x16x32_bf16 v[112:115], v[180:183], v[188:191], v[112:115]
	v_mfma_f32_16x16x32_bf16 v[100:103], v[172:175], v[196:199], v[100:103]
	v_mfma_f32_16x16x32_bf16 v[96:99], v[180:183], v[196:199], v[96:99]
	v_mfma_f32_16x16x32_bf16 v[84:87], v[172:175], v[204:207], v[84:87]
	v_mfma_f32_16x16x32_bf16 v[80:83], v[180:183], v[204:207], v[80:83]
	v_mfma_f32_16x16x32_bf16 v[68:71], v[172:175], v[212:215], v[68:71]
	v_mfma_f32_16x16x32_bf16 v[64:67], v[180:183], v[212:215], v[64:67]
	s_setprio 0
	s_barrier
	s_add_i32 s4, s44, s47
	v_lshl_add_u64 v[164:165], s[34:35], 0, v[130:131]
	s_mov_b32 m0, s4
	ds_read_b128 v[184:187], v151 offset:16384
	ds_read_b128 v[188:191], v151 offset:17408
	ds_read_b128 v[192:195], v151 offset:18432
	ds_read_b128 v[196:199], v151 offset:19456
	ds_read_b128 v[200:203], v151 offset:20480
	ds_read_b128 v[204:207], v151 offset:21504
	ds_read_b128 v[208:211], v151 offset:22528
	ds_read_b128 v[212:215], v151 offset:23552
	global_load_lds_dwordx4 v[164:165], off
	s_add_i32 m0, s4, 0x2000
	s_add_u32 s4, s34, 0x80000
	v_lshl_add_u64 v[216:217], s[34:35], 0, v[134:135]
	s_addc_u32 s5, s35, 0
	s_add_i32 s59, s45, s47
	global_load_lds_dwordx4 v[216:217], off
	v_lshl_add_u64 v[218:219], s[4:5], 0, v[130:131]
	s_mov_b32 m0, s59
	v_lshl_add_u64 v[220:221], s[36:37], 0, v[132:133]
	global_load_lds_dwordx4 v[218:219], off
	v_lshl_add_u64 v[218:219], s[4:5], 0, v[134:135]
	s_add_i32 m0, s59, 0x2000
	s_nop 0
	global_load_lds_dwordx4 v[218:219], off
	v_lshl_add_u64 v[218:219], s[36:37], 0, v[128:129]
	s_mov_b32 m0, s25
	s_nop 0
	global_load_lds_dwordx4 v[218:219], off
	s_mov_b32 m0, s33
	s_nop 0
	global_load_lds_dwordx4 v[220:221], off
	s_waitcnt vmcnt(8)
	s_waitcnt lgkmcnt(0)
	s_barrier
	s_setprio 1
	s_waitcnt lgkmcnt(0)
	v_mfma_f32_16x16x32_bf16 v[60:63], v[144:147], v[184:187], v[60:63]
	v_mfma_f32_16x16x32_bf16 v[56:59], v[156:159], v[184:187], v[56:59]
	v_mfma_f32_16x16x32_bf16 v[44:47], v[144:147], v[192:195], v[44:47]
	v_mfma_f32_16x16x32_bf16 v[40:43], v[156:159], v[192:195], v[40:43]
	v_mfma_f32_16x16x32_bf16 v[28:31], v[144:147], v[200:203], v[28:31]
	v_mfma_f32_16x16x32_bf16 v[24:27], v[156:159], v[200:203], v[24:27]
	v_mfma_f32_16x16x32_bf16 v[12:15], v[144:147], v[208:211], v[12:15]
	v_mfma_f32_16x16x32_bf16 v[8:11], v[156:159], v[208:211], v[8:11]
	v_mfma_f32_16x16x32_bf16 v[60:63], v[152:155], v[188:191], v[60:63]
	v_mfma_f32_16x16x32_bf16 v[56:59], v[160:163], v[188:191], v[56:59]
	v_mfma_f32_16x16x32_bf16 v[44:47], v[152:155], v[196:199], v[44:47]
	v_mfma_f32_16x16x32_bf16 v[40:43], v[160:163], v[196:199], v[40:43]
	v_mfma_f32_16x16x32_bf16 v[28:31], v[152:155], v[204:207], v[28:31]
	v_mfma_f32_16x16x32_bf16 v[24:27], v[160:163], v[204:207], v[24:27]
	v_mfma_f32_16x16x32_bf16 v[12:15], v[152:155], v[212:215], v[12:15]
	v_mfma_f32_16x16x32_bf16 v[8:11], v[160:163], v[212:215], v[8:11]
	s_setprio 0
	s_setprio 1
	v_mfma_f32_16x16x32_bf16 v[52:55], v[168:171], v[184:187], v[52:55]
	v_mfma_f32_16x16x32_bf16 v[48:51], v[176:179], v[184:187], v[48:51]
	v_mfma_f32_16x16x32_bf16 v[36:39], v[168:171], v[192:195], v[36:39]
	v_mfma_f32_16x16x32_bf16 v[32:35], v[176:179], v[192:195], v[32:35]
	v_mfma_f32_16x16x32_bf16 v[20:23], v[168:171], v[200:203], v[20:23]
	v_mfma_f32_16x16x32_bf16 v[16:19], v[176:179], v[200:203], v[16:19]
	v_mfma_f32_16x16x32_bf16 v[4:7], v[168:171], v[208:211], v[4:7]
	v_mfma_f32_16x16x32_bf16 v[0:3], v[176:179], v[208:211], v[0:3]
	v_mfma_f32_16x16x32_bf16 v[52:55], v[172:175], v[188:191], v[52:55]
	v_mfma_f32_16x16x32_bf16 v[48:51], v[180:183], v[188:191], v[48:51]
	v_mfma_f32_16x16x32_bf16 v[36:39], v[172:175], v[196:199], v[36:39]
	v_mfma_f32_16x16x32_bf16 v[32:35], v[180:183], v[196:199], v[32:35]
	v_mfma_f32_16x16x32_bf16 v[20:23], v[172:175], v[204:207], v[20:23]
	v_mfma_f32_16x16x32_bf16 v[16:19], v[180:183], v[204:207], v[16:19]
	v_mfma_f32_16x16x32_bf16 v[4:7], v[172:175], v[212:215], v[4:7]
	v_mfma_f32_16x16x32_bf16 v[0:3], v[180:183], v[212:215], v[0:3]
	s_setprio 0
	s_barrier
; #define PG8_STAGE(bufoff, gbase, voff) do { _Pragma("unroll") for (int _i = 0; _i < 2; ++_i) \
;         __builtin_amdgcn_global_load_lds((const unsigned*)((const char*)(gbase) + (voff)[_i]), (PG8_LAS unsigned*)(lds + (bufoff) + ldsw + _i * 8192), 16, 0, 0); } while (0)
; #define PG8_LDA(dst, b, h) do { _Pragma("unroll") for (int m = 0; m < 4; ++m) _Pragma("unroll") for (int k = 0; k < 2; ++k) dst[m][k] = *(const PG8_LAS bf16x8*)(lds + PG8_SA(b, h) + aoff + m * 2048 + k * 1024); } while (0)
; #define PG8_LDB(dst, b, h) do { _Pragma("unroll") for (int n = 0; n < 2; ++n) _Pragma("unroll") for (int k = 0; k < 2; ++k) dst[n][k] = *(const PG8_LAS bf16x8*)(lds + PG8_SB(b, h) + boff + n * 2048 + k * 1024); } while (0)
; #define PG8_MMA(ai, bj, At, Bt) do { __builtin_amdgcn_s_setprio(1); _Pragma("unroll") for (int m = 0; m < 4; ++m) _Pragma("unroll") for (int n = 0; n < 2; ++n) _Pragma("unroll") for (int k = 0; k < 2; ++k) \
;         acc[ai][bj][m][n] = __builtin_amdgcn_mfma_f32_16x16x32_bf16(Bt[n][k], At[m][k], acc[ai][bj][m][n], 0, 0, 0); __builtin_amdgcn_s_setprio(0); } while (0)
; #define PG8_WAIT_V(n) asm volatile("s_waitcnt vmcnt(" #n ")" ::: "memory")
; #define PG8_WAIT_L(n) asm volatile("s_waitcnt lgkmcnt(" #n ")" ::: "memory")
; #define PG8_BAR __builtin_amdgcn_s_barrier()
; #define PG8_SCHED __builtin_amdgcn_sched_barrier(0)
; template <class Epi, class Sched, bool ALIGN_EPI = false, bool SP2 = false>
; __device__ __forceinline__ void gemm_phase(PG8_LAS unsigned char* lds, const Gemm g, const Sched& S, const Epi& E) {
;     ...
;             PG8_LDB(B0, 1, 0); PG8_LDB(B1, 1, 1); PG8_SCHED; PG8_LDA(At, 1, 0); PG8_STAGE(PG8_SA(0, 1), a2 + hstepA, voffA);
;             PG8_WAIT_V(8); PG8_WAIT_L(0); PG8_BAR; PG8_MMA(0, 0, At, B0); PG8_MMA(0, 1, At, B1); PG8_BAR; PG8_SCHED;
	s_add_i32 s59, 0, 0x18000
	s_add_i32 s60, 0, 0x1c000
	v_add_u32_e32 v160, s59, v148
	v_add_u32_e32 v166, s60, v148
	ds_read_b128 v[144:147], v160
	ds_read_b128 v[152:155], v160 offset:1024
	ds_read_b128 v[156:159], v160 offset:2048
	ds_read_b128 v[160:163], v160 offset:3072
	ds_read_b128 v[168:171], v166
	ds_read_b128 v[172:175], v166 offset:1024
	ds_read_b128 v[176:179], v166 offset:2048
	ds_read_b128 v[180:183], v166 offset:3072
	s_add_u32 s4, s36, 0x80000
	s_addc_u32 s5, s37, 0
	s_mov_b32 m0, s38
	v_lshl_add_u64 v[222:223], s[4:5], 0, v[128:129]
	ds_read_b128 v[184:187], v151 offset:32768
	ds_read_b128 v[188:191], v151 offset:33792
	ds_read_b128 v[192:195], v151 offset:34816
	ds_read_b128 v[196:199], v151 offset:35840
	ds_read_b128 v[200:203], v151 offset:36864
	ds_read_b128 v[204:207], v151 offset:37888
	ds_read_b128 v[208:211], v151 offset:38912
	ds_read_b128 v[212:215], v151 offset:39936
	global_load_lds_dwordx4 v[222:223], off
	v_lshl_add_u64 v[222:223], s[4:5], 0, v[132:133]
	s_mov_b32 m0, s39
	s_nop 0
	global_load_lds_dwordx4 v[222:223], off
	s_waitcnt vmcnt(8)
	s_waitcnt lgkmcnt(0)
	s_barrier
	s_setprio 1
	s_waitcnt lgkmcnt(0)
	v_mfma_f32_16x16x32_bf16 v[124:127], v[144:147], v[184:187], v[124:127]
	v_mfma_f32_16x16x32_bf16 v[120:123], v[156:159], v[184:187], v[120:123]
	v_mfma_f32_16x16x32_bf16 v[108:111], v[144:147], v[192:195], v[108:111]
	v_mfma_f32_16x16x32_bf16 v[104:107], v[156:159], v[192:195], v[104:107]
	v_mfma_f32_16x16x32_bf16 v[92:95], v[144:147], v[200:203], v[92:95]
	v_mfma_f32_16x16x32_bf16 v[88:91], v[156:159], v[200:203], v[88:91]
	v_mfma_f32_16x16x32_bf16 v[76:79], v[144:147], v[208:211], v[76:79]
	v_mfma_f32_16x16x32_bf16 v[72:75], v[156:159], v[208:211], v[72:75]
	v_mfma_f32_16x16x32_bf16 v[124:127], v[152:155], v[188:191], v[124:127]
	v_mfma_f32_16x16x32_bf16 v[120:123], v[160:163], v[188:191], v[120:123]
	v_mfma_f32_16x16x32_bf16 v[108:111], v[152:155], v[196:199], v[108:111]
	v_mfma_f32_16x16x32_bf16 v[104:107], v[160:163], v[196:199], v[104:107]
	v_mfma_f32_16x16x32_bf16 v[92:95], v[152:155], v[204:207], v[92:95]
	v_mfma_f32_16x16x32_bf16 v[88:91], v[160:163], v[204:207], v[88:91]
	v_mfma_f32_16x16x32_bf16 v[76:79], v[152:155], v[212:215], v[76:79]
	v_mfma_f32_16x16x32_bf16 v[72:75], v[160:163], v[212:215], v[72:75]
	s_setprio 0
	s_setprio 1
	v_mfma_f32_16x16x32_bf16 v[116:119], v[168:171], v[184:187], v[116:119]
	v_mfma_f32_16x16x32_bf16 v[112:115], v[176:179], v[184:187], v[112:115]
	v_mfma_f32_16x16x32_bf16 v[100:103], v[168:171], v[192:195], v[100:103]
	v_mfma_f32_16x16x32_bf16 v[96:99], v[176:179], v[192:195], v[96:99]
	v_mfma_f32_16x16x32_bf16 v[84:87], v[168:171], v[200:203], v[84:87]
	v_mfma_f32_16x16x32_bf16 v[80:83], v[176:179], v[200:203], v[80:83]
	v_mfma_f32_16x16x32_bf16 v[68:71], v[168:171], v[208:211], v[68:71]
	v_mfma_f32_16x16x32_bf16 v[64:67], v[176:179], v[208:211], v[64:67]
	v_mfma_f32_16x16x32_bf16 v[116:119], v[172:175], v[188:191], v[116:119]
	v_mfma_f32_16x16x32_bf16 v[112:115], v[180:183], v[188:191], v[112:115]
	v_mfma_f32_16x16x32_bf16 v[100:103], v[172:175], v[196:199], v[100:103]
	v_mfma_f32_16x16x32_bf16 v[96:99], v[180:183], v[196:199], v[96:99]
	v_mfma_f32_16x16x32_bf16 v[84:87], v[172:175], v[204:207], v[84:87]
	v_mfma_f32_16x16x32_bf16 v[80:83], v[180:183], v[204:207], v[80:83]
	v_mfma_f32_16x16x32_bf16 v[68:71], v[172:175], v[212:215], v[68:71]
	v_mfma_f32_16x16x32_bf16 v[64:67], v[180:183], v[212:215], v[64:67]
	s_setprio 0
	s_barrier
; #define PG8_STAGE(bufoff, gbase, voff) do { _Pragma("unroll") for (int _i = 0; _i < 2; ++_i) \
;         __builtin_amdgcn_global_load_lds((const unsigned*)((const char*)(gbase) + (voff)[_i]), (PG8_LAS unsigned*)(lds + (bufoff) + ldsw + _i * 8192), 16, 0, 0); } while (0)
; #define PG8_LDA(dst, b, h) do { _Pragma("unroll") for (int m = 0; m < 4; ++m) _Pragma("unroll") for (int k = 0; k < 2; ++k) dst[m][k] = *(const PG8_LAS bf16x8*)(lds + PG8_SA(b, h) + aoff + m * 2048 + k * 1024); } while (0)
; #define PG8_MMA(ai, bj, At, Bt) do { __builtin_amdgcn_s_setprio(1); _Pragma("unroll") for (int m = 0; m < 4; ++m) _Pragma("unroll") for (int n = 0; n < 2; ++n) _Pragma("unroll") for (int k = 0; k < 2; ++k) \
;         acc[ai][bj][m][n] = __builtin_amdgcn_mfma_f32_16x16x32_bf16(Bt[n][k], At[m][k], acc[ai][bj][m][n], 0, 0, 0); __builtin_amdgcn_s_setprio(0); } while (0)
; #define PG8_WAIT_V(n) asm volatile("s_waitcnt vmcnt(" #n ")" ::: "memory")
; #define PG8_WAIT_L(n) asm volatile("s_waitcnt lgkmcnt(" #n ")" ::: "memory")
; #define PG8_BAR __builtin_amdgcn_s_barrier()
; #define PG8_SCHED __builtin_amdgcn_sched_barrier(0)
; template <class Epi, class Sched, bool ALIGN_EPI = false, bool SP2 = false>
; __device__ __forceinline__ void gemm_phase(PG8_LAS unsigned char* lds, const Gemm g, const Sched& S, const Epi& E) {
;     ...
;             PG8_LDA(At, 1, 1); PG8_STAGE(PG8_SB(1, 0), b3, voffB); PG8_STAGE(PG8_SB(1, 1), b3 + hstepB, voffB); PG8_STAGE(PG8_SA(1, 0), a3, voffA);
;             PG8_WAIT_V(8); PG8_WAIT_L(0); PG8_BAR; PG8_MMA(1, 0, At, B0); PG8_MMA(1, 1, At, B1); PG8_BAR; PG8_SCHED;
;     ...
;         if constexpr (ALIGN_EPI) { if (wr == 0) PG8_BAR; }
	s_add_i32 s4, s59, s47
	v_lshl_add_u64 v[164:165], v[164:165], 0, s[16:17]
	s_mov_b32 m0, s4
	ds_read_b128 v[184:187], v151 offset:49152
	ds_read_b128 v[188:191], v151 offset:50176
	ds_read_b128 v[192:195], v151 offset:51200
	ds_read_b128 v[196:199], v151 offset:52224
	ds_read_b128 v[200:203], v151 offset:53248
	ds_read_b128 v[204:207], v151 offset:54272
	ds_read_b128 v[208:211], v151 offset:55296
	ds_read_b128 v[212:215], v151 offset:56320
	global_load_lds_dwordx4 v[164:165], off
	s_add_i32 m0, s4, 0x2000
	s_add_u32 s4, s34, 0x80080
	v_lshl_add_u64 v[164:165], v[216:217], 0, s[16:17]
	s_addc_u32 s5, s35, 0
	s_add_i32 s34, s60, s47
	global_load_lds_dwordx4 v[164:165], off
	v_lshl_add_u64 v[164:165], s[4:5], 0, v[130:131]
	s_mov_b32 m0, s34
	s_nop 0
	global_load_lds_dwordx4 v[164:165], off
	v_lshl_add_u64 v[164:165], s[4:5], 0, v[134:135]
	s_add_i32 m0, s34, 0x2000
	s_nop 0
	global_load_lds_dwordx4 v[164:165], off
	v_lshl_add_u64 v[164:165], v[218:219], 0, s[16:17]
	s_mov_b32 m0, s40
	s_nop 0
	global_load_lds_dwordx4 v[164:165], off
	v_lshl_add_u64 v[164:165], v[220:221], 0, s[16:17]
	s_mov_b32 m0, s41
	s_nop 0
	global_load_lds_dwordx4 v[164:165], off
	s_waitcnt vmcnt(8)
	s_waitcnt lgkmcnt(0)
	s_barrier
	s_setprio 1
	s_waitcnt lgkmcnt(0)
	v_mfma_f32_16x16x32_bf16 v[60:63], v[144:147], v[184:187], v[60:63]
	v_mfma_f32_16x16x32_bf16 v[56:59], v[156:159], v[184:187], v[56:59]
	v_mfma_f32_16x16x32_bf16 v[44:47], v[144:147], v[192:195], v[44:47]
	v_mfma_f32_16x16x32_bf16 v[40:43], v[156:159], v[192:195], v[40:43]
	v_mfma_f32_16x16x32_bf16 v[28:31], v[144:147], v[200:203], v[28:31]
	v_mfma_f32_16x16x32_bf16 v[24:27], v[156:159], v[200:203], v[24:27]
	v_mfma_f32_16x16x32_bf16 v[12:15], v[144:147], v[208:211], v[12:15]
	v_mfma_f32_16x16x32_bf16 v[8:11], v[156:159], v[208:211], v[8:11]
	v_mfma_f32_16x16x32_bf16 v[60:63], v[152:155], v[188:191], v[60:63]
	v_mfma_f32_16x16x32_bf16 v[56:59], v[160:163], v[188:191], v[56:59]
	v_mfma_f32_16x16x32_bf16 v[44:47], v[152:155], v[196:199], v[44:47]
	v_mfma_f32_16x16x32_bf16 v[40:43], v[160:163], v[196:199], v[40:43]
	v_mfma_f32_16x16x32_bf16 v[28:31], v[152:155], v[204:207], v[28:31]
	v_mfma_f32_16x16x32_bf16 v[24:27], v[160:163], v[204:207], v[24:27]
	v_mfma_f32_16x16x32_bf16 v[12:15], v[152:155], v[212:215], v[12:15]
	v_mfma_f32_16x16x32_bf16 v[8:11], v[160:163], v[212:215], v[8:11]
	s_setprio 0
	s_setprio 1
	v_mfma_f32_16x16x32_bf16 v[52:55], v[168:171], v[184:187], v[52:55]
	v_mfma_f32_16x16x32_bf16 v[48:51], v[176:179], v[184:187], v[48:51]
	v_mfma_f32_16x16x32_bf16 v[36:39], v[168:171], v[192:195], v[36:39]
	v_mfma_f32_16x16x32_bf16 v[32:35], v[176:179], v[192:195], v[32:35]
	v_mfma_f32_16x16x32_bf16 v[20:23], v[168:171], v[200:203], v[20:23]
	v_mfma_f32_16x16x32_bf16 v[16:19], v[176:179], v[200:203], v[16:19]
	v_mfma_f32_16x16x32_bf16 v[4:7], v[168:171], v[208:211], v[4:7]
	v_mfma_f32_16x16x32_bf16 v[0:3], v[176:179], v[208:211], v[0:3]
	v_mfma_f32_16x16x32_bf16 v[52:55], v[172:175], v[188:191], v[52:55]
	v_mfma_f32_16x16x32_bf16 v[48:51], v[180:183], v[188:191], v[48:51]
	v_mfma_f32_16x16x32_bf16 v[36:39], v[172:175], v[196:199], v[36:39]
	v_mfma_f32_16x16x32_bf16 v[32:35], v[180:183], v[196:199], v[32:35]
	v_mfma_f32_16x16x32_bf16 v[20:23], v[172:175], v[204:207], v[20:23]
	v_mfma_f32_16x16x32_bf16 v[16:19], v[180:183], v[204:207], v[16:19]
	v_mfma_f32_16x16x32_bf16 v[4:7], v[172:175], v[212:215], v[4:7]
	v_mfma_f32_16x16x32_bf16 v[0:3], v[180:183], v[212:215], v[0:3]
	s_setprio 0
	s_barrier
	s_add_i32 s58, s58, 2
	s_add_u32 s30, s30, 0x100
	s_addc_u32 s31, s31, 0
	s_add_u32 s56, s56, 0x100
	s_addc_u32 s57, s57, 0
	s_cmp_gt_u32 s58, 29
	s_cbranch_scc0 .LBB0_1211
	s_and_b64 vcc, exec, s[48:49]
	s_cbranch_vccz .LBB0_1214
	s_barrier

; #define PG8_STAGE(bufoff, gbase, voff) do { _Pragma("unroll") for (int _i = 0; _i < 2; ++_i) \
;         __builtin_amdgcn_global_load_lds((const unsigned*)((const char*)(gbase) + (voff)[_i]), (PG8_LAS unsigned*)(lds + (bufoff) + ldsw + _i * 8192), 16, 0, 0); } while (0)
; #define PG8_LDA(dst, b, h) do { _Pragma("unroll") for (int m = 0; m < 4; ++m) _Pragma("unroll") for (int k = 0; k < 2; ++k) dst[m][k] = *(const PG8_LAS bf16x8*)(lds + PG8_SA(b, h) + aoff + m * 2048 + k * 1024); } while (0)
; #define PG8_LDB(dst, b, h) do { _Pragma("unroll") for (int n = 0; n < 2; ++n) _Pragma("unroll") for (int k = 0; k < 2; ++k) dst[n][k] = *(const PG8_LAS bf16x8*)(lds + PG8_SB(b, h) + boff + n * 2048 + k * 1024); } while (0)
; #define PG8_MMA(ai, bj, At, Bt) do { __builtin_amdgcn_s_setprio(1); _Pragma("unroll") for (int m = 0; m < 4; ++m) _Pragma("unroll") for (int n = 0; n < 2; ++n) _Pragma("unroll") for (int k = 0; k < 2; ++k) \
;         acc[ai][bj][m][n] = __builtin_amdgcn_mfma_f32_16x16x32_bf16(Bt[n][k], At[m][k], acc[ai][bj][m][n], 0, 0, 0); __builtin_amdgcn_s_setprio(0); } while (0)
; #define PG8_WAIT_V(n) asm volatile("s_waitcnt vmcnt(" #n ")" ::: "memory")
; #define PG8_WAIT_L(n) asm volatile("s_waitcnt lgkmcnt(" #n ")" ::: "memory")
; #define PG8_BAR __builtin_amdgcn_s_barrier()
; #define PG8_SCHED __builtin_amdgcn_sched_barrier(0)
; template <class Epi, class Sched, bool ALIGN_EPI = false, bool SP2 = false>
; __device__ __forceinline__ void gemm_phase(PG8_LAS unsigned char* lds, const Gemm g, const Sched& S, const Epi& E) {
;     ...
;             PG8_LDB(B0, 0, 0); PG8_LDB(B1, 0, 1); PG8_SCHED; PG8_LDA(At, 0, 0); PG8_STAGE(PG8_SA(1, 1), a1 + hstepA, voffA);
;             PG8_WAIT_V(8); PG8_WAIT_L(0); PG8_BAR; PG8_MMA(0, 0, At, B0); PG8_MMA(0, 1, At, B1); PG8_BAR; PG8_SCHED;
;     ...
; #pragma unroll
;         for (int a = 0; a < 2; ++a)
; #pragma unroll
;             for (int b = 0; b < 2; ++b)
; #pragma unroll
;                 for (int m = 0; m < 4; ++m)
; #pragma unroll
;                     for (int n = 0; n < 2; ++n) acc[a][b][m][n] = (f32x4){0.f, 0.f, 0.f, 0.f};
;         cur = nxt; cA = nA; cB = nB; ++ui;
.LBB0_1360:
	s_add_u32 s45, s22, 0x100
	v_mov_b32_e32 v0, 0
	s_addc_u32 s46, s23, 0
	s_mov_b32 s50, -2
	s_waitcnt lgkmcnt(0)
	v_mov_b32_e32 v1, v0
	v_mov_b32_e32 v2, v0
	v_mov_b32_e32 v3, v0
	v_mov_b32_e32 v4, v0
	v_mov_b32_e32 v5, v0
	v_mov_b32_e32 v6, v0
	v_mov_b32_e32 v7, v0
	v_mov_b32_e32 v16, v0
	v_mov_b32_e32 v17, v0
	v_mov_b32_e32 v18, v0
	v_mov_b32_e32 v19, v0
	v_mov_b32_e32 v20, v0
	v_mov_b32_e32 v21, v0
	v_mov_b32_e32 v22, v0
	v_mov_b32_e32 v23, v0
	v_mov_b32_e32 v32, v0
	v_mov_b32_e32 v33, v0
	v_mov_b32_e32 v34, v0
	v_mov_b32_e32 v35, v0
	v_mov_b32_e32 v36, v0
	v_mov_b32_e32 v37, v0
	v_mov_b32_e32 v38, v0
	v_mov_b32_e32 v39, v0
	v_mov_b32_e32 v48, v0
	v_mov_b32_e32 v49, v0
	v_mov_b32_e32 v50, v0
	v_mov_b32_e32 v51, v0
	v_mov_b32_e32 v52, v0
	v_mov_b32_e32 v53, v0
	v_mov_b32_e32 v54, v0
	v_mov_b32_e32 v55, v0
	v_mov_b32_e32 v8, v0
	v_mov_b32_e32 v9, v0
	v_mov_b32_e32 v10, v0
	v_mov_b32_e32 v11, v0
	v_mov_b32_e32 v12, v0
	v_mov_b32_e32 v13, v0
	v_mov_b32_e32 v14, v0
	v_mov_b32_e32 v15, v0
	v_mov_b32_e32 v24, v0
	v_mov_b32_e32 v25, v0
	v_mov_b32_e32 v26, v0
	v_mov_b32_e32 v27, v0
	v_mov_b32_e32 v28, v0
	v_mov_b32_e32 v29, v0
	v_mov_b32_e32 v30, v0
	v_mov_b32_e32 v31, v0
	v_mov_b32_e32 v40, v0
	v_mov_b32_e32 v41, v0
	v_mov_b32_e32 v42, v0
	v_mov_b32_e32 v43, v0
	v_mov_b32_e32 v44, v0
	v_mov_b32_e32 v45, v0
	v_mov_b32_e32 v46, v0
	v_mov_b32_e32 v47, v0
	v_mov_b32_e32 v56, v0
	v_mov_b32_e32 v57, v0
	v_mov_b32_e32 v58, v0
	v_mov_b32_e32 v59, v0
	v_mov_b32_e32 v60, v0
	v_mov_b32_e32 v61, v0
	v_mov_b32_e32 v62, v0
	v_mov_b32_e32 v63, v0
	v_mov_b32_e32 v64, v0
	v_mov_b32_e32 v65, v0
	v_mov_b32_e32 v66, v0
	v_mov_b32_e32 v67, v0
	v_mov_b32_e32 v68, v0
	v_mov_b32_e32 v69, v0
	v_mov_b32_e32 v70, v0
	v_mov_b32_e32 v71, v0
	v_mov_b32_e32 v80, v0
	v_mov_b32_e32 v81, v0
	v_mov_b32_e32 v82, v0
	v_mov_b32_e32 v83, v0
	v_mov_b32_e32 v84, v0
	v_mov_b32_e32 v85, v0
	v_mov_b32_e32 v86, v0
	v_mov_b32_e32 v87, v0
	v_mov_b32_e32 v96, v0
	v_mov_b32_e32 v97, v0
	v_mov_b32_e32 v98, v0
	v_mov_b32_e32 v99, v0
	v_mov_b32_e32 v100, v0
	v_mov_b32_e32 v101, v0
	v_mov_b32_e32 v102, v0
	v_mov_b32_e32 v103, v0
	v_mov_b32_e32 v112, v0
	v_mov_b32_e32 v113, v0
	v_mov_b32_e32 v114, v0
	v_mov_b32_e32 v115, v0
	v_mov_b32_e32 v116, v0
	v_mov_b32_e32 v117, v0
	v_mov_b32_e32 v118, v0
	v_mov_b32_e32 v119, v0
	v_mov_b32_e32 v72, v0
	v_mov_b32_e32 v73, v0
	v_mov_b32_e32 v74, v0
	v_mov_b32_e32 v75, v0
	v_mov_b32_e32 v76, v0
	v_mov_b32_e32 v77, v0
	v_mov_b32_e32 v78, v0
	v_mov_b32_e32 v79, v0
	v_mov_b32_e32 v88, v0
	v_mov_b32_e32 v89, v0
	v_mov_b32_e32 v90, v0
	v_mov_b32_e32 v91, v0
	v_mov_b32_e32 v92, v0
	v_mov_b32_e32 v93, v0
	v_mov_b32_e32 v94, v0
	v_mov_b32_e32 v95, v0
	v_mov_b32_e32 v104, v0
	v_mov_b32_e32 v105, v0
	v_mov_b32_e32 v106, v0
	v_mov_b32_e32 v107, v0
	v_mov_b32_e32 v108, v0
	v_mov_b32_e32 v109, v0
	v_mov_b32_e32 v110, v0
	v_mov_b32_e32 v111, v0
	v_mov_b32_e32 v120, v0
	v_mov_b32_e32 v121, v0
	v_mov_b32_e32 v122, v0
	v_mov_b32_e32 v123, v0
	v_mov_b32_e32 v124, v0
	v_mov_b32_e32 v125, v0
	v_mov_b32_e32 v126, v0
	v_mov_b32_e32 v127, v0
.LBB0_1361:
	ds_read_b128 v[144:147], v149
	ds_read_b128 v[152:155], v149 offset:1024
	ds_read_b128 v[156:159], v149 offset:2048
	ds_read_b128 v[160:163], v149 offset:3072
	ds_read_b128 v[168:171], v150
	ds_read_b128 v[172:175], v150 offset:1024
	ds_read_b128 v[176:179], v150 offset:2048
	ds_read_b128 v[180:183], v150 offset:3072
	s_add_u32 s22, s20, 0x100
	s_addc_u32 s23, s21, 0
	s_cmpk_eq_i32 s50, 0x54
	s_cselect_b32 s29, s9, s23
	s_cselect_b32 s28, s8, s22
	s_cselect_b32 s27, s19, s46
	s_cselect_b32 s26, s18, s45
	v_lshl_add_u64 v[164:165], s[20:21], 0, v[136:137]
	s_add_i32 m0, s25, 0xc000
	ds_read_b128 v[184:187], v151
	ds_read_b128 v[188:191], v151 offset:1024
	ds_read_b128 v[192:195], v151 offset:2048
	ds_read_b128 v[196:199], v151 offset:3072
	ds_read_b128 v[200:203], v151 offset:4096
	ds_read_b128 v[204:207], v151 offset:5120
	ds_read_b128 v[208:211], v151 offset:6144
	ds_read_b128 v[212:215], v151 offset:7168
	global_load_lds_dwordx4 v[164:165], off
	v_lshl_add_u64 v[164:165], s[20:21], 0, v[138:139]
	s_add_i32 m0, s25, 0xe000
	s_nop 0
	global_load_lds_dwordx4 v[164:165], off
	s_waitcnt vmcnt(8)
	s_waitcnt lgkmcnt(0)
	s_barrier
	s_setprio 1
	s_waitcnt lgkmcnt(0)
	v_mfma_f32_16x16x32_bf16 v[124:127], v[144:147], v[184:187], v[124:127]
	v_mfma_f32_16x16x32_bf16 v[120:123], v[156:159], v[184:187], v[120:123]
	v_mfma_f32_16x16x32_bf16 v[108:111], v[144:147], v[192:195], v[108:111]
	v_mfma_f32_16x16x32_bf16 v[104:107], v[156:159], v[192:195], v[104:107]
	v_mfma_f32_16x16x32_bf16 v[92:95], v[144:147], v[200:203], v[92:95]
	v_mfma_f32_16x16x32_bf16 v[88:91], v[156:159], v[200:203], v[88:91]
	v_mfma_f32_16x16x32_bf16 v[76:79], v[144:147], v[208:211], v[76:79]
	v_mfma_f32_16x16x32_bf16 v[72:75], v[156:159], v[208:211], v[72:75]
	v_mfma_f32_16x16x32_bf16 v[124:127], v[152:155], v[188:191], v[124:127]
	v_mfma_f32_16x16x32_bf16 v[120:123], v[160:163], v[188:191], v[120:123]
	v_mfma_f32_16x16x32_bf16 v[108:111], v[152:155], v[196:199], v[108:111]
	v_mfma_f32_16x16x32_bf16 v[104:107], v[160:163], v[196:199], v[104:107]
	v_mfma_f32_16x16x32_bf16 v[92:95], v[152:155], v[204:207], v[92:95]
	v_mfma_f32_16x16x32_bf16 v[88:91], v[160:163], v[204:207], v[88:91]
	v_mfma_f32_16x16x32_bf16 v[76:79], v[152:155], v[212:215], v[76:79]
	v_mfma_f32_16x16x32_bf16 v[72:75], v[160:163], v[212:215], v[72:75]
	s_setprio 0
	s_setprio 1
	v_mfma_f32_16x16x32_bf16 v[116:119], v[168:171], v[184:187], v[116:119]
	v_mfma_f32_16x16x32_bf16 v[112:115], v[176:179], v[184:187], v[112:115]
	v_mfma_f32_16x16x32_bf16 v[100:103], v[168:171], v[192:195], v[100:103]
	v_mfma_f32_16x16x32_bf16 v[96:99], v[176:179], v[192:195], v[96:99]
	v_mfma_f32_16x16x32_bf16 v[84:87], v[168:171], v[200:203], v[84:87]
	v_mfma_f32_16x16x32_bf16 v[80:83], v[176:179], v[200:203], v[80:83]
	v_mfma_f32_16x16x32_bf16 v[68:71], v[168:171], v[208:211], v[68:71]
	v_mfma_f32_16x16x32_bf16 v[64:67], v[176:179], v[208:211], v[64:67]
	v_mfma_f32_16x16x32_bf16 v[116:119], v[172:175], v[188:191], v[116:119]
	v_mfma_f32_16x16x32_bf16 v[112:115], v[180:183], v[188:191], v[112:115]
	v_mfma_f32_16x16x32_bf16 v[100:103], v[172:175], v[196:199], v[100:103]
	v_mfma_f32_16x16x32_bf16 v[96:99], v[180:183], v[196:199], v[96:99]
	v_mfma_f32_16x16x32_bf16 v[84:87], v[172:175], v[204:207], v[84:87]
	v_mfma_f32_16x16x32_bf16 v[80:83], v[180:183], v[204:207], v[80:83]
	v_mfma_f32_16x16x32_bf16 v[68:71], v[172:175], v[212:215], v[68:71]
	v_mfma_f32_16x16x32_bf16 v[64:67], v[180:183], v[212:215], v[64:67]
	s_setprio 0
	s_barrier
; #define PG8_STAGE(bufoff, gbase, voff) do { _Pragma("unroll") for (int _i = 0; _i < 2; ++_i) \
;         __builtin_amdgcn_global_load_lds((const unsigned*)((const char*)(gbase) + (voff)[_i]), (PG8_LAS unsigned*)(lds + (bufoff) + ldsw + _i * 8192), 16, 0, 0); } while (0)
; #define PG8_LDA(dst, b, h) do { _Pragma("unroll") for (int m = 0; m < 4; ++m) _Pragma("unroll") for (int k = 0; k < 2; ++k) dst[m][k] = *(const PG8_LAS bf16x8*)(lds + PG8_SA(b, h) + aoff + m * 2048 + k * 1024); } while (0)
; #define PG8_LDB(dst, b, h) do { _Pragma("unroll") for (int n = 0; n < 2; ++n) _Pragma("unroll") for (int k = 0; k < 2; ++k) dst[n][k] = *(const PG8_LAS bf16x8*)(lds + PG8_SB(b, h) + boff + n * 2048 + k * 1024); } while (0)
; #define PG8_MMA(ai, bj, At, Bt) do { __builtin_amdgcn_s_setprio(1); _Pragma("unroll") for (int m = 0; m < 4; ++m) _Pragma("unroll") for (int n = 0; n < 2; ++n) _Pragma("unroll") for (int k = 0; k < 2; ++k) \
;         acc[ai][bj][m][n] = __builtin_amdgcn_mfma_f32_16x16x32_bf16(Bt[n][k], At[m][k], acc[ai][bj][m][n], 0, 0, 0); __builtin_amdgcn_s_setprio(0); } while (0)
; #define PG8_WAIT_V(n) asm volatile("s_waitcnt vmcnt(" #n ")" ::: "memory")
; #define PG8_WAIT_L(n) asm volatile("s_waitcnt lgkmcnt(" #n ")" ::: "memory")
; #define PG8_BAR __builtin_amdgcn_s_barrier()
; #define PG8_SCHED __builtin_amdgcn_sched_barrier(0)
; template <class Epi, class Sched, bool ALIGN_EPI = false, bool SP2 = false>
; __device__ __forceinline__ void gemm_phase(PG8_LAS unsigned char* lds, const Gemm g, const Sched& S, const Epi& E) {
;     ...
;             PG8_LDA(At, 0, 1); PG8_STAGE(PG8_SB(0, 0), b2, voffB); PG8_STAGE(PG8_SB(0, 1), b2 + hstepB, voffB); PG8_STAGE(PG8_SA(0, 0), a2, voffA);
;             PG8_WAIT_V(8); PG8_WAIT_L(0); PG8_BAR; PG8_MMA(1, 0, At, B0); PG8_MMA(1, 1, At, B1); PG8_BAR; PG8_SCHED;
;             PG8_LDB(B0, 1, 0); PG8_LDB(B1, 1, 1); PG8_SCHED; PG8_LDA(At, 1, 0); PG8_STAGE(PG8_SA(0, 1), a2 + hstepA, voffA);
;             PG8_WAIT_V(8); PG8_WAIT_L(0); PG8_BAR; PG8_MMA(0, 0, At, B0); PG8_MMA(0, 1, At, B1); PG8_BAR; PG8_SCHED;
	s_add_i32 s4, s36, s47
	v_lshl_add_u64 v[164:165], s[26:27], 0, v[130:131]
	s_mov_b32 m0, s4
	ds_read_b128 v[184:187], v151 offset:16384
	ds_read_b128 v[188:191], v151 offset:17408
	ds_read_b128 v[192:195], v151 offset:18432
	ds_read_b128 v[196:199], v151 offset:19456
	ds_read_b128 v[200:203], v151 offset:20480
	ds_read_b128 v[204:207], v151 offset:21504
	ds_read_b128 v[208:211], v151 offset:22528
	ds_read_b128 v[212:215], v151 offset:23552
	global_load_lds_dwordx4 v[164:165], off
	s_add_i32 m0, s4, 0x2000
	s_add_u32 s4, s26, 0x160000
	v_lshl_add_u64 v[216:217], s[26:27], 0, v[134:135]
	s_addc_u32 s5, s27, 0
	s_add_i32 s20, s37, s47
	global_load_lds_dwordx4 v[216:217], off
	v_lshl_add_u64 v[218:219], s[4:5], 0, v[130:131]
	s_mov_b32 m0, s20
	v_lshl_add_u64 v[220:221], s[28:29], 0, v[132:133]
	global_load_lds_dwordx4 v[218:219], off
	v_lshl_add_u64 v[218:219], s[4:5], 0, v[134:135]
	s_add_i32 m0, s20, 0x2000
	s_nop 0
	global_load_lds_dwordx4 v[218:219], off
	v_lshl_add_u64 v[218:219], s[28:29], 0, v[128:129]
	s_mov_b32 m0, s25
	s_nop 0
	global_load_lds_dwordx4 v[218:219], off
	s_mov_b32 m0, s30
	s_nop 0
	global_load_lds_dwordx4 v[220:221], off
	s_waitcnt vmcnt(8)
	s_waitcnt lgkmcnt(0)
	s_barrier
	s_setprio 1
	s_waitcnt lgkmcnt(0)
	v_mfma_f32_16x16x32_bf16 v[60:63], v[144:147], v[184:187], v[60:63]
	v_mfma_f32_16x16x32_bf16 v[56:59], v[156:159], v[184:187], v[56:59]
	v_mfma_f32_16x16x32_bf16 v[44:47], v[144:147], v[192:195], v[44:47]
	v_mfma_f32_16x16x32_bf16 v[40:43], v[156:159], v[192:195], v[40:43]
	v_mfma_f32_16x16x32_bf16 v[28:31], v[144:147], v[200:203], v[28:31]
	v_mfma_f32_16x16x32_bf16 v[24:27], v[156:159], v[200:203], v[24:27]
	v_mfma_f32_16x16x32_bf16 v[12:15], v[144:147], v[208:211], v[12:15]
	v_mfma_f32_16x16x32_bf16 v[8:11], v[156:159], v[208:211], v[8:11]
	v_mfma_f32_16x16x32_bf16 v[60:63], v[152:155], v[188:191], v[60:63]
	v_mfma_f32_16x16x32_bf16 v[56:59], v[160:163], v[188:191], v[56:59]
	v_mfma_f32_16x16x32_bf16 v[44:47], v[152:155], v[196:199], v[44:47]
	v_mfma_f32_16x16x32_bf16 v[40:43], v[160:163], v[196:199], v[40:43]
	v_mfma_f32_16x16x32_bf16 v[28:31], v[152:155], v[204:207], v[28:31]
	v_mfma_f32_16x16x32_bf16 v[24:27], v[160:163], v[204:207], v[24:27]
	v_mfma_f32_16x16x32_bf16 v[12:15], v[152:155], v[212:215], v[12:15]
	v_mfma_f32_16x16x32_bf16 v[8:11], v[160:163], v[212:215], v[8:11]
	s_setprio 0
	s_setprio 1
	v_mfma_f32_16x16x32_bf16 v[52:55], v[168:171], v[184:187], v[52:55]
	v_mfma_f32_16x16x32_bf16 v[48:51], v[176:179], v[184:187], v[48:51]
	v_mfma_f32_16x16x32_bf16 v[36:39], v[168:171], v[192:195], v[36:39]
	v_mfma_f32_16x16x32_bf16 v[32:35], v[176:179], v[192:195], v[32:35]
	v_mfma_f32_16x16x32_bf16 v[20:23], v[168:171], v[200:203], v[20:23]
	v_mfma_f32_16x16x32_bf16 v[16:19], v[176:179], v[200:203], v[16:19]
	v_mfma_f32_16x16x32_bf16 v[4:7], v[168:171], v[208:211], v[4:7]
	v_mfma_f32_16x16x32_bf16 v[0:3], v[176:179], v[208:211], v[0:3]
	v_mfma_f32_16x16x32_bf16 v[52:55], v[172:175], v[188:191], v[52:55]
	v_mfma_f32_16x16x32_bf16 v[48:51], v[180:183], v[188:191], v[48:51]
	v_mfma_f32_16x16x32_bf16 v[36:39], v[172:175], v[196:199], v[36:39]
	v_mfma_f32_16x16x32_bf16 v[32:35], v[180:183], v[196:199], v[32:35]
	v_mfma_f32_16x16x32_bf16 v[20:23], v[172:175], v[204:207], v[20:23]
	v_mfma_f32_16x16x32_bf16 v[16:19], v[180:183], v[204:207], v[16:19]
	v_mfma_f32_16x16x32_bf16 v[4:7], v[172:175], v[212:215], v[4:7]
	v_mfma_f32_16x16x32_bf16 v[0:3], v[180:183], v[212:215], v[0:3]
	s_setprio 0
	s_barrier
	s_add_i32 s20, 0, 0x18000
	s_add_i32 s21, 0, 0x1c000
	v_add_u32_e32 v160, s20, v148
	v_add_u32_e32 v166, s21, v148
	ds_read_b128 v[144:147], v160
	ds_read_b128 v[152:155], v160 offset:1024
	ds_read_b128 v[156:159], v160 offset:2048
	ds_read_b128 v[160:163], v160 offset:3072
	ds_read_b128 v[168:171], v166
	ds_read_b128 v[172:175], v166 offset:1024
	ds_read_b128 v[176:179], v166 offset:2048
	ds_read_b128 v[180:183], v166 offset:3072
	s_add_u32 s4, s28, 0x160000
	s_addc_u32 s5, s29, 0
	s_mov_b32 m0, s31
	v_lshl_add_u64 v[222:223], s[4:5], 0, v[128:129]
	ds_read_b128 v[184:187], v151 offset:32768
	ds_read_b128 v[188:191], v151 offset:33792
	ds_read_b128 v[192:195], v151 offset:34816
	ds_read_b128 v[196:199], v151 offset:35840
	ds_read_b128 v[200:203], v151 offset:36864
	ds_read_b128 v[204:207], v151 offset:37888
	ds_read_b128 v[208:211], v151 offset:38912
	ds_read_b128 v[212:215], v151 offset:39936
	global_load_lds_dwordx4 v[222:223], off
	v_lshl_add_u64 v[222:223], s[4:5], 0, v[132:133]
	s_mov_b32 m0, s33
	s_nop 0
	global_load_lds_dwordx4 v[222:223], off
	s_waitcnt vmcnt(8)
	s_waitcnt lgkmcnt(0)
	s_barrier
; #define PG8_STAGE(bufoff, gbase, voff) do { _Pragma("unroll") for (int _i = 0; _i < 2; ++_i) \
;         __builtin_amdgcn_global_load_lds((const unsigned*)((const char*)(gbase) + (voff)[_i]), (PG8_LAS unsigned*)(lds + (bufoff) + ldsw + _i * 8192), 16, 0, 0); } while (0)
; #define PG8_LDA(dst, b, h) do { _Pragma("unroll") for (int m = 0; m < 4; ++m) _Pragma("unroll") for (int k = 0; k < 2; ++k) dst[m][k] = *(const PG8_LAS bf16x8*)(lds + PG8_SA(b, h) + aoff + m * 2048 + k * 1024); } while (0)
; #define PG8_MMA(ai, bj, At, Bt) do { __builtin_amdgcn_s_setprio(1); _Pragma("unroll") for (int m = 0; m < 4; ++m) _Pragma("unroll") for (int n = 0; n < 2; ++n) _Pragma("unroll") for (int k = 0; k < 2; ++k) \
;         acc[ai][bj][m][n] = __builtin_amdgcn_mfma_f32_16x16x32_bf16(Bt[n][k], At[m][k], acc[ai][bj][m][n], 0, 0, 0); __builtin_amdgcn_s_setprio(0); } while (0)
; #define PG8_WAIT_V(n) asm volatile("s_waitcnt vmcnt(" #n ")" ::: "memory")
; #define PG8_WAIT_L(n) asm volatile("s_waitcnt lgkmcnt(" #n ")" ::: "memory")
; #define PG8_BAR __builtin_amdgcn_s_barrier()
; #define PG8_SCHED __builtin_amdgcn_sched_barrier(0)
; template <class Epi, class Sched, bool ALIGN_EPI = false, bool SP2 = false>
; __device__ __forceinline__ void gemm_phase(PG8_LAS unsigned char* lds, const Gemm g, const Sched& S, const Epi& E) {
;     ...
;             PG8_WAIT_V(8); PG8_WAIT_L(0); PG8_BAR; PG8_MMA(0, 0, At, B0); PG8_MMA(0, 1, At, B1); PG8_BAR; PG8_SCHED;
;             PG8_LDA(At, 1, 1); PG8_STAGE(PG8_SB(1, 0), b3, voffB); PG8_STAGE(PG8_SB(1, 1), b3 + hstepB, voffB); PG8_STAGE(PG8_SA(1, 0), a3, voffA);
;             PG8_WAIT_V(8); PG8_WAIT_L(0); PG8_BAR; PG8_MMA(1, 0, At, B0); PG8_MMA(1, 1, At, B1); PG8_BAR; PG8_SCHED;
	s_setprio 1
	s_waitcnt lgkmcnt(0)
	v_mfma_f32_16x16x32_bf16 v[124:127], v[144:147], v[184:187], v[124:127]
	v_mfma_f32_16x16x32_bf16 v[120:123], v[156:159], v[184:187], v[120:123]
	v_mfma_f32_16x16x32_bf16 v[108:111], v[144:147], v[192:195], v[108:111]
	v_mfma_f32_16x16x32_bf16 v[104:107], v[156:159], v[192:195], v[104:107]
	v_mfma_f32_16x16x32_bf16 v[92:95], v[144:147], v[200:203], v[92:95]
	v_mfma_f32_16x16x32_bf16 v[88:91], v[156:159], v[200:203], v[88:91]
	v_mfma_f32_16x16x32_bf16 v[76:79], v[144:147], v[208:211], v[76:79]
	v_mfma_f32_16x16x32_bf16 v[72:75], v[156:159], v[208:211], v[72:75]
	v_mfma_f32_16x16x32_bf16 v[124:127], v[152:155], v[188:191], v[124:127]
	v_mfma_f32_16x16x32_bf16 v[120:123], v[160:163], v[188:191], v[120:123]
	v_mfma_f32_16x16x32_bf16 v[108:111], v[152:155], v[196:199], v[108:111]
	v_mfma_f32_16x16x32_bf16 v[104:107], v[160:163], v[196:199], v[104:107]
	v_mfma_f32_16x16x32_bf16 v[92:95], v[152:155], v[204:207], v[92:95]
	v_mfma_f32_16x16x32_bf16 v[88:91], v[160:163], v[204:207], v[88:91]
	v_mfma_f32_16x16x32_bf16 v[76:79], v[152:155], v[212:215], v[76:79]
	v_mfma_f32_16x16x32_bf16 v[72:75], v[160:163], v[212:215], v[72:75]
	s_setprio 0
	s_setprio 1
	v_mfma_f32_16x16x32_bf16 v[116:119], v[168:171], v[184:187], v[116:119]
	v_mfma_f32_16x16x32_bf16 v[112:115], v[176:179], v[184:187], v[112:115]
	v_mfma_f32_16x16x32_bf16 v[100:103], v[168:171], v[192:195], v[100:103]
	v_mfma_f32_16x16x32_bf16 v[96:99], v[176:179], v[192:195], v[96:99]
	v_mfma_f32_16x16x32_bf16 v[84:87], v[168:171], v[200:203], v[84:87]
	v_mfma_f32_16x16x32_bf16 v[80:83], v[176:179], v[200:203], v[80:83]
	v_mfma_f32_16x16x32_bf16 v[68:71], v[168:171], v[208:211], v[68:71]
	v_mfma_f32_16x16x32_bf16 v[64:67], v[176:179], v[208:211], v[64:67]
	v_mfma_f32_16x16x32_bf16 v[116:119], v[172:175], v[188:191], v[116:119]
	v_mfma_f32_16x16x32_bf16 v[112:115], v[180:183], v[188:191], v[112:115]
	v_mfma_f32_16x16x32_bf16 v[100:103], v[172:175], v[196:199], v[100:103]
	v_mfma_f32_16x16x32_bf16 v[96:99], v[180:183], v[196:199], v[96:99]
	v_mfma_f32_16x16x32_bf16 v[84:87], v[172:175], v[204:207], v[84:87]
	v_mfma_f32_16x16x32_bf16 v[80:83], v[180:183], v[204:207], v[80:83]
	v_mfma_f32_16x16x32_bf16 v[68:71], v[172:175], v[212:215], v[68:71]
	v_mfma_f32_16x16x32_bf16 v[64:67], v[180:183], v[212:215], v[64:67]
	s_setprio 0
	s_barrier
	s_add_i32 s4, s20, s47
	v_lshl_add_u64 v[164:165], v[164:165], 0, s[16:17]
	s_mov_b32 m0, s4
	ds_read_b128 v[184:187], v151 offset:49152
	ds_read_b128 v[188:191], v151 offset:50176
	ds_read_b128 v[192:195], v151 offset:51200
	ds_read_b128 v[196:199], v151 offset:52224
	ds_read_b128 v[200:203], v151 offset:53248
	ds_read_b128 v[204:207], v151 offset:54272
	ds_read_b128 v[208:211], v151 offset:55296
	ds_read_b128 v[212:215], v151 offset:56320
	global_load_lds_dwordx4 v[164:165], off
	s_add_i32 m0, s4, 0x2000
	s_add_u32 s4, s26, 0x160080
	v_lshl_add_u64 v[164:165], v[216:217], 0, s[16:17]
	s_addc_u32 s5, s27, 0
	s_add_i32 s20, s21, s47
	global_load_lds_dwordx4 v[164:165], off
	v_lshl_add_u64 v[164:165], s[4:5], 0, v[130:131]
	s_mov_b32 m0, s20
	s_nop 0
	global_load_lds_dwordx4 v[164:165], off
	v_lshl_add_u64 v[164:165], s[4:5], 0, v[134:135]
	s_add_i32 m0, s20, 0x2000
	s_nop 0
	global_load_lds_dwordx4 v[164:165], off
	v_lshl_add_u64 v[164:165], v[218:219], 0, s[16:17]
	s_mov_b32 m0, s34
	s_nop 0
	global_load_lds_dwordx4 v[164:165], off
	v_lshl_add_u64 v[164:165], v[220:221], 0, s[16:17]
	s_mov_b32 m0, s35
	s_nop 0
	global_load_lds_dwordx4 v[164:165], off
	s_waitcnt vmcnt(8)
	s_waitcnt lgkmcnt(0)
	s_barrier
	s_setprio 1
	s_waitcnt lgkmcnt(0)
	v_mfma_f32_16x16x32_bf16 v[60:63], v[144:147], v[184:187], v[60:63]
	v_mfma_f32_16x16x32_bf16 v[56:59], v[156:159], v[184:187], v[56:59]
	v_mfma_f32_16x16x32_bf16 v[44:47], v[144:147], v[192:195], v[44:47]
	v_mfma_f32_16x16x32_bf16 v[40:43], v[156:159], v[192:195], v[40:43]
	v_mfma_f32_16x16x32_bf16 v[28:31], v[144:147], v[200:203], v[28:31]
	v_mfma_f32_16x16x32_bf16 v[24:27], v[156:159], v[200:203], v[24:27]
	v_mfma_f32_16x16x32_bf16 v[12:15], v[144:147], v[208:211], v[12:15]
	v_mfma_f32_16x16x32_bf16 v[8:11], v[156:159], v[208:211], v[8:11]
	v_mfma_f32_16x16x32_bf16 v[60:63], v[152:155], v[188:191], v[60:63]
	v_mfma_f32_16x16x32_bf16 v[56:59], v[160:163], v[188:191], v[56:59]
	v_mfma_f32_16x16x32_bf16 v[44:47], v[152:155], v[196:199], v[44:47]
	v_mfma_f32_16x16x32_bf16 v[40:43], v[160:163], v[196:199], v[40:43]
	v_mfma_f32_16x16x32_bf16 v[28:31], v[152:155], v[204:207], v[28:31]
	v_mfma_f32_16x16x32_bf16 v[24:27], v[160:163], v[204:207], v[24:27]
	v_mfma_f32_16x16x32_bf16 v[12:15], v[152:155], v[212:215], v[12:15]
	v_mfma_f32_16x16x32_bf16 v[8:11], v[160:163], v[212:215], v[8:11]
	s_setprio 0
	s_setprio 1
	v_mfma_f32_16x16x32_bf16 v[52:55], v[168:171], v[184:187], v[52:55]
	v_mfma_f32_16x16x32_bf16 v[48:51], v[176:179], v[184:187], v[48:51]
	v_mfma_f32_16x16x32_bf16 v[36:39], v[168:171], v[192:195], v[36:39]
	v_mfma_f32_16x16x32_bf16 v[32:35], v[176:179], v[192:195], v[32:35]
	v_mfma_f32_16x16x32_bf16 v[20:23], v[168:171], v[200:203], v[20:23]
	v_mfma_f32_16x16x32_bf16 v[16:19], v[176:179], v[200:203], v[16:19]
	v_mfma_f32_16x16x32_bf16 v[4:7], v[168:171], v[208:211], v[4:7]
	v_mfma_f32_16x16x32_bf16 v[0:3], v[176:179], v[208:211], v[0:3]
	v_mfma_f32_16x16x32_bf16 v[52:55], v[172:175], v[188:191], v[52:55]
	v_mfma_f32_16x16x32_bf16 v[48:51], v[180:183], v[188:191], v[48:51]
	v_mfma_f32_16x16x32_bf16 v[36:39], v[172:175], v[196:199], v[36:39]
	v_mfma_f32_16x16x32_bf16 v[32:35], v[180:183], v[196:199], v[32:35]
	v_mfma_f32_16x16x32_bf16 v[20:23], v[172:175], v[204:207], v[20:23]
	v_mfma_f32_16x16x32_bf16 v[16:19], v[180:183], v[204:207], v[16:19]
	v_mfma_f32_16x16x32_bf16 v[4:7], v[172:175], v[212:215], v[4:7]
	v_mfma_f32_16x16x32_bf16 v[0:3], v[180:183], v[212:215], v[0:3]
	s_setprio 0
	s_barrier
	s_add_i32 s50, s50, 2
	s_add_u32 s45, s45, 0x100
	s_addc_u32 s46, s46, 0
	s_cmpk_gt_u32 s50, 0x55
	s_mov_b64 s[20:21], s[22:23]
	s_cbranch_scc0 .LBB0_1361
	s_and_b64 vcc, exec, s[48:49]
	s_cbranch_vccz .LBB0_1364
	s_barrier
; __device__ __forceinline__ unsigned cvt_pk_bf16(float lo, float hi) { unsigned r; asm volatile("v_cvt_pk_bf16_f32 %0, %1, %2" : "=v"(r) : "v"(lo), "v"(hi)); return r; }
; __device__ __forceinline__ float shx(float v, int mask, int lane) { return __int_as_float(__builtin_amdgcn_ds_bpermute((lane ^ mask) << 2, __float_as_int(v))); }
; __device__ __forceinline__ float bf_lo(unsigned w) { return __uint_as_float(w << 16); }
; __device__ __forceinline__ float bf_hi(unsigned w) { return __uint_as_float(w & 0xffff0000u); }
;     __device__ __forceinline__ void operator()(const f32x4 (&acc)[2][2][4][2], const Unit& u, int wr, int wc, int fr, int fq) const {
;     ...
;             for (int m = 0; m < 4; ++m) { const int row = row0 + ai * HALF + m * 16; bf16_t* bp = HB + (size_t)row * 2048 + col0; float s = 0.f;
;                 u32x4 hv[2];
; #pragma unroll
;                 for (int bj = 0; bj < 2; ++bj) hv[bj] = *(const u32x4*)(bp + bj * HALF);
; #pragma unroll
;                 for (int bj = 0; bj < 2; ++bj) { const f32x4 a0 = acc[ai][bj][m][0], a1 = acc[ai][bj][m][1]; const u32x4 x = hv[bj];
;                     const float h0 = bf_lo(x.x) + a0[0], h1 = bf_hi(x.x) + a0[1], h2 = bf_lo(x.y) + a0[2], h3 = bf_hi(x.y) + a0[3], h4 = bf_lo(x.z) + a1[0], h5 = bf_hi(x.z) + a1[1], h6 = bf_lo(x.w) + a1[2], h7 = bf_hi(x.w) + a1[3];
;                     s += (h0 * h0 + h1 * h1) + (h2 * h2 + h3 * h3) + (h4 * h4 + h5 * h5) + (h6 * h6 + h7 * h7);
;                     u32x4 w; w.x = cvt_pk_bf16(h0, h1); w.y = cvt_pk_bf16(h2, h3); w.z = cvt_pk_bf16(h4, h5); w.w = cvt_pk_bf16(h6, h7); *(u32x4*)(bp + bj * HALF) = w; }
;                 { const int ln = fr + 16 * fq; s += shx(s, 16, ln); s += shx(s, 32, ln); }
;                 if (fq == 0) ssq_out[(size_t)row * 32 + u.pn * 4 + wc] = s;
.LBB0_1364:
	v_and_b32_e32 v232, 15, v167
	v_lshrrev_b32_e32 v233, 4, v167
	s_lshl_b32 s4, s44, 8
	s_add_i32 s4, s4, s78
	v_or_b32_e32 v234, s4, v232
	s_lshl_b32 s4, s10, 8
	s_or_b32 s4, s4, s73
	v_lshl_add_u32 v235, v233, 3, s4
	v_lshlrev_b32_e32 v235, 1, v235
	v_lshl_add_u32 v235, v234, 12, v235
	v_add_u32_e32 v236, 0x10000, v235
	v_add_u32_e32 v237, 0x20000, v235
	v_add_u32_e32 v238, 0x30000, v235
	v_add_u32_e32 v239, 0x80000, v235
	v_add_u32_e32 v240, 0x90000, v235
	v_add_u32_e32 v241, 0xa0000, v235
	v_add_u32_e32 v242, 0xb0000, v235
	global_load_dwordx4 v[168:171], v235, s[12:13]
	global_load_dwordx4 v[172:175], v235, s[12:13] offset:256
	global_load_dwordx4 v[176:179], v236, s[12:13]
	global_load_dwordx4 v[180:183], v236, s[12:13] offset:256
	global_load_dwordx4 v[184:187], v237, s[12:13]
	global_load_dwordx4 v[188:191], v237, s[12:13] offset:256
	global_load_dwordx4 v[192:195], v238, s[12:13]
	global_load_dwordx4 v[196:199], v238, s[12:13] offset:256
	global_load_dwordx4 v[200:203], v239, s[12:13]
	global_load_dwordx4 v[204:207], v239, s[12:13] offset:256
	global_load_dwordx4 v[208:211], v240, s[12:13]
	global_load_dwordx4 v[212:215], v240, s[12:13] offset:256
	global_load_dwordx4 v[216:219], v241, s[12:13]
	global_load_dwordx4 v[220:223], v241, s[12:13] offset:256
	global_load_dwordx4 v[224:227], v242, s[12:13]
	global_load_dwordx4 v[228:231], v242, s[12:13] offset:256
	s_waitcnt vmcnt(0)
	v_mov_b32_e32 v164, v167
	s_lshl_b32 s4, s44, 8
	s_add_i32 s4, s4, s78
	v_and_b32_e32 v165, 15, v164
	v_or_b32_e32 v146, s4, v165
	s_lshl_b32 s4, s10, 8
	v_ashrrev_i32_e32 v166, 4, v164
	s_or_b32 s4, s4, s73
	v_ashrrev_i32_e32 v147, 31, v146
	v_lshl_add_u32 v144, v166, 3, s4
	v_lshlrev_b64 v[152:153], 12, v[146:147]
	v_ashrrev_i32_e32 v145, 31, v144
	v_lshl_add_u64 v[152:153], s[12:13], 0, v[152:153]
	v_lshl_add_u64 v[162:163], v[144:145], 1, v[152:153]
	s_nop 1
	v_mov_b32_e32 v154, v168
	v_mov_b32_e32 v155, v169
	v_mov_b32_e32 v156, v170
	v_mov_b32_e32 v157, v171
	v_mov_b32_e32 v158, v172
	v_mov_b32_e32 v159, v173
	v_mov_b32_e32 v160, v174
	v_mov_b32_e32 v161, v175
	v_cmp_gt_u32_e32 vcc, 16, v164
	v_lshlrev_b32_e32 v152, 6, v166
	v_lshlrev_b32_e32 v164, 2, v165
	v_bitop3_b32 v153, v152, 64, v164 bitop3:0x36
	v_bitop3_b32 v152, v152, s38, v164 bitop3:0x36
	s_lshl_b32 s20, s10, 2
	s_ashr_i32 s21, s20, 31
	v_lshlrev_b32_e32 v164, 16, v154
	v_and_b32_e32 v154, 0xffff0000, v154
	v_lshlrev_b32_e32 v165, 16, v155
	v_and_b32_e32 v155, 0xffff0000, v155
	v_lshlrev_b32_e32 v169, 16, v158
	v_and_b32_e32 v158, 0xffff0000, v158
	v_lshlrev_b32_e32 v170, 16, v159
	v_and_b32_e32 v159, 0xffff0000, v159
	v_lshlrev_b32_e32 v166, 16, v156
	v_and_b32_e32 v156, 0xffff0000, v156
	v_lshlrev_b32_e32 v168, 16, v157
	v_and_b32_e32 v157, 0xffff0000, v157
	v_lshlrev_b32_e32 v171, 16, v160
	v_and_b32_e32 v160, 0xffff0000, v160
	v_lshlrev_b32_e32 v172, 16, v161
	v_and_b32_e32 v161, 0xffff0000, v161
	v_add_f32_e32 v125, v125, v154
	v_add_f32_e32 v127, v127, v155
	v_add_f32_e32 v117, v117, v158
	v_add_f32_e32 v119, v119, v159
	v_add_f32_e32 v124, v124, v164
	v_add_f32_e32 v126, v126, v165
	v_add_f32_e32 v121, v121, v156
	v_add_f32_e32 v123, v123, v157
	v_add_f32_e32 v116, v116, v169
	v_add_f32_e32 v118, v118, v170
	v_add_f32_e32 v154, v112, v171
	v_add_f32_e32 v155, v113, v160
	v_add_f32_e32 v156, v114, v172
	v_add_f32_e32 v157, v115, v161
	v_mul_f32_e32 v114, v125, v125
	v_mul_f32_e32 v115, v127, v127
	v_cvt_pk_bf16_f32 v112, v124, v125
	v_cvt_pk_bf16_f32 v113, v126, v127
	v_mul_f32_e32 v125, v117, v117
	v_mul_f32_e32 v127, v119, v119
	v_add_f32_e32 v120, v120, v166
	v_mul_f32_e32 v158, v121, v121
	v_mul_f32_e32 v160, v155, v155
	v_fmac_f32_e32 v114, v124, v124
	v_fmac_f32_e32 v115, v126, v126
	v_fmac_f32_e32 v125, v116, v116
	v_fmac_f32_e32 v127, v118, v118
	v_add_f32_e32 v122, v122, v168
	v_mul_f32_e32 v159, v123, v123
	v_mul_f32_e32 v161, v157, v157
	v_fmac_f32_e32 v158, v120, v120
	v_fmac_f32_e32 v160, v154, v154
	v_add_f32_e32 v114, v114, v115
	v_add_f32_e32 v115, v125, v127
	v_fmac_f32_e32 v159, v122, v122
	v_fmac_f32_e32 v161, v156, v156
	v_add_f32_e32 v114, v158, v114
	v_add_f32_e32 v115, v160, v115
	v_add_f32_e32 v114, v159, v114
	v_add_f32_e32 v115, v161, v115
	v_add_f32_e32 v124, v114, v115
	ds_bpermute_b32 v125, v153, v124
	v_cvt_pk_bf16_f32 v114, v120, v121
	v_cvt_pk_bf16_f32 v115, v122, v123
	global_store_dwordx4 v[162:163], v[112:115], off
	s_waitcnt lgkmcnt(0)
	s_nop 0
	v_add_f32_e32 v112, v124, v125
	ds_bpermute_b32 v113, v152, v112
	v_cvt_pk_bf16_f32 v114, v116, v117
	v_cvt_pk_bf16_f32 v115, v118, v119
	v_cvt_pk_bf16_f32 v116, v154, v155
	v_cvt_pk_bf16_f32 v117, v156, v157
	global_store_dwordx4 v[162:163], v[114:117], off offset:256
	s_and_saveexec_b64 s[22:23], vcc
	s_cbranch_execz .LBB0_1366
	s_waitcnt lgkmcnt(0)
	v_add_f32_e32 v114, v112, v113
	v_lshlrev_b64 v[112:113], 7, v[146:147]
	v_lshl_add_u64 v[112:113], s[14:15], 0, v[112:113]
	v_lshl_add_u64 v[112:113], s[20:21], 2, v[112:113]
	s_lshl_b32 s10, s72, 2
	v_lshl_add_u64 v[112:113], v[112:113], 0, s[10:11]
	global_store_dword v[112:113], v114, off
; __device__ __forceinline__ unsigned cvt_pk_bf16(float lo, float hi) { unsigned r; asm volatile("v_cvt_pk_bf16_f32 %0, %1, %2" : "=v"(r) : "v"(lo), "v"(hi)); return r; }
; __device__ __forceinline__ float shx(float v, int mask, int lane) { return __int_as_float(__builtin_amdgcn_ds_bpermute((lane ^ mask) << 2, __float_as_int(v))); }
; __device__ __forceinline__ float bf_lo(unsigned w) { return __uint_as_float(w << 16); }
; __device__ __forceinline__ float bf_hi(unsigned w) { return __uint_as_float(w & 0xffff0000u); }
;     __device__ __forceinline__ void operator()(const f32x4 (&acc)[2][2][4][2], const Unit& u, int wr, int wc, int fr, int fq) const {
;     ...
;             for (int m = 0; m < 4; ++m) { const int row = row0 + ai * HALF + m * 16; bf16_t* bp = HB + (size_t)row * 2048 + col0; float s = 0.f;
;                 u32x4 hv[2];
; #pragma unroll
;                 for (int bj = 0; bj < 2; ++bj) hv[bj] = *(const u32x4*)(bp + bj * HALF);
; #pragma unroll
;                 for (int bj = 0; bj < 2; ++bj) { const f32x4 a0 = acc[ai][bj][m][0], a1 = acc[ai][bj][m][1]; const u32x4 x = hv[bj];
;                     const float h0 = bf_lo(x.x) + a0[0], h1 = bf_hi(x.x) + a0[1], h2 = bf_lo(x.y) + a0[2], h3 = bf_hi(x.y) + a0[3], h4 = bf_lo(x.z) + a1[0], h5 = bf_hi(x.z) + a1[1], h6 = bf_lo(x.w) + a1[2], h7 = bf_hi(x.w) + a1[3];
;                     s += (h0 * h0 + h1 * h1) + (h2 * h2 + h3 * h3) + (h4 * h4 + h5 * h5) + (h6 * h6 + h7 * h7);
;                     u32x4 w; w.x = cvt_pk_bf16(h0, h1); w.y = cvt_pk_bf16(h2, h3); w.z = cvt_pk_bf16(h4, h5); w.w = cvt_pk_bf16(h6, h7); *(u32x4*)(bp + bj * HALF) = w; }
;                 { const int ln = fr + 16 * fq; s += shx(s, 16, ln); s += shx(s, 32, ln); }
;                 if (fq == 0) ssq_out[(size_t)row * 32 + u.pn * 4 + wc] = s;
;                 asm volatile("" ::: "memory"); }
.LBB0_1366:
	s_or_b64 exec, exec, s[22:23]
	v_or_b32_e32 v112, 16, v146
	s_waitcnt lgkmcnt(0)
	v_ashrrev_i32_e32 v113, 31, v112
	v_lshlrev_b64 v[114:115], 12, v[112:113]
	v_lshl_add_u64 v[114:115], s[12:13], 0, v[114:115]
	v_lshl_add_u64 v[122:123], v[144:145], 1, v[114:115]
	s_nop 1
	v_mov_b32_e32 v114, v176
	v_mov_b32_e32 v115, v177
	v_mov_b32_e32 v116, v178
	v_mov_b32_e32 v117, v179
	v_mov_b32_e32 v118, v180
	v_mov_b32_e32 v119, v181
	v_mov_b32_e32 v120, v182
	v_mov_b32_e32 v121, v183
	v_lshlrev_b32_e32 v124, 16, v114
	v_and_b32_e32 v114, 0xffff0000, v114
	v_lshlrev_b32_e32 v125, 16, v115
	v_and_b32_e32 v115, 0xffff0000, v115
	v_lshlrev_b32_e32 v147, 16, v118
	v_and_b32_e32 v118, 0xffff0000, v118
	v_lshlrev_b32_e32 v154, 16, v119
	v_and_b32_e32 v119, 0xffff0000, v119
	v_lshlrev_b32_e32 v126, 16, v116
	v_and_b32_e32 v116, 0xffff0000, v116
	v_lshlrev_b32_e32 v127, 16, v117
	v_and_b32_e32 v117, 0xffff0000, v117
	v_lshlrev_b32_e32 v155, 16, v120
	v_and_b32_e32 v120, 0xffff0000, v120
	v_lshlrev_b32_e32 v156, 16, v121
	v_and_b32_e32 v121, 0xffff0000, v121
	v_add_f32_e32 v109, v109, v114
	v_add_f32_e32 v111, v111, v115
	v_add_f32_e32 v101, v101, v118
	v_add_f32_e32 v103, v103, v119
	v_add_f32_e32 v108, v108, v124
	v_add_f32_e32 v110, v110, v125
	v_add_f32_e32 v105, v105, v116
	v_add_f32_e32 v107, v107, v117
	v_add_f32_e32 v100, v100, v147
	v_add_f32_e32 v102, v102, v154
	v_add_f32_e32 v114, v96, v155
	v_add_f32_e32 v115, v97, v120
	v_add_f32_e32 v116, v98, v156
	v_add_f32_e32 v117, v99, v121
	v_mul_f32_e32 v98, v109, v109
	v_mul_f32_e32 v99, v111, v111
	v_cvt_pk_bf16_f32 v96, v108, v109
	v_cvt_pk_bf16_f32 v97, v110, v111
	v_mul_f32_e32 v109, v101, v101
	v_mul_f32_e32 v111, v103, v103
	v_add_f32_e32 v104, v104, v126
	v_mul_f32_e32 v118, v105, v105
	v_mul_f32_e32 v120, v115, v115
	v_fmac_f32_e32 v98, v108, v108
	v_fmac_f32_e32 v99, v110, v110
	v_fmac_f32_e32 v109, v100, v100
	v_fmac_f32_e32 v111, v102, v102
	v_add_f32_e32 v106, v106, v127
	v_mul_f32_e32 v119, v107, v107
	v_mul_f32_e32 v121, v117, v117
	v_fmac_f32_e32 v118, v104, v104
	v_fmac_f32_e32 v120, v114, v114
	v_add_f32_e32 v98, v98, v99
	v_add_f32_e32 v99, v109, v111
	v_fmac_f32_e32 v119, v106, v106
	v_fmac_f32_e32 v121, v116, v116
	v_add_f32_e32 v98, v118, v98
	v_add_f32_e32 v99, v120, v99
	v_add_f32_e32 v98, v119, v98
	v_add_f32_e32 v99, v121, v99
	v_add_f32_e32 v108, v98, v99
	ds_bpermute_b32 v109, v153, v108
	v_cvt_pk_bf16_f32 v98, v104, v105
	v_cvt_pk_bf16_f32 v99, v106, v107
	global_store_dwordx4 v[122:123], v[96:99], off
	s_waitcnt lgkmcnt(0)
	s_nop 0
	v_add_f32_e32 v96, v108, v109
	ds_bpermute_b32 v97, v152, v96
	v_cvt_pk_bf16_f32 v98, v100, v101
	v_cvt_pk_bf16_f32 v99, v102, v103
	v_cvt_pk_bf16_f32 v100, v114, v115
	v_cvt_pk_bf16_f32 v101, v116, v117
	global_store_dwordx4 v[122:123], v[98:101], off offset:256
	s_and_saveexec_b64 s[22:23], vcc
	s_cbranch_execz .LBB0_1368
	s_waitcnt lgkmcnt(0)
	v_add_f32_e32 v98, v96, v97
	v_lshlrev_b64 v[96:97], 7, v[112:113]
	v_lshl_add_u64 v[96:97], s[14:15], 0, v[96:97]
	v_lshl_add_u64 v[96:97], s[20:21], 2, v[96:97]
	s_lshl_b32 s10, s72, 2
	v_lshl_add_u64 v[96:97], v[96:97], 0, s[10:11]
	global_store_dword v[96:97], v98, off
.LBB0_1368:
	s_or_b64 exec, exec, s[22:23]
	v_or_b32_e32 v96, 32, v146
	s_waitcnt lgkmcnt(0)
	v_ashrrev_i32_e32 v97, 31, v96
	v_lshlrev_b64 v[98:99], 12, v[96:97]
	v_lshl_add_u64 v[98:99], s[12:13], 0, v[98:99]
	v_lshl_add_u64 v[106:107], v[144:145], 1, v[98:99]
	s_nop 1
	v_mov_b32_e32 v98, v184
	v_mov_b32_e32 v99, v185
	v_mov_b32_e32 v100, v186
	v_mov_b32_e32 v101, v187
	v_mov_b32_e32 v102, v188
	v_mov_b32_e32 v103, v189
	v_mov_b32_e32 v104, v190
	v_mov_b32_e32 v105, v191
	v_lshlrev_b32_e32 v108, 16, v98
	v_and_b32_e32 v98, 0xffff0000, v98
	v_lshlrev_b32_e32 v109, 16, v99
	v_and_b32_e32 v99, 0xffff0000, v99
	v_lshlrev_b32_e32 v112, 16, v102
	v_and_b32_e32 v102, 0xffff0000, v102
	v_lshlrev_b32_e32 v113, 16, v103
	v_and_b32_e32 v103, 0xffff0000, v103
	v_lshlrev_b32_e32 v110, 16, v100
	v_and_b32_e32 v100, 0xffff0000, v100
	v_lshlrev_b32_e32 v111, 16, v101
	v_and_b32_e32 v101, 0xffff0000, v101
	v_lshlrev_b32_e32 v114, 16, v104
	v_and_b32_e32 v104, 0xffff0000, v104
	v_lshlrev_b32_e32 v115, 16, v105
	v_and_b32_e32 v105, 0xffff0000, v105
	v_add_f32_e32 v93, v93, v98
	v_add_f32_e32 v95, v95, v99
	v_add_f32_e32 v85, v85, v102
	v_add_f32_e32 v87, v87, v103
	v_add_f32_e32 v92, v92, v108
	v_add_f32_e32 v94, v94, v109
	v_add_f32_e32 v89, v89, v100
	v_add_f32_e32 v91, v91, v101
	v_add_f32_e32 v84, v84, v112
	v_add_f32_e32 v86, v86, v113
	v_add_f32_e32 v98, v80, v114
	v_add_f32_e32 v99, v81, v104
	v_add_f32_e32 v100, v82, v115
	v_add_f32_e32 v101, v83, v105
	v_mul_f32_e32 v82, v93, v93
	v_mul_f32_e32 v83, v95, v95
	v_cvt_pk_bf16_f32 v80, v92, v93
	v_cvt_pk_bf16_f32 v81, v94, v95
	v_mul_f32_e32 v93, v85, v85
	v_mul_f32_e32 v95, v87, v87
	v_add_f32_e32 v88, v88, v110
	v_mul_f32_e32 v102, v89, v89
	v_mul_f32_e32 v104, v99, v99
	v_fmac_f32_e32 v82, v92, v92
	v_fmac_f32_e32 v83, v94, v94
	v_fmac_f32_e32 v93, v84, v84
	v_fmac_f32_e32 v95, v86, v86
	v_add_f32_e32 v90, v90, v111
	v_mul_f32_e32 v103, v91, v91
	v_mul_f32_e32 v105, v101, v101
	v_fmac_f32_e32 v102, v88, v88
	v_fmac_f32_e32 v104, v98, v98
	v_add_f32_e32 v82, v82, v83
	v_add_f32_e32 v83, v93, v95
	v_fmac_f32_e32 v103, v90, v90
	v_fmac_f32_e32 v105, v100, v100
	v_add_f32_e32 v82, v102, v82
	v_add_f32_e32 v83, v104, v83
	v_add_f32_e32 v82, v103, v82
	v_add_f32_e32 v83, v105, v83
	v_add_f32_e32 v92, v82, v83
	ds_bpermute_b32 v93, v153, v92
	v_cvt_pk_bf16_f32 v82, v88, v89
	v_cvt_pk_bf16_f32 v83, v90, v91
	global_store_dwordx4 v[106:107], v[80:83], off
	s_waitcnt lgkmcnt(0)
	s_nop 0
	v_add_f32_e32 v80, v92, v93
	ds_bpermute_b32 v81, v152, v80
	v_cvt_pk_bf16_f32 v82, v84, v85
	v_cvt_pk_bf16_f32 v83, v86, v87
	v_cvt_pk_bf16_f32 v84, v98, v99
	v_cvt_pk_bf16_f32 v85, v100, v101
	global_store_dwordx4 v[106:107], v[82:85], off offset:256
	s_and_saveexec_b64 s[22:23], vcc
	s_cbranch_execz .LBB0_1370
	s_waitcnt lgkmcnt(0)
	v_add_f32_e32 v82, v80, v81
	v_lshlrev_b64 v[80:81], 7, v[96:97]
	v_lshl_add_u64 v[80:81], s[14:15], 0, v[80:81]
	v_lshl_add_u64 v[80:81], s[20:21], 2, v[80:81]
	s_lshl_b32 s10, s72, 2
	v_lshl_add_u64 v[80:81], v[80:81], 0, s[10:11]
	global_store_dword v[80:81], v82, off
; __device__ __forceinline__ unsigned cvt_pk_bf16(float lo, float hi) { unsigned r; asm volatile("v_cvt_pk_bf16_f32 %0, %1, %2" : "=v"(r) : "v"(lo), "v"(hi)); return r; }
; __device__ __forceinline__ float shx(float v, int mask, int lane) { return __int_as_float(__builtin_amdgcn_ds_bpermute((lane ^ mask) << 2, __float_as_int(v))); }
; __device__ __forceinline__ float bf_lo(unsigned w) { return __uint_as_float(w << 16); }
; __device__ __forceinline__ float bf_hi(unsigned w) { return __uint_as_float(w & 0xffff0000u); }
;     __device__ __forceinline__ void operator()(const f32x4 (&acc)[2][2][4][2], const Unit& u, int wr, int wc, int fr, int fq) const {
;     ...
;             for (int m = 0; m < 4; ++m) { const int row = row0 + ai * HALF + m * 16; bf16_t* bp = HB + (size_t)row * 2048 + col0; float s = 0.f;
;                 u32x4 hv[2];
; #pragma unroll
;                 for (int bj = 0; bj < 2; ++bj) hv[bj] = *(const u32x4*)(bp + bj * HALF);
; #pragma unroll
;                 for (int bj = 0; bj < 2; ++bj) { const f32x4 a0 = acc[ai][bj][m][0], a1 = acc[ai][bj][m][1]; const u32x4 x = hv[bj];
;                     const float h0 = bf_lo(x.x) + a0[0], h1 = bf_hi(x.x) + a0[1], h2 = bf_lo(x.y) + a0[2], h3 = bf_hi(x.y) + a0[3], h4 = bf_lo(x.z) + a1[0], h5 = bf_hi(x.z) + a1[1], h6 = bf_lo(x.w) + a1[2], h7 = bf_hi(x.w) + a1[3];
;                     s += (h0 * h0 + h1 * h1) + (h2 * h2 + h3 * h3) + (h4 * h4 + h5 * h5) + (h6 * h6 + h7 * h7);
;                     u32x4 w; w.x = cvt_pk_bf16(h0, h1); w.y = cvt_pk_bf16(h2, h3); w.z = cvt_pk_bf16(h4, h5); w.w = cvt_pk_bf16(h6, h7); *(u32x4*)(bp + bj * HALF) = w; }
;                 { const int ln = fr + 16 * fq; s += shx(s, 16, ln); s += shx(s, 32, ln); }
;                 if (fq == 0) ssq_out[(size_t)row * 32 + u.pn * 4 + wc] = s;
;                 asm volatile("" ::: "memory"); }
.LBB0_1370:
	s_or_b64 exec, exec, s[22:23]
	v_or_b32_e32 v80, 48, v146
	s_waitcnt lgkmcnt(0)
	v_ashrrev_i32_e32 v81, 31, v80
	v_lshlrev_b64 v[82:83], 12, v[80:81]
	v_lshl_add_u64 v[82:83], s[12:13], 0, v[82:83]
	v_lshl_add_u64 v[90:91], v[144:145], 1, v[82:83]
	s_nop 1
	v_mov_b32_e32 v82, v192
	v_mov_b32_e32 v83, v193
	v_mov_b32_e32 v84, v194
	v_mov_b32_e32 v85, v195
	v_mov_b32_e32 v86, v196
	v_mov_b32_e32 v87, v197
	v_mov_b32_e32 v88, v198
	v_mov_b32_e32 v89, v199
	v_lshlrev_b32_e32 v92, 16, v82
	v_and_b32_e32 v82, 0xffff0000, v82
	v_lshlrev_b32_e32 v93, 16, v83
	v_and_b32_e32 v83, 0xffff0000, v83
	v_lshlrev_b32_e32 v96, 16, v86
	v_and_b32_e32 v86, 0xffff0000, v86
	v_lshlrev_b32_e32 v97, 16, v87
	v_and_b32_e32 v87, 0xffff0000, v87
	v_lshlrev_b32_e32 v94, 16, v84
	v_and_b32_e32 v84, 0xffff0000, v84
	v_lshlrev_b32_e32 v95, 16, v85
	v_and_b32_e32 v85, 0xffff0000, v85
	v_lshlrev_b32_e32 v98, 16, v88
	v_and_b32_e32 v88, 0xffff0000, v88
	v_lshlrev_b32_e32 v99, 16, v89
	v_and_b32_e32 v89, 0xffff0000, v89
	v_add_f32_e32 v77, v77, v82
	v_add_f32_e32 v79, v79, v83
	v_add_f32_e32 v69, v69, v86
	v_add_f32_e32 v71, v71, v87
	v_add_f32_e32 v76, v76, v92
	v_add_f32_e32 v78, v78, v93
	v_add_f32_e32 v73, v73, v84
	v_add_f32_e32 v75, v75, v85
	v_add_f32_e32 v68, v68, v96
	v_add_f32_e32 v70, v70, v97
	v_add_f32_e32 v82, v64, v98
	v_add_f32_e32 v83, v65, v88
	v_add_f32_e32 v84, v66, v99
	v_add_f32_e32 v85, v67, v89
	v_mul_f32_e32 v66, v77, v77
	v_mul_f32_e32 v67, v79, v79
	v_cvt_pk_bf16_f32 v64, v76, v77
	v_cvt_pk_bf16_f32 v65, v78, v79
	v_mul_f32_e32 v77, v69, v69
	v_mul_f32_e32 v79, v71, v71
	v_add_f32_e32 v72, v72, v94
	v_mul_f32_e32 v86, v73, v73
	v_mul_f32_e32 v88, v83, v83
	v_fmac_f32_e32 v66, v76, v76
	v_fmac_f32_e32 v67, v78, v78
	v_fmac_f32_e32 v77, v68, v68
	v_fmac_f32_e32 v79, v70, v70
	v_add_f32_e32 v74, v74, v95
	v_mul_f32_e32 v87, v75, v75
	v_mul_f32_e32 v89, v85, v85
	v_fmac_f32_e32 v86, v72, v72
	v_fmac_f32_e32 v88, v82, v82
	v_add_f32_e32 v66, v66, v67
	v_add_f32_e32 v67, v77, v79
	v_fmac_f32_e32 v87, v74, v74
	v_fmac_f32_e32 v89, v84, v84
	v_add_f32_e32 v66, v86, v66
	v_add_f32_e32 v67, v88, v67
	v_add_f32_e32 v66, v87, v66
	v_add_f32_e32 v67, v89, v67
	v_add_f32_e32 v76, v66, v67
	ds_bpermute_b32 v77, v153, v76
	v_cvt_pk_bf16_f32 v66, v72, v73
	v_cvt_pk_bf16_f32 v67, v74, v75
	global_store_dwordx4 v[90:91], v[64:67], off
	s_waitcnt lgkmcnt(0)
	s_nop 0
	v_add_f32_e32 v64, v76, v77
	ds_bpermute_b32 v65, v152, v64
	v_cvt_pk_bf16_f32 v66, v68, v69
	v_cvt_pk_bf16_f32 v67, v70, v71
	v_cvt_pk_bf16_f32 v68, v82, v83
	v_cvt_pk_bf16_f32 v69, v84, v85
	global_store_dwordx4 v[90:91], v[66:69], off offset:256
	s_and_saveexec_b64 s[22:23], vcc
	s_cbranch_execz .LBB0_1372
	s_waitcnt lgkmcnt(0)
	v_add_f32_e32 v66, v64, v65
	v_lshlrev_b64 v[64:65], 7, v[80:81]
	v_lshl_add_u64 v[64:65], s[14:15], 0, v[64:65]
	v_lshl_add_u64 v[64:65], s[20:21], 2, v[64:65]
	s_lshl_b32 s10, s72, 2
	v_lshl_add_u64 v[64:65], v[64:65], 0, s[10:11]
	global_store_dword v[64:65], v66, off
.LBB0_1372:
	s_or_b64 exec, exec, s[22:23]
	v_add_u32_e32 v64, 0x80, v146
	s_waitcnt lgkmcnt(0)
	v_ashrrev_i32_e32 v65, 31, v64
	v_lshlrev_b64 v[66:67], 12, v[64:65]
	v_lshl_add_u64 v[66:67], s[12:13], 0, v[66:67]
	v_lshl_add_u64 v[74:75], v[144:145], 1, v[66:67]
	s_nop 1
	v_mov_b32_e32 v66, v200
	v_mov_b32_e32 v67, v201
	v_mov_b32_e32 v68, v202
	v_mov_b32_e32 v69, v203
	v_mov_b32_e32 v70, v204
	v_mov_b32_e32 v71, v205
	v_mov_b32_e32 v72, v206
	v_mov_b32_e32 v73, v207
	v_lshlrev_b32_e32 v76, 16, v66
	v_and_b32_e32 v66, 0xffff0000, v66
	v_lshlrev_b32_e32 v77, 16, v67
	v_and_b32_e32 v67, 0xffff0000, v67
	v_lshlrev_b32_e32 v80, 16, v70
	v_and_b32_e32 v70, 0xffff0000, v70
	v_lshlrev_b32_e32 v81, 16, v71
	v_and_b32_e32 v71, 0xffff0000, v71
	v_lshlrev_b32_e32 v78, 16, v68
	v_and_b32_e32 v68, 0xffff0000, v68
	v_lshlrev_b32_e32 v79, 16, v69
	v_and_b32_e32 v69, 0xffff0000, v69
	v_lshlrev_b32_e32 v82, 16, v72
	v_and_b32_e32 v72, 0xffff0000, v72
	v_lshlrev_b32_e32 v83, 16, v73
	v_and_b32_e32 v73, 0xffff0000, v73
	v_add_f32_e32 v61, v61, v66
	v_add_f32_e32 v63, v63, v67
	v_add_f32_e32 v53, v53, v70
	v_add_f32_e32 v55, v55, v71
	v_add_f32_e32 v60, v60, v76
	v_add_f32_e32 v62, v62, v77
	v_add_f32_e32 v57, v57, v68
	v_add_f32_e32 v59, v59, v69
	v_add_f32_e32 v52, v52, v80
	v_add_f32_e32 v54, v54, v81
	v_add_f32_e32 v66, v48, v82
	v_add_f32_e32 v67, v49, v72
	v_add_f32_e32 v68, v50, v83
	v_add_f32_e32 v69, v51, v73
	v_mul_f32_e32 v50, v61, v61
	v_mul_f32_e32 v51, v63, v63
	v_cvt_pk_bf16_f32 v48, v60, v61
	v_cvt_pk_bf16_f32 v49, v62, v63
	v_mul_f32_e32 v61, v53, v53
	v_mul_f32_e32 v63, v55, v55
	v_add_f32_e32 v56, v56, v78
	v_mul_f32_e32 v70, v57, v57
	v_mul_f32_e32 v72, v67, v67
	v_fmac_f32_e32 v50, v60, v60
	v_fmac_f32_e32 v51, v62, v62
	v_fmac_f32_e32 v61, v52, v52
	v_fmac_f32_e32 v63, v54, v54
	v_add_f32_e32 v58, v58, v79
	v_mul_f32_e32 v71, v59, v59
	v_mul_f32_e32 v73, v69, v69
	v_fmac_f32_e32 v70, v56, v56
	v_fmac_f32_e32 v72, v66, v66
	v_add_f32_e32 v50, v50, v51
	v_add_f32_e32 v51, v61, v63
	v_fmac_f32_e32 v71, v58, v58
	v_fmac_f32_e32 v73, v68, v68
	v_add_f32_e32 v50, v70, v50
	v_add_f32_e32 v51, v72, v51
	v_add_f32_e32 v50, v71, v50
	v_add_f32_e32 v51, v73, v51
	v_add_f32_e32 v60, v50, v51
	ds_bpermute_b32 v61, v153, v60
	v_cvt_pk_bf16_f32 v50, v56, v57
	v_cvt_pk_bf16_f32 v51, v58, v59
	global_store_dwordx4 v[74:75], v[48:51], off
	s_waitcnt lgkmcnt(0)
	s_nop 0
	v_add_f32_e32 v48, v60, v61
	ds_bpermute_b32 v49, v152, v48
	v_cvt_pk_bf16_f32 v50, v52, v53
	v_cvt_pk_bf16_f32 v51, v54, v55
	v_cvt_pk_bf16_f32 v52, v66, v67
	v_cvt_pk_bf16_f32 v53, v68, v69
	global_store_dwordx4 v[74:75], v[50:53], off offset:256
	s_and_saveexec_b64 s[22:23], vcc
	s_cbranch_execz .LBB0_1374
	s_waitcnt lgkmcnt(0)
	v_add_f32_e32 v50, v48, v49
	v_lshlrev_b64 v[48:49], 7, v[64:65]
	v_lshl_add_u64 v[48:49], s[14:15], 0, v[48:49]
	v_lshl_add_u64 v[48:49], s[20:21], 2, v[48:49]
	s_lshl_b32 s10, s72, 2
	v_lshl_add_u64 v[48:49], v[48:49], 0, s[10:11]
	global_store_dword v[48:49], v50, off
; __device__ __forceinline__ unsigned cvt_pk_bf16(float lo, float hi) { unsigned r; asm volatile("v_cvt_pk_bf16_f32 %0, %1, %2" : "=v"(r) : "v"(lo), "v"(hi)); return r; }
; __device__ __forceinline__ float shx(float v, int mask, int lane) { return __int_as_float(__builtin_amdgcn_ds_bpermute((lane ^ mask) << 2, __float_as_int(v))); }
; __device__ __forceinline__ float bf_lo(unsigned w) { return __uint_as_float(w << 16); }
; __device__ __forceinline__ float bf_hi(unsigned w) { return __uint_as_float(w & 0xffff0000u); }
;     __device__ __forceinline__ void operator()(const f32x4 (&acc)[2][2][4][2], const Unit& u, int wr, int wc, int fr, int fq) const {
;     ...
;             for (int m = 0; m < 4; ++m) { const int row = row0 + ai * HALF + m * 16; bf16_t* bp = HB + (size_t)row * 2048 + col0; float s = 0.f;
;                 u32x4 hv[2];
; #pragma unroll
;                 for (int bj = 0; bj < 2; ++bj) hv[bj] = *(const u32x4*)(bp + bj * HALF);
; #pragma unroll
;                 for (int bj = 0; bj < 2; ++bj) { const f32x4 a0 = acc[ai][bj][m][0], a1 = acc[ai][bj][m][1]; const u32x4 x = hv[bj];
;                     const float h0 = bf_lo(x.x) + a0[0], h1 = bf_hi(x.x) + a0[1], h2 = bf_lo(x.y) + a0[2], h3 = bf_hi(x.y) + a0[3], h4 = bf_lo(x.z) + a1[0], h5 = bf_hi(x.z) + a1[1], h6 = bf_lo(x.w) + a1[2], h7 = bf_hi(x.w) + a1[3];
;                     s += (h0 * h0 + h1 * h1) + (h2 * h2 + h3 * h3) + (h4 * h4 + h5 * h5) + (h6 * h6 + h7 * h7);
;                     u32x4 w; w.x = cvt_pk_bf16(h0, h1); w.y = cvt_pk_bf16(h2, h3); w.z = cvt_pk_bf16(h4, h5); w.w = cvt_pk_bf16(h6, h7); *(u32x4*)(bp + bj * HALF) = w; }
;                 { const int ln = fr + 16 * fq; s += shx(s, 16, ln); s += shx(s, 32, ln); }
;                 if (fq == 0) ssq_out[(size_t)row * 32 + u.pn * 4 + wc] = s;
;                 asm volatile("" ::: "memory"); }
.LBB0_1374:
	s_or_b64 exec, exec, s[22:23]
	v_add_u32_e32 v48, 0x90, v146
	s_waitcnt lgkmcnt(0)
	v_ashrrev_i32_e32 v49, 31, v48
	v_lshlrev_b64 v[50:51], 12, v[48:49]
	v_lshl_add_u64 v[50:51], s[12:13], 0, v[50:51]
	v_lshl_add_u64 v[58:59], v[144:145], 1, v[50:51]
	s_nop 1
	v_mov_b32_e32 v50, v208
	v_mov_b32_e32 v51, v209
	v_mov_b32_e32 v52, v210
	v_mov_b32_e32 v53, v211
	v_mov_b32_e32 v54, v212
	v_mov_b32_e32 v55, v213
	v_mov_b32_e32 v56, v214
	v_mov_b32_e32 v57, v215
	v_lshlrev_b32_e32 v60, 16, v50
	v_and_b32_e32 v50, 0xffff0000, v50
	v_lshlrev_b32_e32 v61, 16, v51
	v_and_b32_e32 v51, 0xffff0000, v51
	v_lshlrev_b32_e32 v64, 16, v54
	v_and_b32_e32 v54, 0xffff0000, v54
	v_lshlrev_b32_e32 v65, 16, v55
	v_and_b32_e32 v55, 0xffff0000, v55
	v_lshlrev_b32_e32 v62, 16, v52
	v_and_b32_e32 v52, 0xffff0000, v52
	v_lshlrev_b32_e32 v63, 16, v53
	v_and_b32_e32 v53, 0xffff0000, v53
	v_lshlrev_b32_e32 v66, 16, v56
	v_and_b32_e32 v56, 0xffff0000, v56
	v_lshlrev_b32_e32 v67, 16, v57
	v_and_b32_e32 v57, 0xffff0000, v57
	v_add_f32_e32 v45, v45, v50
	v_add_f32_e32 v47, v47, v51
	v_add_f32_e32 v37, v37, v54
	v_add_f32_e32 v39, v39, v55
	v_add_f32_e32 v44, v44, v60
	v_add_f32_e32 v46, v46, v61
	v_add_f32_e32 v41, v41, v52
	v_add_f32_e32 v43, v43, v53
	v_add_f32_e32 v36, v36, v64
	v_add_f32_e32 v38, v38, v65
	v_add_f32_e32 v50, v32, v66
	v_add_f32_e32 v51, v33, v56
	v_add_f32_e32 v52, v34, v67
	v_add_f32_e32 v53, v35, v57
	v_mul_f32_e32 v34, v45, v45
	v_mul_f32_e32 v35, v47, v47
	v_cvt_pk_bf16_f32 v32, v44, v45
	v_cvt_pk_bf16_f32 v33, v46, v47
	v_mul_f32_e32 v45, v37, v37
	v_mul_f32_e32 v47, v39, v39
	v_add_f32_e32 v40, v40, v62
	v_mul_f32_e32 v54, v41, v41
	v_mul_f32_e32 v56, v51, v51
	v_fmac_f32_e32 v34, v44, v44
	v_fmac_f32_e32 v35, v46, v46
	v_fmac_f32_e32 v45, v36, v36
	v_fmac_f32_e32 v47, v38, v38
	v_add_f32_e32 v42, v42, v63
	v_mul_f32_e32 v55, v43, v43
	v_mul_f32_e32 v57, v53, v53
	v_fmac_f32_e32 v54, v40, v40
	v_fmac_f32_e32 v56, v50, v50
	v_add_f32_e32 v34, v34, v35
	v_add_f32_e32 v35, v45, v47
	v_fmac_f32_e32 v55, v42, v42
	v_fmac_f32_e32 v57, v52, v52
	v_add_f32_e32 v34, v54, v34
	v_add_f32_e32 v35, v56, v35
	v_add_f32_e32 v34, v55, v34
	v_add_f32_e32 v35, v57, v35
	v_add_f32_e32 v44, v34, v35
	ds_bpermute_b32 v45, v153, v44
	v_cvt_pk_bf16_f32 v34, v40, v41
	v_cvt_pk_bf16_f32 v35, v42, v43
	global_store_dwordx4 v[58:59], v[32:35], off
	s_waitcnt lgkmcnt(0)
	s_nop 0
	v_add_f32_e32 v32, v44, v45
	ds_bpermute_b32 v33, v152, v32
	v_cvt_pk_bf16_f32 v34, v36, v37
	v_cvt_pk_bf16_f32 v35, v38, v39
	v_cvt_pk_bf16_f32 v36, v50, v51
	v_cvt_pk_bf16_f32 v37, v52, v53
	global_store_dwordx4 v[58:59], v[34:37], off offset:256
	s_and_saveexec_b64 s[22:23], vcc
	s_cbranch_execz .LBB0_1376
	s_waitcnt lgkmcnt(0)
	v_add_f32_e32 v34, v32, v33
	v_lshlrev_b64 v[32:33], 7, v[48:49]
	v_lshl_add_u64 v[32:33], s[14:15], 0, v[32:33]
	v_lshl_add_u64 v[32:33], s[20:21], 2, v[32:33]
	s_lshl_b32 s10, s72, 2
	v_lshl_add_u64 v[32:33], v[32:33], 0, s[10:11]
	global_store_dword v[32:33], v34, off
; __device__ __forceinline__ unsigned cvt_pk_bf16(float lo, float hi) { unsigned r; asm volatile("v_cvt_pk_bf16_f32 %0, %1, %2" : "=v"(r) : "v"(lo), "v"(hi)); return r; }
; __device__ __forceinline__ float shx(float v, int mask, int lane) { return __int_as_float(__builtin_amdgcn_ds_bpermute((lane ^ mask) << 2, __float_as_int(v))); }
; __device__ __forceinline__ float bf_lo(unsigned w) { return __uint_as_float(w << 16); }
; __device__ __forceinline__ float bf_hi(unsigned w) { return __uint_as_float(w & 0xffff0000u); }
;     __device__ __forceinline__ void operator()(const f32x4 (&acc)[2][2][4][2], const Unit& u, int wr, int wc, int fr, int fq) const {
;     ...
;             for (int m = 0; m < 4; ++m) { const int row = row0 + ai * HALF + m * 16; bf16_t* bp = HB + (size_t)row * 2048 + col0; float s = 0.f;
;                 u32x4 hv[2];
; #pragma unroll
;                 for (int bj = 0; bj < 2; ++bj) hv[bj] = *(const u32x4*)(bp + bj * HALF);
; #pragma unroll
;                 for (int bj = 0; bj < 2; ++bj) { const f32x4 a0 = acc[ai][bj][m][0], a1 = acc[ai][bj][m][1]; const u32x4 x = hv[bj];
;                     const float h0 = bf_lo(x.x) + a0[0], h1 = bf_hi(x.x) + a0[1], h2 = bf_lo(x.y) + a0[2], h3 = bf_hi(x.y) + a0[3], h4 = bf_lo(x.z) + a1[0], h5 = bf_hi(x.z) + a1[1], h6 = bf_lo(x.w) + a1[2], h7 = bf_hi(x.w) + a1[3];
;                     s += (h0 * h0 + h1 * h1) + (h2 * h2 + h3 * h3) + (h4 * h4 + h5 * h5) + (h6 * h6 + h7 * h7);
;                     u32x4 w; w.x = cvt_pk_bf16(h0, h1); w.y = cvt_pk_bf16(h2, h3); w.z = cvt_pk_bf16(h4, h5); w.w = cvt_pk_bf16(h6, h7); *(u32x4*)(bp + bj * HALF) = w; }
;                 { const int ln = fr + 16 * fq; s += shx(s, 16, ln); s += shx(s, 32, ln); }
;                 if (fq == 0) ssq_out[(size_t)row * 32 + u.pn * 4 + wc] = s;
;                 asm volatile("" ::: "memory"); }
.LBB0_1376:
	s_or_b64 exec, exec, s[22:23]
	v_add_u32_e32 v32, 0xa0, v146
	s_waitcnt lgkmcnt(0)
	v_ashrrev_i32_e32 v33, 31, v32
	v_lshlrev_b64 v[34:35], 12, v[32:33]
	v_lshl_add_u64 v[34:35], s[12:13], 0, v[34:35]
	v_lshl_add_u64 v[42:43], v[144:145], 1, v[34:35]
	s_nop 1
	v_mov_b32_e32 v34, v216
	v_mov_b32_e32 v35, v217
	v_mov_b32_e32 v36, v218
	v_mov_b32_e32 v37, v219
	v_mov_b32_e32 v38, v220
	v_mov_b32_e32 v39, v221
	v_mov_b32_e32 v40, v222
	v_mov_b32_e32 v41, v223
	v_lshlrev_b32_e32 v44, 16, v34
	v_and_b32_e32 v34, 0xffff0000, v34
	v_lshlrev_b32_e32 v45, 16, v35
	v_and_b32_e32 v35, 0xffff0000, v35
	v_lshlrev_b32_e32 v48, 16, v38
	v_and_b32_e32 v38, 0xffff0000, v38
	v_lshlrev_b32_e32 v49, 16, v39
	v_and_b32_e32 v39, 0xffff0000, v39
	v_lshlrev_b32_e32 v46, 16, v36
	v_and_b32_e32 v36, 0xffff0000, v36
	v_lshlrev_b32_e32 v47, 16, v37
	v_and_b32_e32 v37, 0xffff0000, v37
	v_lshlrev_b32_e32 v50, 16, v40
	v_and_b32_e32 v40, 0xffff0000, v40
	v_lshlrev_b32_e32 v51, 16, v41
	v_and_b32_e32 v41, 0xffff0000, v41
	v_add_f32_e32 v29, v29, v34
	v_add_f32_e32 v31, v31, v35
	v_add_f32_e32 v21, v21, v38
	v_add_f32_e32 v23, v23, v39
	v_add_f32_e32 v28, v28, v44
	v_add_f32_e32 v30, v30, v45
	v_add_f32_e32 v25, v25, v36
	v_add_f32_e32 v27, v27, v37
	v_add_f32_e32 v20, v20, v48
	v_add_f32_e32 v22, v22, v49
	v_add_f32_e32 v34, v16, v50
	v_add_f32_e32 v35, v17, v40
	v_add_f32_e32 v36, v18, v51
	v_add_f32_e32 v37, v19, v41
	v_mul_f32_e32 v18, v29, v29
	v_mul_f32_e32 v19, v31, v31
	v_cvt_pk_bf16_f32 v16, v28, v29
	v_cvt_pk_bf16_f32 v17, v30, v31
	v_mul_f32_e32 v29, v21, v21
	v_mul_f32_e32 v31, v23, v23
	v_add_f32_e32 v24, v24, v46
	v_mul_f32_e32 v38, v25, v25
	v_mul_f32_e32 v40, v35, v35
	v_fmac_f32_e32 v18, v28, v28
	v_fmac_f32_e32 v19, v30, v30
	v_fmac_f32_e32 v29, v20, v20
	v_fmac_f32_e32 v31, v22, v22
	v_add_f32_e32 v26, v26, v47
	v_mul_f32_e32 v39, v27, v27
	v_mul_f32_e32 v41, v37, v37
	v_fmac_f32_e32 v38, v24, v24
	v_fmac_f32_e32 v40, v34, v34
	v_add_f32_e32 v18, v18, v19
	v_add_f32_e32 v19, v29, v31
	v_fmac_f32_e32 v39, v26, v26
	v_fmac_f32_e32 v41, v36, v36
	v_add_f32_e32 v18, v38, v18
	v_add_f32_e32 v19, v40, v19
	v_add_f32_e32 v18, v39, v18
	v_add_f32_e32 v19, v41, v19
	v_add_f32_e32 v28, v18, v19
	ds_bpermute_b32 v29, v153, v28
	v_cvt_pk_bf16_f32 v18, v24, v25
	v_cvt_pk_bf16_f32 v19, v26, v27
	global_store_dwordx4 v[42:43], v[16:19], off
	s_waitcnt lgkmcnt(0)
	s_nop 0
	v_add_f32_e32 v16, v28, v29
	ds_bpermute_b32 v17, v152, v16
	v_cvt_pk_bf16_f32 v18, v20, v21
	v_cvt_pk_bf16_f32 v19, v22, v23
	v_cvt_pk_bf16_f32 v20, v34, v35
	v_cvt_pk_bf16_f32 v21, v36, v37
	global_store_dwordx4 v[42:43], v[18:21], off offset:256
	s_and_saveexec_b64 s[22:23], vcc
	s_cbranch_execz .LBB0_1378
	s_waitcnt lgkmcnt(0)
	v_add_f32_e32 v18, v16, v17
	v_lshlrev_b64 v[16:17], 7, v[32:33]
	v_lshl_add_u64 v[16:17], s[14:15], 0, v[16:17]
	v_lshl_add_u64 v[16:17], s[20:21], 2, v[16:17]
	s_lshl_b32 s10, s72, 2
	v_lshl_add_u64 v[16:17], v[16:17], 0, s[10:11]
	global_store_dword v[16:17], v18, off
.LBB0_1378:
	s_or_b64 exec, exec, s[22:23]
	v_add_u32_e32 v16, 0xb0, v146
	s_waitcnt lgkmcnt(0)
	v_ashrrev_i32_e32 v17, 31, v16
	v_lshlrev_b64 v[18:19], 12, v[16:17]
	v_lshl_add_u64 v[18:19], s[12:13], 0, v[18:19]
	v_lshl_add_u64 v[26:27], v[144:145], 1, v[18:19]
	s_nop 1
	v_mov_b32_e32 v18, v224
	v_mov_b32_e32 v19, v225
	v_mov_b32_e32 v20, v226
	v_mov_b32_e32 v21, v227
	v_mov_b32_e32 v22, v228
	v_mov_b32_e32 v23, v229
	v_mov_b32_e32 v24, v230
	v_mov_b32_e32 v25, v231
	v_lshlrev_b32_e32 v28, 16, v18
	v_and_b32_e32 v18, 0xffff0000, v18
	v_lshlrev_b32_e32 v29, 16, v19
	v_and_b32_e32 v19, 0xffff0000, v19
	v_lshlrev_b32_e32 v32, 16, v22
	v_and_b32_e32 v22, 0xffff0000, v22
	v_lshlrev_b32_e32 v33, 16, v23
	v_and_b32_e32 v23, 0xffff0000, v23
	v_lshlrev_b32_e32 v30, 16, v20
	v_and_b32_e32 v20, 0xffff0000, v20
	v_lshlrev_b32_e32 v31, 16, v21
	v_and_b32_e32 v21, 0xffff0000, v21
	v_lshlrev_b32_e32 v34, 16, v24
	v_and_b32_e32 v24, 0xffff0000, v24
	v_lshlrev_b32_e32 v35, 16, v25
	v_and_b32_e32 v25, 0xffff0000, v25
	v_add_f32_e32 v13, v13, v18
	v_add_f32_e32 v15, v15, v19
	v_add_f32_e32 v5, v5, v22
	v_add_f32_e32 v7, v7, v23
	v_add_f32_e32 v12, v12, v28
	v_add_f32_e32 v14, v14, v29
	v_add_f32_e32 v9, v9, v20
	v_add_f32_e32 v11, v11, v21
	v_add_f32_e32 v4, v4, v32
	v_add_f32_e32 v6, v6, v33
	v_add_f32_e32 v18, v0, v34
	v_add_f32_e32 v19, v1, v24
	v_add_f32_e32 v20, v2, v35
	v_add_f32_e32 v21, v3, v25
	v_mul_f32_e32 v2, v13, v13
	v_mul_f32_e32 v3, v15, v15
	v_cvt_pk_bf16_f32 v0, v12, v13
	v_cvt_pk_bf16_f32 v1, v14, v15
	v_mul_f32_e32 v13, v5, v5
	v_mul_f32_e32 v15, v7, v7
	v_add_f32_e32 v8, v8, v30
	v_mul_f32_e32 v22, v9, v9
	v_mul_f32_e32 v24, v19, v19
	v_fmac_f32_e32 v2, v12, v12
	v_fmac_f32_e32 v3, v14, v14
	v_fmac_f32_e32 v13, v4, v4
	v_fmac_f32_e32 v15, v6, v6
	v_add_f32_e32 v10, v10, v31
	v_mul_f32_e32 v23, v11, v11
	v_mul_f32_e32 v25, v21, v21
	v_fmac_f32_e32 v22, v8, v8
	v_fmac_f32_e32 v24, v18, v18
	v_add_f32_e32 v2, v2, v3
	v_add_f32_e32 v3, v13, v15
	v_fmac_f32_e32 v23, v10, v10
	v_fmac_f32_e32 v25, v20, v20
	v_add_f32_e32 v2, v22, v2
	v_add_f32_e32 v3, v24, v3
	v_add_f32_e32 v2, v23, v2
	v_add_f32_e32 v3, v25, v3
	v_add_f32_e32 v12, v2, v3
	ds_bpermute_b32 v13, v153, v12
	v_cvt_pk_bf16_f32 v2, v8, v9
	v_cvt_pk_bf16_f32 v3, v10, v11
	global_store_dwordx4 v[26:27], v[0:3], off
	s_waitcnt lgkmcnt(0)
	s_nop 0
	v_add_f32_e32 v0, v12, v13
	ds_bpermute_b32 v1, v152, v0
	v_cvt_pk_bf16_f32 v2, v4, v5
	v_cvt_pk_bf16_f32 v3, v6, v7
	v_cvt_pk_bf16_f32 v4, v18, v19
	v_cvt_pk_bf16_f32 v5, v20, v21
	global_store_dwordx4 v[26:27], v[2:5], off offset:256
	s_and_saveexec_b64 s[22:23], vcc
	s_cbranch_execz .LBB0_1380
	s_waitcnt lgkmcnt(0)
	v_add_f32_e32 v2, v0, v1
	v_lshlrev_b64 v[0:1], 7, v[16:17]
	v_lshl_add_u64 v[0:1], s[14:15], 0, v[0:1]
	v_lshl_add_u64 v[0:1], s[20:21], 2, v[0:1]
	s_lshl_b32 s10, s72, 2
	v_lshl_add_u64 v[0:1], v[0:1], 0, s[10:11]
	global_store_dword v[0:1], v2, off
